# lean P3/P10/P13: loads of batch b+2 issued before batch b's second norm and stores
# baseline (speedup 1.0000x reference)
;     __device__ __forceinline__ const float* in(int i) const { return karg_in(i); }
; __device__ __forceinline__ const float* xrow_ptr(const Ctx& C, int row) { return row < MPROMPT ? C.in(0) + (size_t)row * DM : C.in(1) + (size_t)(row - MPROMPT) * DM; }
; __device__ __forceinline__ v4f ld4_bf16(const bf16* p) { const v2u w = *(const v2u*)p; return (v4f){bf_lo(w.x), bf_hi(w.x), bf_lo(w.y), bf_hi(w.y)}; }
; __device__ __forceinline__ float ssq4(v4f v) { return (v.x * v.x + v.y * v.y) + (v.z * v.z + v.w * v.w); }
; #define FTID const int ftid_ = fresh_tid()
; template <int R, bool BASE_F32, bool OUT_F32>
; __device__ __forceinline__ void rows_res(const Ctx& C, int m0, int stride, int mx, const float* gpost, float scale, int lane) {
;     v4f d[R][4], b[R][4]; int mr[R]; bool ok[R]; float r1[R];
;     const bf16* D = C.D(); bf16* XN = C.XN();
; #pragma unroll
;     for (int r = 0; r < R; ++r) { mr[r] = (r == 4) ? mx : m0 + r * stride; ok[r] = (r == 4) ? (mx < M) : (mr[r] < MPROMPT); const int mm = ok[r] ? mr[r] : 0;
; #pragma unroll
;         for (int j = 0; j < 4; ++j) d[r][j] = ld4_bf16(D + (size_t)mm * DM + 4 * lane + 256 * j);
;         if (BASE_F32) { const float* x = xrow_ptr(C, mm);
; #pragma unroll
;             for (int j = 0; j < 4; ++j) b[r][j] = ld4_f32(x + 4 * lane + 256 * j);
;         } else { const float inv = C.RS()[mm];
; #pragma unroll
;             for (int j = 0; j < 4; ++j) b[r][j] = ld4_bf16(XN + (size_t)mm * DM + 4 * lane + 256 * j) * inv;
;         } }
; #pragma unroll
;     for (int r = 0; r < R; ++r) { float s = 0.f;
; #pragma unroll
;         for (int j = 0; j < 4; ++j) s += ssq4(d[r][j]);
; __global__ void __launch_bounds__(NTHREADS, 2) fwd_kernel(Args args) {
;     ...
;     { FTID; const float* gp = C.in(8); { const int gw_ = GWV, ngw_ = NGWV, nit = (MPROMPT + 4 * ngw_ - 1) / (4 * ngw_);
;       for (int it = 0; it < nit - 1; ++it) rows_res<4, false, false>(C, gw_ + 4 * it * ngw_, ngw_, M, gp, 0.5f, LANE);
.LBB0_366:
	s_or_b64 exec, exec, s[6:7]
	s_waitcnt lgkmcnt(0)
	v_mov_b32_e32 v0, v182
	s_mov_b64 s[0:1], s[80:81]
	s_barrier
	s_load_dwordx2 s[14:15], s[0:1], 0x40
	v_readfirstlane_b32 s0, v0
	s_ashr_i32 s47, s0, 6
	v_readlane_b32 s0, v232, 0
	s_add_i32 s42, s47, s0
	v_readlane_b32 s0, v232, 1
	v_and_b32_e32 v189, 63, v0
	v_readlane_b32 s1, v232, 2
	v_lshlrev_b32_e32 v0, 2, v189
	v_mov_b32_e32 v1, 0
	v_cndmask_b32_e64 v2, 0, 1, s[0:1]
	v_cmp_ne_u32_e64 s[6:7], 1, v2
	s_andn2_b64 vcc, exec, s[0:1]
	v_lshlrev_b32_e32 v2, 2, v0
	v_cmp_ne_u32_e64 s[8:9], 0, v189
	v_lshlrev_b32_e32 v0, 1, v0
	s_load_dwordx2 s[98:99], s[80:81], 0x110
	s_load_dwordx2 s[100:101], s[80:81], 0x40
	v_and_b32_e32 v176, 63, v182
	v_lshlrev_b32_e32 v170, 3, v176
	s_lshl_b32 vcc_lo, s42, 11
	v_add_u32_e32 v170, vcc_lo, v170
	v_add_u32_e32 v171, 0x3000000, v170
	v_add_u32_e32 v170, 0x7100000, v170
	v_mov_b32_e32 v173, v171
	s_lshl_b32 vcc_lo, s42, 2
	v_mov_b32_e32 v172, 0x2a80000
	v_add_u32_e32 v172, vcc_lo, v172
	v_mov_b32_e32 v174, v172
	v_lshlrev_b32_e32 v176, 4, v176
	v_mov_b32_e32 v138, 0x358637bd
	s_waitcnt lgkmcnt(0)
	global_load_dwordx4 v[192:195], v176, s[100:101]
	global_load_dwordx4 v[196:199], v176, s[100:101] offset:1024
	global_load_dwordx4 v[200:203], v176, s[100:101] offset:2048
	global_load_dwordx4 v[204:207], v176, s[100:101] offset:3072
	global_load_dword v52, v172, s[98:99]
	global_load_dwordx2 v[20:21], v170, s[98:99]
	global_load_dwordx2 v[22:23], v170, s[98:99] offset:512
	global_load_dwordx2 v[24:25], v170, s[98:99] offset:1024
	global_load_dwordx2 v[26:27], v170, s[98:99] offset:1536
	global_load_dwordx2 v[36:37], v171, s[98:99]
	global_load_dwordx2 v[38:39], v171, s[98:99] offset:512
	global_load_dwordx2 v[40:41], v171, s[98:99] offset:1024
	global_load_dwordx2 v[42:43], v171, s[98:99] offset:1536
	v_add_u32_e32 v170, 0x400000, v170
	v_add_u32_e32 v171, 0x400000, v171
	v_add_u32_e32 v172, 0x2000, v172
	global_load_dword v54, v172, s[98:99]
	global_load_dwordx2 v[28:29], v170, s[98:99]
	global_load_dwordx2 v[30:31], v170, s[98:99] offset:512
	global_load_dwordx2 v[32:33], v170, s[98:99] offset:1024
	global_load_dwordx2 v[34:35], v170, s[98:99] offset:1536
	global_load_dwordx2 v[44:45], v171, s[98:99]
	global_load_dwordx2 v[46:47], v171, s[98:99] offset:512
	global_load_dwordx2 v[48:49], v171, s[98:99] offset:1024
	global_load_dwordx2 v[50:51], v171, s[98:99] offset:1536
	v_add_u32_e32 v170, 0x400000, v170
	v_add_u32_e32 v171, 0x400000, v171
	v_add_u32_e32 v172, 0x2000, v172
	global_load_dword v88, v172, s[98:99]
	global_load_dwordx2 v[56:57], v170, s[98:99]
	global_load_dwordx2 v[58:59], v170, s[98:99] offset:512
	global_load_dwordx2 v[60:61], v170, s[98:99] offset:1024
	global_load_dwordx2 v[62:63], v170, s[98:99] offset:1536
	global_load_dwordx2 v[72:73], v171, s[98:99]
	global_load_dwordx2 v[74:75], v171, s[98:99] offset:512
	global_load_dwordx2 v[76:77], v171, s[98:99] offset:1024
	global_load_dwordx2 v[78:79], v171, s[98:99] offset:1536
	v_add_u32_e32 v170, 0x400000, v170
	v_add_u32_e32 v171, 0x400000, v171
	v_add_u32_e32 v172, 0x2000, v172
	global_load_dword v90, v172, s[98:99]
	global_load_dwordx2 v[64:65], v170, s[98:99]
	global_load_dwordx2 v[66:67], v170, s[98:99] offset:512
	global_load_dwordx2 v[68:69], v170, s[98:99] offset:1024
	global_load_dwordx2 v[70:71], v170, s[98:99] offset:1536
	global_load_dwordx2 v[80:81], v171, s[98:99]
	global_load_dwordx2 v[82:83], v171, s[98:99] offset:512
	global_load_dwordx2 v[84:85], v171, s[98:99] offset:1024
	global_load_dwordx2 v[86:87], v171, s[98:99] offset:1536
	v_add_u32_e32 v170, 0x400000, v170
	v_add_u32_e32 v171, 0x400000, v171
	v_add_u32_e32 v172, 0x2000, v172
	s_waitcnt vmcnt(31)
	v_lshlrev_b32_e32 v96, 16, v20
	v_and_b32_e32 v97, 0xffff0000, v20
	v_lshlrev_b32_e32 v98, 16, v21
	v_and_b32_e32 v99, 0xffff0000, v21
	v_lshlrev_b32_e32 v100, 16, v22
	v_and_b32_e32 v101, 0xffff0000, v22
	v_lshlrev_b32_e32 v102, 16, v23
	v_and_b32_e32 v103, 0xffff0000, v23
	v_lshlrev_b32_e32 v104, 16, v24
	v_and_b32_e32 v105, 0xffff0000, v24
	v_lshlrev_b32_e32 v106, 16, v25
	v_and_b32_e32 v107, 0xffff0000, v25
	v_lshlrev_b32_e32 v108, 16, v26
	v_and_b32_e32 v109, 0xffff0000, v26
	v_lshlrev_b32_e32 v110, 16, v27
	v_and_b32_e32 v111, 0xffff0000, v27
	v_pk_mul_f32 v[128:129], v[96:97], v[96:97]
	v_pk_fma_f32 v[128:129], v[98:99], v[98:99], v[128:129]
	v_pk_fma_f32 v[128:129], v[100:101], v[100:101], v[128:129]
	v_pk_fma_f32 v[128:129], v[102:103], v[102:103], v[128:129]
	v_pk_fma_f32 v[128:129], v[104:105], v[104:105], v[128:129]
	v_pk_fma_f32 v[128:129], v[106:107], v[106:107], v[128:129]
	v_pk_fma_f32 v[128:129], v[108:109], v[108:109], v[128:129]
	v_pk_fma_f32 v[128:129], v[110:111], v[110:111], v[128:129]
	s_nop 0
	v_add_f32_e32 v128, v128, v129
	s_waitcnt vmcnt(22)
;     __device__ __forceinline__ float* out() const { return (float*)karg_in(33); }
; __device__ __forceinline__ float ssq4(v4f v) { return (v.x * v.x + v.y * v.y) + (v.z * v.z + v.w * v.w); }
; template <int R, bool BASE_F32, bool OUT_F32>
; __device__ __forceinline__ void rows_res(const Ctx& C, int m0, int stride, int mx, const float* gpost, float scale, int lane) {
;     ...
;     for (int r = 0; r < R; ++r) { float s = 0.f;
; #pragma unroll
;         for (int j = 0; j < 4; ++j) s += ssq4(d[r][j]);
;         r1[r] = s; }
; #pragma unroll
;     for (int r = 0; r < R; ++r) r1[r] = rsqrtf(wave_sum(r1[r]) * (1.f / DM) + EPS) * scale;
; #pragma unroll
;     for (int j = 0; j < 4; ++j) { const v4f gp = ld4_f32(gpost + 4 * lane + 256 * j);
; #pragma unroll
;         for (int r = 0; r < R; ++r) d[r][j] = b[r][j] + d[r][j] * r1[r] * gp; }
;     if (OUT_F32) { float* Y = C.out();
; #pragma unroll
;         for (int r = 0; r < R; ++r)
; #pragma unroll
;             for (int j = 0; j < 4; ++j) if (ok[r]) *(v4f*)(Y + (size_t)mr[r] * DM + 4 * lane + 256 * j) = d[r][j];
;     } else { float* rs = C.RS(); float t[R];
; #pragma unroll
;         for (int r = 0; r < R; ++r) { float s = 0.f;
; #pragma unroll
;             for (int j = 0; j < 4; ++j) s += ssq4(d[r][j]);
;             t[r] = s; }
	v_lshlrev_b32_e32 v112, 16, v28
	v_and_b32_e32 v113, 0xffff0000, v28
	v_lshlrev_b32_e32 v114, 16, v29
	v_and_b32_e32 v115, 0xffff0000, v29
	v_lshlrev_b32_e32 v116, 16, v30
	v_and_b32_e32 v117, 0xffff0000, v30
	v_lshlrev_b32_e32 v118, 16, v31
	v_and_b32_e32 v119, 0xffff0000, v31
	v_lshlrev_b32_e32 v120, 16, v32
	v_and_b32_e32 v121, 0xffff0000, v32
	v_lshlrev_b32_e32 v122, 16, v33
	v_and_b32_e32 v123, 0xffff0000, v33
	v_lshlrev_b32_e32 v124, 16, v34
	v_and_b32_e32 v125, 0xffff0000, v34
	v_lshlrev_b32_e32 v126, 16, v35
	v_and_b32_e32 v127, 0xffff0000, v35
	v_pk_mul_f32 v[130:131], v[112:113], v[112:113]
	v_pk_fma_f32 v[130:131], v[114:115], v[114:115], v[130:131]
	v_pk_fma_f32 v[130:131], v[116:117], v[116:117], v[130:131]
	v_pk_fma_f32 v[130:131], v[118:119], v[118:119], v[130:131]
	v_pk_fma_f32 v[130:131], v[120:121], v[120:121], v[130:131]
	v_pk_fma_f32 v[130:131], v[122:123], v[122:123], v[130:131]
	v_pk_fma_f32 v[130:131], v[124:125], v[124:125], v[130:131]
	v_pk_fma_f32 v[130:131], v[126:127], v[126:127], v[130:131]
	s_nop 0
	v_add_f32_e32 v130, v130, v131
	s_nop 1
	v_add_f32_dpp v128, v128, v128 quad_perm:[1,0,3,2] row_mask:0xf bank_mask:0xf
	v_add_f32_dpp v130, v130, v130 quad_perm:[1,0,3,2] row_mask:0xf bank_mask:0xf
	s_nop 0
	v_add_f32_dpp v128, v128, v128 quad_perm:[2,3,0,1] row_mask:0xf bank_mask:0xf
	v_add_f32_dpp v130, v130, v130 quad_perm:[2,3,0,1] row_mask:0xf bank_mask:0xf
	s_nop 0
	v_add_f32_dpp v128, v128, v128 row_half_mirror row_mask:0xf bank_mask:0xf
	v_add_f32_dpp v130, v130, v130 row_half_mirror row_mask:0xf bank_mask:0xf
	s_nop 0
	v_add_f32_dpp v128, v128, v128 row_mirror row_mask:0xf bank_mask:0xf
	v_add_f32_dpp v130, v130, v130 row_mirror row_mask:0xf bank_mask:0xf
	s_nop 0
	ds_bpermute_b32 v136, v187, v128
	ds_bpermute_b32 v137, v187, v130
	s_waitcnt lgkmcnt(0)
	v_add_f32_e32 v128, v128, v136
	v_add_f32_e32 v130, v130, v137
	ds_bpermute_b32 v136, v188, v128
	ds_bpermute_b32 v137, v188, v130
	s_waitcnt lgkmcnt(0)
	v_add_f32_e32 v128, v128, v136
	v_add_f32_e32 v130, v130, v137
	v_fmamk_f32 v128, v128, 0x3a800000, v138
	v_fmamk_f32 v130, v130, 0x3a800000, v138
	s_nop 0
	v_rsq_f32_e32 v128, v128
	v_rsq_f32_e32 v130, v130
	s_nop 1
	v_mul_f32_e32 v128, 0.5, v128
	v_mul_f32_e32 v130, 0.5, v130
	s_waitcnt vmcnt(18)
	v_pk_mul_f32 v[96:97], v[128:129], v[96:97] op_sel_hi:[0,1]
	v_pk_mul_f32 v[98:99], v[128:129], v[98:99] op_sel_hi:[0,1]
	v_pk_mul_f32 v[100:101], v[128:129], v[100:101] op_sel_hi:[0,1]
	v_pk_mul_f32 v[102:103], v[128:129], v[102:103] op_sel_hi:[0,1]
	v_pk_mul_f32 v[104:105], v[128:129], v[104:105] op_sel_hi:[0,1]
	v_pk_mul_f32 v[106:107], v[128:129], v[106:107] op_sel_hi:[0,1]
	v_pk_mul_f32 v[108:109], v[128:129], v[108:109] op_sel_hi:[0,1]
	v_pk_mul_f32 v[110:111], v[128:129], v[110:111] op_sel_hi:[0,1]
	v_pk_mul_f32 v[96:97], v[96:97], v[192:193]
	v_pk_mul_f32 v[98:99], v[98:99], v[194:195]
	v_pk_mul_f32 v[100:101], v[100:101], v[196:197]
	v_pk_mul_f32 v[102:103], v[102:103], v[198:199]
	v_pk_mul_f32 v[104:105], v[104:105], v[200:201]
	v_pk_mul_f32 v[106:107], v[106:107], v[202:203]
	v_pk_mul_f32 v[108:109], v[108:109], v[204:205]
	v_pk_mul_f32 v[110:111], v[110:111], v[206:207]
	v_lshlrev_b32_e32 v20, 16, v36
	v_and_b32_e32 v21, 0xffff0000, v36
	v_lshlrev_b32_e32 v22, 16, v37
	v_and_b32_e32 v23, 0xffff0000, v37
	v_lshlrev_b32_e32 v24, 16, v38
	v_and_b32_e32 v25, 0xffff0000, v38
	v_lshlrev_b32_e32 v26, 16, v39
	v_and_b32_e32 v27, 0xffff0000, v39
	v_pk_fma_f32 v[96:97], v[52:53], v[20:21], v[96:97] op_sel_hi:[0,1,1]
	v_pk_fma_f32 v[98:99], v[52:53], v[22:23], v[98:99] op_sel_hi:[0,1,1]
	v_pk_fma_f32 v[100:101], v[52:53], v[24:25], v[100:101] op_sel_hi:[0,1,1]
	v_pk_fma_f32 v[102:103], v[52:53], v[26:27], v[102:103] op_sel_hi:[0,1,1]
	v_lshlrev_b32_e32 v20, 16, v40
	v_and_b32_e32 v21, 0xffff0000, v40
	v_lshlrev_b32_e32 v22, 16, v41
	v_and_b32_e32 v23, 0xffff0000, v41
	v_lshlrev_b32_e32 v24, 16, v42
	v_and_b32_e32 v25, 0xffff0000, v42
	v_lshlrev_b32_e32 v26, 16, v43
	v_and_b32_e32 v27, 0xffff0000, v43
	v_pk_fma_f32 v[104:105], v[52:53], v[20:21], v[104:105] op_sel_hi:[0,1,1]
	v_pk_fma_f32 v[106:107], v[52:53], v[22:23], v[106:107] op_sel_hi:[0,1,1]
	v_pk_fma_f32 v[108:109], v[52:53], v[24:25], v[108:109] op_sel_hi:[0,1,1]
	v_pk_fma_f32 v[110:111], v[52:53], v[26:27], v[110:111] op_sel_hi:[0,1,1]
	v_pk_mul_f32 v[132:133], v[96:97], v[96:97]
	v_pk_fma_f32 v[132:133], v[98:99], v[98:99], v[132:133]
	v_pk_fma_f32 v[132:133], v[100:101], v[100:101], v[132:133]
	v_pk_fma_f32 v[132:133], v[102:103], v[102:103], v[132:133]
	v_pk_fma_f32 v[132:133], v[104:105], v[104:105], v[132:133]
	v_pk_fma_f32 v[132:133], v[106:107], v[106:107], v[132:133]
	v_pk_fma_f32 v[132:133], v[108:109], v[108:109], v[132:133]
	v_pk_fma_f32 v[132:133], v[110:111], v[110:111], v[132:133]
	s_nop 0
	v_add_f32_e32 v132, v132, v133
	v_pk_mul_f32 v[112:113], v[130:131], v[112:113] op_sel_hi:[0,1]
	v_pk_mul_f32 v[114:115], v[130:131], v[114:115] op_sel_hi:[0,1]
	v_pk_mul_f32 v[116:117], v[130:131], v[116:117] op_sel_hi:[0,1]
	v_pk_mul_f32 v[118:119], v[130:131], v[118:119] op_sel_hi:[0,1]
	v_pk_mul_f32 v[120:121], v[130:131], v[120:121] op_sel_hi:[0,1]
	v_pk_mul_f32 v[122:123], v[130:131], v[122:123] op_sel_hi:[0,1]
	v_pk_mul_f32 v[124:125], v[130:131], v[124:125] op_sel_hi:[0,1]
	v_pk_mul_f32 v[126:127], v[130:131], v[126:127] op_sel_hi:[0,1]
	v_pk_mul_f32 v[112:113], v[112:113], v[192:193]
	v_pk_mul_f32 v[114:115], v[114:115], v[194:195]
	v_pk_mul_f32 v[116:117], v[116:117], v[196:197]
	v_pk_mul_f32 v[118:119], v[118:119], v[198:199]
	v_pk_mul_f32 v[120:121], v[120:121], v[200:201]
	v_pk_mul_f32 v[122:123], v[122:123], v[202:203]
;     __device__ __forceinline__ float* out() const { return (float*)karg_in(33); }
; __device__ __forceinline__ const float* xrow_ptr(const Ctx& C, int row) { return row < MPROMPT ? C.in(0) + (size_t)row * DM : C.in(1) + (size_t)(row - MPROMPT) * DM; }
; __device__ __forceinline__ v4f ld4_bf16(const bf16* p) { const v2u w = *(const v2u*)p; return (v4f){bf_lo(w.x), bf_hi(w.x), bf_lo(w.y), bf_hi(w.y)}; }
; template <int R, bool BASE_F32, bool OUT_F32>
; __device__ __forceinline__ void rows_res(const Ctx& C, int m0, int stride, int mx, const float* gpost, float scale, int lane) {
;     ...
;     for (int r = 0; r < R; ++r) { mr[r] = (r == 4) ? mx : m0 + r * stride; ok[r] = (r == 4) ? (mx < M) : (mr[r] < MPROMPT); const int mm = ok[r] ? mr[r] : 0;
; #pragma unroll
;         for (int j = 0; j < 4; ++j) d[r][j] = ld4_bf16(D + (size_t)mm * DM + 4 * lane + 256 * j);
;         if (BASE_F32) { const float* x = xrow_ptr(C, mm);
; #pragma unroll
;             for (int j = 0; j < 4; ++j) b[r][j] = ld4_f32(x + 4 * lane + 256 * j);
;         } else { const float inv = C.RS()[mm];
; #pragma unroll
;             for (int j = 0; j < 4; ++j) b[r][j] = ld4_bf16(XN + (size_t)mm * DM + 4 * lane + 256 * j) * inv;
;         } }
;     ...
;     for (int r = 0; r < R; ++r) r1[r] = rsqrtf(wave_sum(r1[r]) * (1.f / DM) + EPS) * scale;
; #pragma unroll
;     for (int j = 0; j < 4; ++j) { const v4f gp = ld4_f32(gpost + 4 * lane + 256 * j);
; #pragma unroll
;         for (int r = 0; r < R; ++r) d[r][j] = b[r][j] + d[r][j] * r1[r] * gp; }
;     if (OUT_F32) { float* Y = C.out();
; #pragma unroll
;         for (int r = 0; r < R; ++r)
; #pragma unroll
;             for (int j = 0; j < 4; ++j) if (ok[r]) *(v4f*)(Y + (size_t)mr[r] * DM + 4 * lane + 256 * j) = d[r][j];
;     } else { float* rs = C.RS(); float t[R];
; #pragma unroll
;         for (int r = 0; r < R; ++r) { float s = 0.f;
; #pragma unroll
;             for (int j = 0; j < 4; ++j) s += ssq4(d[r][j]);
;             t[r] = s; }
; #pragma unroll
;         for (int r = 0; r < R; ++r) t[r] = wave_sum(t[r]) * (1.f / DM) + EPS;
; #pragma unroll
;         for (int r = 0; r < R; ++r) { const float rstd = rsqrtf(t[r]);
; #pragma unroll
;             for (int j = 0; j < 4; ++j) if (ok[r]) st4_bf16(XN + (size_t)mr[r] * DM + 4 * lane + 256 * j, d[r][j] * rstd);
;             if (lane == 0 && ok[r]) rs[mr[r]] = sqrtf(t[r]); }
	v_pk_mul_f32 v[124:125], v[124:125], v[204:205]
	v_pk_mul_f32 v[126:127], v[126:127], v[206:207]
	v_lshlrev_b32_e32 v28, 16, v44
	v_and_b32_e32 v29, 0xffff0000, v44
	v_lshlrev_b32_e32 v30, 16, v45
	v_and_b32_e32 v31, 0xffff0000, v45
	v_lshlrev_b32_e32 v32, 16, v46
	v_and_b32_e32 v33, 0xffff0000, v46
	v_lshlrev_b32_e32 v34, 16, v47
	v_and_b32_e32 v35, 0xffff0000, v47
	v_pk_fma_f32 v[112:113], v[54:55], v[28:29], v[112:113] op_sel_hi:[0,1,1]
	v_pk_fma_f32 v[114:115], v[54:55], v[30:31], v[114:115] op_sel_hi:[0,1,1]
	v_pk_fma_f32 v[116:117], v[54:55], v[32:33], v[116:117] op_sel_hi:[0,1,1]
	v_pk_fma_f32 v[118:119], v[54:55], v[34:35], v[118:119] op_sel_hi:[0,1,1]
	v_lshlrev_b32_e32 v28, 16, v48
	v_and_b32_e32 v29, 0xffff0000, v48
	v_lshlrev_b32_e32 v30, 16, v49
	v_and_b32_e32 v31, 0xffff0000, v49
	v_lshlrev_b32_e32 v32, 16, v50
	v_and_b32_e32 v33, 0xffff0000, v50
	v_lshlrev_b32_e32 v34, 16, v51
	v_and_b32_e32 v35, 0xffff0000, v51
	v_pk_fma_f32 v[120:121], v[54:55], v[28:29], v[120:121] op_sel_hi:[0,1,1]
	v_pk_fma_f32 v[122:123], v[54:55], v[30:31], v[122:123] op_sel_hi:[0,1,1]
	v_pk_fma_f32 v[124:125], v[54:55], v[32:33], v[124:125] op_sel_hi:[0,1,1]
	v_pk_fma_f32 v[126:127], v[54:55], v[34:35], v[126:127] op_sel_hi:[0,1,1]
	v_pk_mul_f32 v[134:135], v[112:113], v[112:113]
	v_pk_fma_f32 v[134:135], v[114:115], v[114:115], v[134:135]
	v_pk_fma_f32 v[134:135], v[116:117], v[116:117], v[134:135]
	v_pk_fma_f32 v[134:135], v[118:119], v[118:119], v[134:135]
	v_pk_fma_f32 v[134:135], v[120:121], v[120:121], v[134:135]
	v_pk_fma_f32 v[134:135], v[122:123], v[122:123], v[134:135]
	v_pk_fma_f32 v[134:135], v[124:125], v[124:125], v[134:135]
	v_pk_fma_f32 v[134:135], v[126:127], v[126:127], v[134:135]
	s_nop 0
	v_add_f32_e32 v134, v134, v135
	global_load_dword v52, v172, s[98:99]
	global_load_dwordx2 v[20:21], v170, s[98:99]
	global_load_dwordx2 v[22:23], v170, s[98:99] offset:512
	global_load_dwordx2 v[24:25], v170, s[98:99] offset:1024
	global_load_dwordx2 v[26:27], v170, s[98:99] offset:1536
	global_load_dwordx2 v[36:37], v171, s[98:99]
	global_load_dwordx2 v[38:39], v171, s[98:99] offset:512
	global_load_dwordx2 v[40:41], v171, s[98:99] offset:1024
	global_load_dwordx2 v[42:43], v171, s[98:99] offset:1536
	v_add_u32_e32 v170, 0x400000, v170
	v_add_u32_e32 v171, 0x400000, v171
	v_add_u32_e32 v172, 0x2000, v172
	global_load_dword v54, v172, s[98:99]
	global_load_dwordx2 v[28:29], v170, s[98:99]
	global_load_dwordx2 v[30:31], v170, s[98:99] offset:512
	global_load_dwordx2 v[32:33], v170, s[98:99] offset:1024
	global_load_dwordx2 v[34:35], v170, s[98:99] offset:1536
	global_load_dwordx2 v[44:45], v171, s[98:99]
	global_load_dwordx2 v[46:47], v171, s[98:99] offset:512
	global_load_dwordx2 v[48:49], v171, s[98:99] offset:1024
	global_load_dwordx2 v[50:51], v171, s[98:99] offset:1536
	v_add_u32_e32 v170, 0x400000, v170
	v_add_u32_e32 v171, 0x400000, v171
	v_add_u32_e32 v172, 0x2000, v172
	s_nop 1
	v_add_f32_dpp v132, v132, v132 quad_perm:[1,0,3,2] row_mask:0xf bank_mask:0xf
	v_add_f32_dpp v134, v134, v134 quad_perm:[1,0,3,2] row_mask:0xf bank_mask:0xf
	s_nop 0
	v_add_f32_dpp v132, v132, v132 quad_perm:[2,3,0,1] row_mask:0xf bank_mask:0xf
	v_add_f32_dpp v134, v134, v134 quad_perm:[2,3,0,1] row_mask:0xf bank_mask:0xf
	s_nop 0
	v_add_f32_dpp v132, v132, v132 row_half_mirror row_mask:0xf bank_mask:0xf
	v_add_f32_dpp v134, v134, v134 row_half_mirror row_mask:0xf bank_mask:0xf
	s_nop 0
	v_add_f32_dpp v132, v132, v132 row_mirror row_mask:0xf bank_mask:0xf
	v_add_f32_dpp v134, v134, v134 row_mirror row_mask:0xf bank_mask:0xf
	s_nop 0
	ds_bpermute_b32 v136, v187, v132
	ds_bpermute_b32 v137, v187, v134
	s_waitcnt lgkmcnt(0)
	v_add_f32_e32 v132, v132, v136
	v_add_f32_e32 v134, v134, v137
	ds_bpermute_b32 v136, v188, v132
	ds_bpermute_b32 v137, v188, v134
	s_waitcnt lgkmcnt(0)
	v_add_f32_e32 v132, v132, v136
	v_add_f32_e32 v134, v134, v137
	v_fmamk_f32 v164, v132, 0x3a800000, v138
	v_fmamk_f32 v167, v134, 0x3a800000, v138
	s_nop 0
	v_rsq_f32_e32 v132, v164
	v_rsq_f32_e32 v134, v167
	v_sqrt_f32_e32 v165, v164
	v_sqrt_f32_e32 v168, v167
	s_nop 1
	v_pk_mul_f32 v[140:141], v[96:97], v[132:133] op_sel_hi:[1,0]
	v_cvt_pk_bf16_f32 v148, v140, v141
	v_pk_mul_f32 v[142:143], v[98:99], v[132:133] op_sel_hi:[1,0]
	v_cvt_pk_bf16_f32 v149, v142, v143
	v_pk_mul_f32 v[144:145], v[100:101], v[132:133] op_sel_hi:[1,0]
	v_cvt_pk_bf16_f32 v150, v144, v145
	v_pk_mul_f32 v[146:147], v[102:103], v[132:133] op_sel_hi:[1,0]
	v_cvt_pk_bf16_f32 v151, v146, v147
	v_pk_mul_f32 v[140:141], v[104:105], v[132:133] op_sel_hi:[1,0]
	v_cvt_pk_bf16_f32 v152, v140, v141
	v_pk_mul_f32 v[142:143], v[106:107], v[132:133] op_sel_hi:[1,0]
	v_cvt_pk_bf16_f32 v153, v142, v143
	v_pk_mul_f32 v[144:145], v[108:109], v[132:133] op_sel_hi:[1,0]
	v_cvt_pk_bf16_f32 v154, v144, v145
	v_pk_mul_f32 v[146:147], v[110:111], v[132:133] op_sel_hi:[1,0]
	v_cvt_pk_bf16_f32 v155, v146, v147
	global_store_dwordx2 v173, v[148:149], s[98:99]
	global_store_dwordx2 v173, v[150:151], s[98:99] offset:512
	global_store_dwordx2 v173, v[152:153], s[98:99] offset:1024
	global_store_dwordx2 v173, v[154:155], s[98:99] offset:1536
	v_add_u32_e32 v173, 0x400000, v173
	v_pk_mul_f32 v[140:141], v[112:113], v[134:135] op_sel_hi:[1,0]
	v_cvt_pk_bf16_f32 v156, v140, v141
	v_pk_mul_f32 v[142:143], v[114:115], v[134:135] op_sel_hi:[1,0]
	v_cvt_pk_bf16_f32 v157, v142, v143
	v_pk_mul_f32 v[144:145], v[116:117], v[134:135] op_sel_hi:[1,0]
	v_cvt_pk_bf16_f32 v158, v144, v145
	v_pk_mul_f32 v[146:147], v[118:119], v[134:135] op_sel_hi:[1,0]
	v_cvt_pk_bf16_f32 v159, v146, v147
	v_pk_mul_f32 v[140:141], v[120:121], v[134:135] op_sel_hi:[1,0]
	v_cvt_pk_bf16_f32 v160, v140, v141
	v_pk_mul_f32 v[142:143], v[122:123], v[134:135] op_sel_hi:[1,0]
	v_cvt_pk_bf16_f32 v161, v142, v143
	v_pk_mul_f32 v[144:145], v[124:125], v[134:135] op_sel_hi:[1,0]
	v_cvt_pk_bf16_f32 v162, v144, v145
	v_pk_mul_f32 v[146:147], v[126:127], v[134:135] op_sel_hi:[1,0]
	v_cvt_pk_bf16_f32 v163, v146, v147
	global_store_dwordx2 v173, v[156:157], s[98:99]
	global_store_dwordx2 v173, v[158:159], s[98:99] offset:512
	global_store_dwordx2 v173, v[160:161], s[98:99] offset:1024
	global_store_dwordx2 v173, v[162:163], s[98:99] offset:1536
	v_add_u32_e32 v173, 0x400000, v173
	v_add_u32_e32 v166, -1, v165
	v_fma_f32 v140, -v166, v165, v164
	v_cmp_ge_f32_e32 vcc, 0, v140
	v_add_u32_e32 v141, 1, v165
	v_cndmask_b32_e32 v166, v165, v166, vcc
	v_fma_f32 v140, -v141, v165, v164
	v_cmp_lt_f32_e32 vcc, 0, v140
	s_nop 1
	v_cndmask_b32_e32 v165, v166, v141, vcc
	v_add_u32_e32 v169, -1, v168
	v_fma_f32 v142, -v169, v168, v167
	v_cmp_ge_f32_e32 vcc, 0, v142
	v_add_u32_e32 v143, 1, v168
	v_cndmask_b32_e32 v169, v168, v169, vcc
	v_fma_f32 v142, -v143, v168, v167
	v_cmp_lt_f32_e32 vcc, 0, v142
	s_nop 1
	v_cndmask_b32_e32 v168, v169, v143, vcc
	s_mov_b64 exec, 1
	global_store_dword v174, v165, s[98:99]
	v_add_u32_e32 v174, 0x2000, v174
	global_store_dword v174, v168, s[98:99]
	v_add_u32_e32 v174, 0x2000, v174
	s_mov_b64 exec, -1
	s_waitcnt vmcnt(41)
;     __device__ __forceinline__ float* out() const { return (float*)karg_in(33); }
; __device__ __forceinline__ float ssq4(v4f v) { return (v.x * v.x + v.y * v.y) + (v.z * v.z + v.w * v.w); }
; template <int R, bool BASE_F32, bool OUT_F32>
; __device__ __forceinline__ void rows_res(const Ctx& C, int m0, int stride, int mx, const float* gpost, float scale, int lane) {
;     ...
;     for (int r = 0; r < R; ++r) { float s = 0.f;
; #pragma unroll
;         for (int j = 0; j < 4; ++j) s += ssq4(d[r][j]);
;         r1[r] = s; }
; #pragma unroll
;     for (int r = 0; r < R; ++r) r1[r] = rsqrtf(wave_sum(r1[r]) * (1.f / DM) + EPS) * scale;
; #pragma unroll
;     for (int j = 0; j < 4; ++j) { const v4f gp = ld4_f32(gpost + 4 * lane + 256 * j);
; #pragma unroll
;         for (int r = 0; r < R; ++r) d[r][j] = b[r][j] + d[r][j] * r1[r] * gp; }
;     if (OUT_F32) { float* Y = C.out();
; #pragma unroll
;         for (int r = 0; r < R; ++r)
; #pragma unroll
;             for (int j = 0; j < 4; ++j) if (ok[r]) *(v4f*)(Y + (size_t)mr[r] * DM + 4 * lane + 256 * j) = d[r][j];
;     } else { float* rs = C.RS(); float t[R];
; #pragma unroll
;         for (int r = 0; r < R; ++r) { float s = 0.f;
; #pragma unroll
;             for (int j = 0; j < 4; ++j) s += ssq4(d[r][j]);
;             t[r] = s; }
	v_lshlrev_b32_e32 v96, 16, v56
	v_and_b32_e32 v97, 0xffff0000, v56
	v_lshlrev_b32_e32 v98, 16, v57
	v_and_b32_e32 v99, 0xffff0000, v57
	v_lshlrev_b32_e32 v100, 16, v58
	v_and_b32_e32 v101, 0xffff0000, v58
	v_lshlrev_b32_e32 v102, 16, v59
	v_and_b32_e32 v103, 0xffff0000, v59
	v_lshlrev_b32_e32 v104, 16, v60
	v_and_b32_e32 v105, 0xffff0000, v60
	v_lshlrev_b32_e32 v106, 16, v61
	v_and_b32_e32 v107, 0xffff0000, v61
	v_lshlrev_b32_e32 v108, 16, v62
	v_and_b32_e32 v109, 0xffff0000, v62
	v_lshlrev_b32_e32 v110, 16, v63
	v_and_b32_e32 v111, 0xffff0000, v63
	v_pk_mul_f32 v[128:129], v[96:97], v[96:97]
	v_pk_fma_f32 v[128:129], v[98:99], v[98:99], v[128:129]
	v_pk_fma_f32 v[128:129], v[100:101], v[100:101], v[128:129]
	v_pk_fma_f32 v[128:129], v[102:103], v[102:103], v[128:129]
	v_pk_fma_f32 v[128:129], v[104:105], v[104:105], v[128:129]
	v_pk_fma_f32 v[128:129], v[106:107], v[106:107], v[128:129]
	v_pk_fma_f32 v[128:129], v[108:109], v[108:109], v[128:129]
	v_pk_fma_f32 v[128:129], v[110:111], v[110:111], v[128:129]
	s_nop 0
	v_add_f32_e32 v128, v128, v129
	s_waitcnt vmcnt(32)
	v_lshlrev_b32_e32 v112, 16, v64
	v_and_b32_e32 v113, 0xffff0000, v64
	v_lshlrev_b32_e32 v114, 16, v65
	v_and_b32_e32 v115, 0xffff0000, v65
	v_lshlrev_b32_e32 v116, 16, v66
	v_and_b32_e32 v117, 0xffff0000, v66
	v_lshlrev_b32_e32 v118, 16, v67
	v_and_b32_e32 v119, 0xffff0000, v67
	v_lshlrev_b32_e32 v120, 16, v68
	v_and_b32_e32 v121, 0xffff0000, v68
	v_lshlrev_b32_e32 v122, 16, v69
	v_and_b32_e32 v123, 0xffff0000, v69
	v_lshlrev_b32_e32 v124, 16, v70
	v_and_b32_e32 v125, 0xffff0000, v70
	v_lshlrev_b32_e32 v126, 16, v71
	v_and_b32_e32 v127, 0xffff0000, v71
	v_pk_mul_f32 v[130:131], v[112:113], v[112:113]
	v_pk_fma_f32 v[130:131], v[114:115], v[114:115], v[130:131]
	v_pk_fma_f32 v[130:131], v[116:117], v[116:117], v[130:131]
	v_pk_fma_f32 v[130:131], v[118:119], v[118:119], v[130:131]
	v_pk_fma_f32 v[130:131], v[120:121], v[120:121], v[130:131]
	v_pk_fma_f32 v[130:131], v[122:123], v[122:123], v[130:131]
	v_pk_fma_f32 v[130:131], v[124:125], v[124:125], v[130:131]
	v_pk_fma_f32 v[130:131], v[126:127], v[126:127], v[130:131]
	s_nop 0
	v_add_f32_e32 v130, v130, v131
	s_nop 1
	v_add_f32_dpp v128, v128, v128 quad_perm:[1,0,3,2] row_mask:0xf bank_mask:0xf
	v_add_f32_dpp v130, v130, v130 quad_perm:[1,0,3,2] row_mask:0xf bank_mask:0xf
	s_nop 0
	v_add_f32_dpp v128, v128, v128 quad_perm:[2,3,0,1] row_mask:0xf bank_mask:0xf
	v_add_f32_dpp v130, v130, v130 quad_perm:[2,3,0,1] row_mask:0xf bank_mask:0xf
	s_nop 0
	v_add_f32_dpp v128, v128, v128 row_half_mirror row_mask:0xf bank_mask:0xf
	v_add_f32_dpp v130, v130, v130 row_half_mirror row_mask:0xf bank_mask:0xf
	s_nop 0
	v_add_f32_dpp v128, v128, v128 row_mirror row_mask:0xf bank_mask:0xf
	v_add_f32_dpp v130, v130, v130 row_mirror row_mask:0xf bank_mask:0xf
	s_nop 0
	ds_bpermute_b32 v136, v187, v128
	ds_bpermute_b32 v137, v187, v130
	s_waitcnt lgkmcnt(0)
	v_add_f32_e32 v128, v128, v136
	v_add_f32_e32 v130, v130, v137
	ds_bpermute_b32 v136, v188, v128
	ds_bpermute_b32 v137, v188, v130
	s_waitcnt lgkmcnt(0)
	v_add_f32_e32 v128, v128, v136
	v_add_f32_e32 v130, v130, v137
	v_fmamk_f32 v128, v128, 0x3a800000, v138
	v_fmamk_f32 v130, v130, 0x3a800000, v138
	s_nop 0
	v_rsq_f32_e32 v128, v128
	v_rsq_f32_e32 v130, v130
	s_nop 1
	v_mul_f32_e32 v128, 0.5, v128
	v_mul_f32_e32 v130, 0.5, v130
	s_waitcnt vmcnt(28)
	v_pk_mul_f32 v[96:97], v[128:129], v[96:97] op_sel_hi:[0,1]
	v_pk_mul_f32 v[98:99], v[128:129], v[98:99] op_sel_hi:[0,1]
	v_pk_mul_f32 v[100:101], v[128:129], v[100:101] op_sel_hi:[0,1]
	v_pk_mul_f32 v[102:103], v[128:129], v[102:103] op_sel_hi:[0,1]
	v_pk_mul_f32 v[104:105], v[128:129], v[104:105] op_sel_hi:[0,1]
	v_pk_mul_f32 v[106:107], v[128:129], v[106:107] op_sel_hi:[0,1]
	v_pk_mul_f32 v[108:109], v[128:129], v[108:109] op_sel_hi:[0,1]
	v_pk_mul_f32 v[110:111], v[128:129], v[110:111] op_sel_hi:[0,1]
	v_pk_mul_f32 v[96:97], v[96:97], v[192:193]
	v_pk_mul_f32 v[98:99], v[98:99], v[194:195]
	v_pk_mul_f32 v[100:101], v[100:101], v[196:197]
	v_pk_mul_f32 v[102:103], v[102:103], v[198:199]
	v_pk_mul_f32 v[104:105], v[104:105], v[200:201]
	v_pk_mul_f32 v[106:107], v[106:107], v[202:203]
	v_pk_mul_f32 v[108:109], v[108:109], v[204:205]
	v_pk_mul_f32 v[110:111], v[110:111], v[206:207]
	v_lshlrev_b32_e32 v56, 16, v72
	v_and_b32_e32 v57, 0xffff0000, v72
	v_lshlrev_b32_e32 v58, 16, v73
	v_and_b32_e32 v59, 0xffff0000, v73
	v_lshlrev_b32_e32 v60, 16, v74
	v_and_b32_e32 v61, 0xffff0000, v74
	v_lshlrev_b32_e32 v62, 16, v75
	v_and_b32_e32 v63, 0xffff0000, v75
	v_pk_fma_f32 v[96:97], v[88:89], v[56:57], v[96:97] op_sel_hi:[0,1,1]
	v_pk_fma_f32 v[98:99], v[88:89], v[58:59], v[98:99] op_sel_hi:[0,1,1]
	v_pk_fma_f32 v[100:101], v[88:89], v[60:61], v[100:101] op_sel_hi:[0,1,1]
	v_pk_fma_f32 v[102:103], v[88:89], v[62:63], v[102:103] op_sel_hi:[0,1,1]
	v_lshlrev_b32_e32 v56, 16, v76
	v_and_b32_e32 v57, 0xffff0000, v76
	v_lshlrev_b32_e32 v58, 16, v77
	v_and_b32_e32 v59, 0xffff0000, v77
	v_lshlrev_b32_e32 v60, 16, v78
	v_and_b32_e32 v61, 0xffff0000, v78
	v_lshlrev_b32_e32 v62, 16, v79
	v_and_b32_e32 v63, 0xffff0000, v79
	v_pk_fma_f32 v[104:105], v[88:89], v[56:57], v[104:105] op_sel_hi:[0,1,1]
	v_pk_fma_f32 v[106:107], v[88:89], v[58:59], v[106:107] op_sel_hi:[0,1,1]
	v_pk_fma_f32 v[108:109], v[88:89], v[60:61], v[108:109] op_sel_hi:[0,1,1]
	v_pk_fma_f32 v[110:111], v[88:89], v[62:63], v[110:111] op_sel_hi:[0,1,1]
	v_pk_mul_f32 v[132:133], v[96:97], v[96:97]
	v_pk_fma_f32 v[132:133], v[98:99], v[98:99], v[132:133]
	v_pk_fma_f32 v[132:133], v[100:101], v[100:101], v[132:133]
	v_pk_fma_f32 v[132:133], v[102:103], v[102:103], v[132:133]
;     __device__ __forceinline__ float* out() const { return (float*)karg_in(33); }
; __device__ __forceinline__ const float* xrow_ptr(const Ctx& C, int row) { return row < MPROMPT ? C.in(0) + (size_t)row * DM : C.in(1) + (size_t)(row - MPROMPT) * DM; }
; __device__ __forceinline__ v4f ld4_bf16(const bf16* p) { const v2u w = *(const v2u*)p; return (v4f){bf_lo(w.x), bf_hi(w.x), bf_lo(w.y), bf_hi(w.y)}; }
; __device__ __forceinline__ float ssq4(v4f v) { return (v.x * v.x + v.y * v.y) + (v.z * v.z + v.w * v.w); }
; template <int R, bool BASE_F32, bool OUT_F32>
; __device__ __forceinline__ void rows_res(const Ctx& C, int m0, int stride, int mx, const float* gpost, float scale, int lane) {
;     ...
;     for (int r = 0; r < R; ++r) { mr[r] = (r == 4) ? mx : m0 + r * stride; ok[r] = (r == 4) ? (mx < M) : (mr[r] < MPROMPT); const int mm = ok[r] ? mr[r] : 0;
; #pragma unroll
;         for (int j = 0; j < 4; ++j) d[r][j] = ld4_bf16(D + (size_t)mm * DM + 4 * lane + 256 * j);
;         if (BASE_F32) { const float* x = xrow_ptr(C, mm);
; #pragma unroll
;             for (int j = 0; j < 4; ++j) b[r][j] = ld4_f32(x + 4 * lane + 256 * j);
;         } else { const float inv = C.RS()[mm];
; #pragma unroll
;             for (int j = 0; j < 4; ++j) b[r][j] = ld4_bf16(XN + (size_t)mm * DM + 4 * lane + 256 * j) * inv;
;         } }
; #pragma unroll
;     for (int r = 0; r < R; ++r) { float s = 0.f;
; #pragma unroll
;         for (int j = 0; j < 4; ++j) s += ssq4(d[r][j]);
;         r1[r] = s; }
; #pragma unroll
;     for (int r = 0; r < R; ++r) r1[r] = rsqrtf(wave_sum(r1[r]) * (1.f / DM) + EPS) * scale;
; #pragma unroll
;     for (int j = 0; j < 4; ++j) { const v4f gp = ld4_f32(gpost + 4 * lane + 256 * j);
; #pragma unroll
;         for (int r = 0; r < R; ++r) d[r][j] = b[r][j] + d[r][j] * r1[r] * gp; }
;     if (OUT_F32) { float* Y = C.out();
; #pragma unroll
;         for (int r = 0; r < R; ++r)
; #pragma unroll
;             for (int j = 0; j < 4; ++j) if (ok[r]) *(v4f*)(Y + (size_t)mr[r] * DM + 4 * lane + 256 * j) = d[r][j];
;     } else { float* rs = C.RS(); float t[R];
; #pragma unroll
;         for (int r = 0; r < R; ++r) { float s = 0.f;
; #pragma unroll
;             for (int j = 0; j < 4; ++j) s += ssq4(d[r][j]);
;             t[r] = s; }
; #pragma unroll
;         for (int r = 0; r < R; ++r) t[r] = wave_sum(t[r]) * (1.f / DM) + EPS;
	v_pk_fma_f32 v[132:133], v[104:105], v[104:105], v[132:133]
	v_pk_fma_f32 v[132:133], v[106:107], v[106:107], v[132:133]
	v_pk_fma_f32 v[132:133], v[108:109], v[108:109], v[132:133]
	v_pk_fma_f32 v[132:133], v[110:111], v[110:111], v[132:133]
	s_nop 0
	v_add_f32_e32 v132, v132, v133
	v_pk_mul_f32 v[112:113], v[130:131], v[112:113] op_sel_hi:[0,1]
	v_pk_mul_f32 v[114:115], v[130:131], v[114:115] op_sel_hi:[0,1]
	v_pk_mul_f32 v[116:117], v[130:131], v[116:117] op_sel_hi:[0,1]
	v_pk_mul_f32 v[118:119], v[130:131], v[118:119] op_sel_hi:[0,1]
	v_pk_mul_f32 v[120:121], v[130:131], v[120:121] op_sel_hi:[0,1]
	v_pk_mul_f32 v[122:123], v[130:131], v[122:123] op_sel_hi:[0,1]
	v_pk_mul_f32 v[124:125], v[130:131], v[124:125] op_sel_hi:[0,1]
	v_pk_mul_f32 v[126:127], v[130:131], v[126:127] op_sel_hi:[0,1]
	v_pk_mul_f32 v[112:113], v[112:113], v[192:193]
	v_pk_mul_f32 v[114:115], v[114:115], v[194:195]
	v_pk_mul_f32 v[116:117], v[116:117], v[196:197]
	v_pk_mul_f32 v[118:119], v[118:119], v[198:199]
	v_pk_mul_f32 v[120:121], v[120:121], v[200:201]
	v_pk_mul_f32 v[122:123], v[122:123], v[202:203]
	v_pk_mul_f32 v[124:125], v[124:125], v[204:205]
	v_pk_mul_f32 v[126:127], v[126:127], v[206:207]
	v_lshlrev_b32_e32 v64, 16, v80
	v_and_b32_e32 v65, 0xffff0000, v80
	v_lshlrev_b32_e32 v66, 16, v81
	v_and_b32_e32 v67, 0xffff0000, v81
	v_lshlrev_b32_e32 v68, 16, v82
	v_and_b32_e32 v69, 0xffff0000, v82
	v_lshlrev_b32_e32 v70, 16, v83
	v_and_b32_e32 v71, 0xffff0000, v83
	v_pk_fma_f32 v[112:113], v[90:91], v[64:65], v[112:113] op_sel_hi:[0,1,1]
	v_pk_fma_f32 v[114:115], v[90:91], v[66:67], v[114:115] op_sel_hi:[0,1,1]
	v_pk_fma_f32 v[116:117], v[90:91], v[68:69], v[116:117] op_sel_hi:[0,1,1]
	v_pk_fma_f32 v[118:119], v[90:91], v[70:71], v[118:119] op_sel_hi:[0,1,1]
	v_lshlrev_b32_e32 v64, 16, v84
	v_and_b32_e32 v65, 0xffff0000, v84
	v_lshlrev_b32_e32 v66, 16, v85
	v_and_b32_e32 v67, 0xffff0000, v85
	v_lshlrev_b32_e32 v68, 16, v86
	v_and_b32_e32 v69, 0xffff0000, v86
	v_lshlrev_b32_e32 v70, 16, v87
	v_and_b32_e32 v71, 0xffff0000, v87
	v_pk_fma_f32 v[120:121], v[90:91], v[64:65], v[120:121] op_sel_hi:[0,1,1]
	v_pk_fma_f32 v[122:123], v[90:91], v[66:67], v[122:123] op_sel_hi:[0,1,1]
	v_pk_fma_f32 v[124:125], v[90:91], v[68:69], v[124:125] op_sel_hi:[0,1,1]
	v_pk_fma_f32 v[126:127], v[90:91], v[70:71], v[126:127] op_sel_hi:[0,1,1]
	v_pk_mul_f32 v[134:135], v[112:113], v[112:113]
	v_pk_fma_f32 v[134:135], v[114:115], v[114:115], v[134:135]
	v_pk_fma_f32 v[134:135], v[116:117], v[116:117], v[134:135]
	v_pk_fma_f32 v[134:135], v[118:119], v[118:119], v[134:135]
	v_pk_fma_f32 v[134:135], v[120:121], v[120:121], v[134:135]
	v_pk_fma_f32 v[134:135], v[122:123], v[122:123], v[134:135]
	v_pk_fma_f32 v[134:135], v[124:125], v[124:125], v[134:135]
	v_pk_fma_f32 v[134:135], v[126:127], v[126:127], v[134:135]
	s_nop 0
	v_add_f32_e32 v134, v134, v135
	global_load_dword v88, v172, s[98:99]
	global_load_dwordx2 v[56:57], v170, s[98:99]
	global_load_dwordx2 v[58:59], v170, s[98:99] offset:512
	global_load_dwordx2 v[60:61], v170, s[98:99] offset:1024
	global_load_dwordx2 v[62:63], v170, s[98:99] offset:1536
	global_load_dwordx2 v[72:73], v171, s[98:99]
	global_load_dwordx2 v[74:75], v171, s[98:99] offset:512
	global_load_dwordx2 v[76:77], v171, s[98:99] offset:1024
	global_load_dwordx2 v[78:79], v171, s[98:99] offset:1536
	v_add_u32_e32 v170, 0x400000, v170
	v_add_u32_e32 v171, 0x400000, v171
	v_add_u32_e32 v172, 0x2000, v172
	global_load_dword v90, v172, s[98:99]
	global_load_dwordx2 v[64:65], v170, s[98:99]
	global_load_dwordx2 v[66:67], v170, s[98:99] offset:512
	global_load_dwordx2 v[68:69], v170, s[98:99] offset:1024
	global_load_dwordx2 v[70:71], v170, s[98:99] offset:1536
	global_load_dwordx2 v[80:81], v171, s[98:99]
	global_load_dwordx2 v[82:83], v171, s[98:99] offset:512
	global_load_dwordx2 v[84:85], v171, s[98:99] offset:1024
	global_load_dwordx2 v[86:87], v171, s[98:99] offset:1536
	v_add_u32_e32 v170, 0x400000, v170
	v_add_u32_e32 v171, 0x400000, v171
	v_add_u32_e32 v172, 0x2000, v172
	s_nop 1
	v_add_f32_dpp v132, v132, v132 quad_perm:[1,0,3,2] row_mask:0xf bank_mask:0xf
	v_add_f32_dpp v134, v134, v134 quad_perm:[1,0,3,2] row_mask:0xf bank_mask:0xf
	s_nop 0
	v_add_f32_dpp v132, v132, v132 quad_perm:[2,3,0,1] row_mask:0xf bank_mask:0xf
	v_add_f32_dpp v134, v134, v134 quad_perm:[2,3,0,1] row_mask:0xf bank_mask:0xf
	s_nop 0
	v_add_f32_dpp v132, v132, v132 row_half_mirror row_mask:0xf bank_mask:0xf
	v_add_f32_dpp v134, v134, v134 row_half_mirror row_mask:0xf bank_mask:0xf
	s_nop 0
	v_add_f32_dpp v132, v132, v132 row_mirror row_mask:0xf bank_mask:0xf
	v_add_f32_dpp v134, v134, v134 row_mirror row_mask:0xf bank_mask:0xf
	s_nop 0
	ds_bpermute_b32 v136, v187, v132
	ds_bpermute_b32 v137, v187, v134
	s_waitcnt lgkmcnt(0)
	v_add_f32_e32 v132, v132, v136
	v_add_f32_e32 v134, v134, v137
	ds_bpermute_b32 v136, v188, v132
	ds_bpermute_b32 v137, v188, v134
	s_waitcnt lgkmcnt(0)
;     __device__ __forceinline__ float* out() const { return (float*)karg_in(33); }
; __device__ __forceinline__ void st4_bf16(bf16* p, v4f o) { v2u w; w.x = cvt_pk_nv(o.x, o.y); w.y = cvt_pk_nv(o.z, o.w); *(v2u*)p = w; }
; __device__ __forceinline__ float ssq4(v4f v) { return (v.x * v.x + v.y * v.y) + (v.z * v.z + v.w * v.w); }
; template <int R, bool BASE_F32, bool OUT_F32>
; __device__ __forceinline__ void rows_res(const Ctx& C, int m0, int stride, int mx, const float* gpost, float scale, int lane) {
;     ...
;     for (int r = 0; r < R; ++r) { float s = 0.f;
; #pragma unroll
;         for (int j = 0; j < 4; ++j) s += ssq4(d[r][j]);
;         r1[r] = s; }
; #pragma unroll
;     for (int r = 0; r < R; ++r) r1[r] = rsqrtf(wave_sum(r1[r]) * (1.f / DM) + EPS) * scale;
; #pragma unroll
;     for (int j = 0; j < 4; ++j) { const v4f gp = ld4_f32(gpost + 4 * lane + 256 * j);
; #pragma unroll
;         for (int r = 0; r < R; ++r) d[r][j] = b[r][j] + d[r][j] * r1[r] * gp; }
;     if (OUT_F32) { float* Y = C.out();
; #pragma unroll
;         for (int r = 0; r < R; ++r)
; #pragma unroll
;             for (int j = 0; j < 4; ++j) if (ok[r]) *(v4f*)(Y + (size_t)mr[r] * DM + 4 * lane + 256 * j) = d[r][j];
;     } else { float* rs = C.RS(); float t[R];
; #pragma unroll
;         for (int r = 0; r < R; ++r) { float s = 0.f;
; #pragma unroll
;             for (int j = 0; j < 4; ++j) s += ssq4(d[r][j]);
;             t[r] = s; }
; #pragma unroll
;         for (int r = 0; r < R; ++r) t[r] = wave_sum(t[r]) * (1.f / DM) + EPS;
; #pragma unroll
;         for (int r = 0; r < R; ++r) { const float rstd = rsqrtf(t[r]);
; #pragma unroll
;             for (int j = 0; j < 4; ++j) if (ok[r]) st4_bf16(XN + (size_t)mr[r] * DM + 4 * lane + 256 * j, d[r][j] * rstd);
;             if (lane == 0 && ok[r]) rs[mr[r]] = sqrtf(t[r]); }
	v_add_f32_e32 v132, v132, v136
	v_add_f32_e32 v134, v134, v137
	v_fmamk_f32 v164, v132, 0x3a800000, v138
	v_fmamk_f32 v167, v134, 0x3a800000, v138
	s_nop 0
	v_rsq_f32_e32 v132, v164
	v_rsq_f32_e32 v134, v167
	v_sqrt_f32_e32 v165, v164
	v_sqrt_f32_e32 v168, v167
	s_nop 1
	v_pk_mul_f32 v[140:141], v[96:97], v[132:133] op_sel_hi:[1,0]
	v_cvt_pk_bf16_f32 v148, v140, v141
	v_pk_mul_f32 v[142:143], v[98:99], v[132:133] op_sel_hi:[1,0]
	v_cvt_pk_bf16_f32 v149, v142, v143
	v_pk_mul_f32 v[144:145], v[100:101], v[132:133] op_sel_hi:[1,0]
	v_cvt_pk_bf16_f32 v150, v144, v145
	v_pk_mul_f32 v[146:147], v[102:103], v[132:133] op_sel_hi:[1,0]
	v_cvt_pk_bf16_f32 v151, v146, v147
	v_pk_mul_f32 v[140:141], v[104:105], v[132:133] op_sel_hi:[1,0]
	v_cvt_pk_bf16_f32 v152, v140, v141
	v_pk_mul_f32 v[142:143], v[106:107], v[132:133] op_sel_hi:[1,0]
	v_cvt_pk_bf16_f32 v153, v142, v143
	v_pk_mul_f32 v[144:145], v[108:109], v[132:133] op_sel_hi:[1,0]
	v_cvt_pk_bf16_f32 v154, v144, v145
	v_pk_mul_f32 v[146:147], v[110:111], v[132:133] op_sel_hi:[1,0]
	v_cvt_pk_bf16_f32 v155, v146, v147
	global_store_dwordx2 v173, v[148:149], s[98:99]
	global_store_dwordx2 v173, v[150:151], s[98:99] offset:512
	global_store_dwordx2 v173, v[152:153], s[98:99] offset:1024
	global_store_dwordx2 v173, v[154:155], s[98:99] offset:1536
	v_add_u32_e32 v173, 0x400000, v173
	v_pk_mul_f32 v[140:141], v[112:113], v[134:135] op_sel_hi:[1,0]
	v_cvt_pk_bf16_f32 v156, v140, v141
	v_pk_mul_f32 v[142:143], v[114:115], v[134:135] op_sel_hi:[1,0]
	v_cvt_pk_bf16_f32 v157, v142, v143
	v_pk_mul_f32 v[144:145], v[116:117], v[134:135] op_sel_hi:[1,0]
	v_cvt_pk_bf16_f32 v158, v144, v145
	v_pk_mul_f32 v[146:147], v[118:119], v[134:135] op_sel_hi:[1,0]
	v_cvt_pk_bf16_f32 v159, v146, v147
	v_pk_mul_f32 v[140:141], v[120:121], v[134:135] op_sel_hi:[1,0]
	v_cvt_pk_bf16_f32 v160, v140, v141
	v_pk_mul_f32 v[142:143], v[122:123], v[134:135] op_sel_hi:[1,0]
	v_cvt_pk_bf16_f32 v161, v142, v143
	v_pk_mul_f32 v[144:145], v[124:125], v[134:135] op_sel_hi:[1,0]
	v_cvt_pk_bf16_f32 v162, v144, v145
	v_pk_mul_f32 v[146:147], v[126:127], v[134:135] op_sel_hi:[1,0]
	v_cvt_pk_bf16_f32 v163, v146, v147
	global_store_dwordx2 v173, v[156:157], s[98:99]
	global_store_dwordx2 v173, v[158:159], s[98:99] offset:512
	global_store_dwordx2 v173, v[160:161], s[98:99] offset:1024
	global_store_dwordx2 v173, v[162:163], s[98:99] offset:1536
	v_add_u32_e32 v173, 0x400000, v173
	v_add_u32_e32 v166, -1, v165
	v_fma_f32 v140, -v166, v165, v164
	v_cmp_ge_f32_e32 vcc, 0, v140
	v_add_u32_e32 v141, 1, v165
	v_cndmask_b32_e32 v166, v165, v166, vcc
	v_fma_f32 v140, -v141, v165, v164
	v_cmp_lt_f32_e32 vcc, 0, v140
	s_nop 1
	v_cndmask_b32_e32 v165, v166, v141, vcc
	v_add_u32_e32 v169, -1, v168
	v_fma_f32 v142, -v169, v168, v167
	v_cmp_ge_f32_e32 vcc, 0, v142
	v_add_u32_e32 v143, 1, v168
	v_cndmask_b32_e32 v169, v168, v169, vcc
	v_fma_f32 v142, -v143, v168, v167
	v_cmp_lt_f32_e32 vcc, 0, v142
	s_nop 1
	v_cndmask_b32_e32 v168, v169, v143, vcc
	s_mov_b64 exec, 1
	global_store_dword v174, v165, s[98:99]
	v_add_u32_e32 v174, 0x2000, v174
	global_store_dword v174, v168, s[98:99]
	v_add_u32_e32 v174, 0x2000, v174
	s_mov_b64 exec, -1
	s_waitcnt vmcnt(51)
	v_lshlrev_b32_e32 v96, 16, v20
	v_and_b32_e32 v97, 0xffff0000, v20
	v_lshlrev_b32_e32 v98, 16, v21
	v_and_b32_e32 v99, 0xffff0000, v21
	v_lshlrev_b32_e32 v100, 16, v22
	v_and_b32_e32 v101, 0xffff0000, v22
	v_lshlrev_b32_e32 v102, 16, v23
	v_and_b32_e32 v103, 0xffff0000, v23
	v_lshlrev_b32_e32 v104, 16, v24
	v_and_b32_e32 v105, 0xffff0000, v24
	v_lshlrev_b32_e32 v106, 16, v25
	v_and_b32_e32 v107, 0xffff0000, v25
	v_lshlrev_b32_e32 v108, 16, v26
	v_and_b32_e32 v109, 0xffff0000, v26
	v_lshlrev_b32_e32 v110, 16, v27
	v_and_b32_e32 v111, 0xffff0000, v27
	v_pk_mul_f32 v[128:129], v[96:97], v[96:97]
	v_pk_fma_f32 v[128:129], v[98:99], v[98:99], v[128:129]
	v_pk_fma_f32 v[128:129], v[100:101], v[100:101], v[128:129]
	v_pk_fma_f32 v[128:129], v[102:103], v[102:103], v[128:129]
	v_pk_fma_f32 v[128:129], v[104:105], v[104:105], v[128:129]
	v_pk_fma_f32 v[128:129], v[106:107], v[106:107], v[128:129]
	v_pk_fma_f32 v[128:129], v[108:109], v[108:109], v[128:129]
	v_pk_fma_f32 v[128:129], v[110:111], v[110:111], v[128:129]
	s_nop 0
	v_add_f32_e32 v128, v128, v129
	s_waitcnt vmcnt(42)
	v_lshlrev_b32_e32 v112, 16, v28
	v_and_b32_e32 v113, 0xffff0000, v28
	v_lshlrev_b32_e32 v114, 16, v29
	v_and_b32_e32 v115, 0xffff0000, v29
	v_lshlrev_b32_e32 v116, 16, v30
	v_and_b32_e32 v117, 0xffff0000, v30
	v_lshlrev_b32_e32 v118, 16, v31
	v_and_b32_e32 v119, 0xffff0000, v31
	v_lshlrev_b32_e32 v120, 16, v32
	v_and_b32_e32 v121, 0xffff0000, v32
	v_lshlrev_b32_e32 v122, 16, v33
	v_and_b32_e32 v123, 0xffff0000, v33
	v_lshlrev_b32_e32 v124, 16, v34
	v_and_b32_e32 v125, 0xffff0000, v34
	v_lshlrev_b32_e32 v126, 16, v35
	v_and_b32_e32 v127, 0xffff0000, v35
	v_pk_mul_f32 v[130:131], v[112:113], v[112:113]
	v_pk_fma_f32 v[130:131], v[114:115], v[114:115], v[130:131]
	v_pk_fma_f32 v[130:131], v[116:117], v[116:117], v[130:131]
	v_pk_fma_f32 v[130:131], v[118:119], v[118:119], v[130:131]
	v_pk_fma_f32 v[130:131], v[120:121], v[120:121], v[130:131]
	v_pk_fma_f32 v[130:131], v[122:123], v[122:123], v[130:131]
	v_pk_fma_f32 v[130:131], v[124:125], v[124:125], v[130:131]
	v_pk_fma_f32 v[130:131], v[126:127], v[126:127], v[130:131]
	s_nop 0
	v_add_f32_e32 v130, v130, v131
	s_nop 1
	v_add_f32_dpp v128, v128, v128 quad_perm:[1,0,3,2] row_mask:0xf bank_mask:0xf
	v_add_f32_dpp v130, v130, v130 quad_perm:[1,0,3,2] row_mask:0xf bank_mask:0xf
	s_nop 0
	v_add_f32_dpp v128, v128, v128 quad_perm:[2,3,0,1] row_mask:0xf bank_mask:0xf
	v_add_f32_dpp v130, v130, v130 quad_perm:[2,3,0,1] row_mask:0xf bank_mask:0xf
	s_nop 0
	v_add_f32_dpp v128, v128, v128 row_half_mirror row_mask:0xf bank_mask:0xf
	v_add_f32_dpp v130, v130, v130 row_half_mirror row_mask:0xf bank_mask:0xf
	s_nop 0
	v_add_f32_dpp v128, v128, v128 row_mirror row_mask:0xf bank_mask:0xf
	v_add_f32_dpp v130, v130, v130 row_mirror row_mask:0xf bank_mask:0xf
	s_nop 0
	ds_bpermute_b32 v136, v187, v128
	ds_bpermute_b32 v137, v187, v130
	s_waitcnt lgkmcnt(0)
;     __device__ __forceinline__ float* out() const { return (float*)karg_in(33); }
; __device__ __forceinline__ const float* xrow_ptr(const Ctx& C, int row) { return row < MPROMPT ? C.in(0) + (size_t)row * DM : C.in(1) + (size_t)(row - MPROMPT) * DM; }
; __device__ __forceinline__ v4f ld4_bf16(const bf16* p) { const v2u w = *(const v2u*)p; return (v4f){bf_lo(w.x), bf_hi(w.x), bf_lo(w.y), bf_hi(w.y)}; }
; __device__ __forceinline__ float ssq4(v4f v) { return (v.x * v.x + v.y * v.y) + (v.z * v.z + v.w * v.w); }
; template <int R, bool BASE_F32, bool OUT_F32>
; __device__ __forceinline__ void rows_res(const Ctx& C, int m0, int stride, int mx, const float* gpost, float scale, int lane) {
;     ...
;     for (int r = 0; r < R; ++r) { mr[r] = (r == 4) ? mx : m0 + r * stride; ok[r] = (r == 4) ? (mx < M) : (mr[r] < MPROMPT); const int mm = ok[r] ? mr[r] : 0;
; #pragma unroll
;         for (int j = 0; j < 4; ++j) d[r][j] = ld4_bf16(D + (size_t)mm * DM + 4 * lane + 256 * j);
;         if (BASE_F32) { const float* x = xrow_ptr(C, mm);
; #pragma unroll
;             for (int j = 0; j < 4; ++j) b[r][j] = ld4_f32(x + 4 * lane + 256 * j);
;         } else { const float inv = C.RS()[mm];
; #pragma unroll
;             for (int j = 0; j < 4; ++j) b[r][j] = ld4_bf16(XN + (size_t)mm * DM + 4 * lane + 256 * j) * inv;
;         } }
; #pragma unroll
;     for (int r = 0; r < R; ++r) { float s = 0.f;
; #pragma unroll
;         for (int j = 0; j < 4; ++j) s += ssq4(d[r][j]);
;         r1[r] = s; }
; #pragma unroll
;     for (int r = 0; r < R; ++r) r1[r] = rsqrtf(wave_sum(r1[r]) * (1.f / DM) + EPS) * scale;
; #pragma unroll
;     for (int j = 0; j < 4; ++j) { const v4f gp = ld4_f32(gpost + 4 * lane + 256 * j);
; #pragma unroll
;         for (int r = 0; r < R; ++r) d[r][j] = b[r][j] + d[r][j] * r1[r] * gp; }
;     if (OUT_F32) { float* Y = C.out();
; #pragma unroll
;         for (int r = 0; r < R; ++r)
; #pragma unroll
;             for (int j = 0; j < 4; ++j) if (ok[r]) *(v4f*)(Y + (size_t)mr[r] * DM + 4 * lane + 256 * j) = d[r][j];
;     } else { float* rs = C.RS(); float t[R];
; #pragma unroll
;         for (int r = 0; r < R; ++r) { float s = 0.f;
; #pragma unroll
;             for (int j = 0; j < 4; ++j) s += ssq4(d[r][j]);
;             t[r] = s; }
; #pragma unroll
;         for (int r = 0; r < R; ++r) t[r] = wave_sum(t[r]) * (1.f / DM) + EPS;
	v_add_f32_e32 v128, v128, v136
	v_add_f32_e32 v130, v130, v137
	ds_bpermute_b32 v136, v188, v128
	ds_bpermute_b32 v137, v188, v130
	s_waitcnt lgkmcnt(0)
	v_add_f32_e32 v128, v128, v136
	v_add_f32_e32 v130, v130, v137
	v_fmamk_f32 v128, v128, 0x3a800000, v138
	v_fmamk_f32 v130, v130, 0x3a800000, v138
	s_nop 0
	v_rsq_f32_e32 v128, v128
	v_rsq_f32_e32 v130, v130
	s_nop 1
	v_mul_f32_e32 v128, 0.5, v128
	v_mul_f32_e32 v130, 0.5, v130
	s_waitcnt vmcnt(38)
	v_pk_mul_f32 v[96:97], v[128:129], v[96:97] op_sel_hi:[0,1]
	v_pk_mul_f32 v[98:99], v[128:129], v[98:99] op_sel_hi:[0,1]
	v_pk_mul_f32 v[100:101], v[128:129], v[100:101] op_sel_hi:[0,1]
	v_pk_mul_f32 v[102:103], v[128:129], v[102:103] op_sel_hi:[0,1]
	v_pk_mul_f32 v[104:105], v[128:129], v[104:105] op_sel_hi:[0,1]
	v_pk_mul_f32 v[106:107], v[128:129], v[106:107] op_sel_hi:[0,1]
	v_pk_mul_f32 v[108:109], v[128:129], v[108:109] op_sel_hi:[0,1]
	v_pk_mul_f32 v[110:111], v[128:129], v[110:111] op_sel_hi:[0,1]
	v_pk_mul_f32 v[96:97], v[96:97], v[192:193]
	v_pk_mul_f32 v[98:99], v[98:99], v[194:195]
	v_pk_mul_f32 v[100:101], v[100:101], v[196:197]
	v_pk_mul_f32 v[102:103], v[102:103], v[198:199]
	v_pk_mul_f32 v[104:105], v[104:105], v[200:201]
	v_pk_mul_f32 v[106:107], v[106:107], v[202:203]
	v_pk_mul_f32 v[108:109], v[108:109], v[204:205]
	v_pk_mul_f32 v[110:111], v[110:111], v[206:207]
	v_lshlrev_b32_e32 v20, 16, v36
	v_and_b32_e32 v21, 0xffff0000, v36
	v_lshlrev_b32_e32 v22, 16, v37
	v_and_b32_e32 v23, 0xffff0000, v37
	v_lshlrev_b32_e32 v24, 16, v38
	v_and_b32_e32 v25, 0xffff0000, v38
	v_lshlrev_b32_e32 v26, 16, v39
	v_and_b32_e32 v27, 0xffff0000, v39
	v_pk_fma_f32 v[96:97], v[52:53], v[20:21], v[96:97] op_sel_hi:[0,1,1]
	v_pk_fma_f32 v[98:99], v[52:53], v[22:23], v[98:99] op_sel_hi:[0,1,1]
	v_pk_fma_f32 v[100:101], v[52:53], v[24:25], v[100:101] op_sel_hi:[0,1,1]
	v_pk_fma_f32 v[102:103], v[52:53], v[26:27], v[102:103] op_sel_hi:[0,1,1]
	v_lshlrev_b32_e32 v20, 16, v40
	v_and_b32_e32 v21, 0xffff0000, v40
	v_lshlrev_b32_e32 v22, 16, v41
	v_and_b32_e32 v23, 0xffff0000, v41
	v_lshlrev_b32_e32 v24, 16, v42
	v_and_b32_e32 v25, 0xffff0000, v42
	v_lshlrev_b32_e32 v26, 16, v43
	v_and_b32_e32 v27, 0xffff0000, v43
	v_pk_fma_f32 v[104:105], v[52:53], v[20:21], v[104:105] op_sel_hi:[0,1,1]
	v_pk_fma_f32 v[106:107], v[52:53], v[22:23], v[106:107] op_sel_hi:[0,1,1]
	v_pk_fma_f32 v[108:109], v[52:53], v[24:25], v[108:109] op_sel_hi:[0,1,1]
	v_pk_fma_f32 v[110:111], v[52:53], v[26:27], v[110:111] op_sel_hi:[0,1,1]
	v_pk_mul_f32 v[132:133], v[96:97], v[96:97]
	v_pk_fma_f32 v[132:133], v[98:99], v[98:99], v[132:133]
	v_pk_fma_f32 v[132:133], v[100:101], v[100:101], v[132:133]
	v_pk_fma_f32 v[132:133], v[102:103], v[102:103], v[132:133]
	v_pk_fma_f32 v[132:133], v[104:105], v[104:105], v[132:133]
	v_pk_fma_f32 v[132:133], v[106:107], v[106:107], v[132:133]
	v_pk_fma_f32 v[132:133], v[108:109], v[108:109], v[132:133]
	v_pk_fma_f32 v[132:133], v[110:111], v[110:111], v[132:133]
	s_nop 0
	v_add_f32_e32 v132, v132, v133
	v_pk_mul_f32 v[112:113], v[130:131], v[112:113] op_sel_hi:[0,1]
	v_pk_mul_f32 v[114:115], v[130:131], v[114:115] op_sel_hi:[0,1]
	v_pk_mul_f32 v[116:117], v[130:131], v[116:117] op_sel_hi:[0,1]
	v_pk_mul_f32 v[118:119], v[130:131], v[118:119] op_sel_hi:[0,1]
	v_pk_mul_f32 v[120:121], v[130:131], v[120:121] op_sel_hi:[0,1]
	v_pk_mul_f32 v[122:123], v[130:131], v[122:123] op_sel_hi:[0,1]
	v_pk_mul_f32 v[124:125], v[130:131], v[124:125] op_sel_hi:[0,1]
	v_pk_mul_f32 v[126:127], v[130:131], v[126:127] op_sel_hi:[0,1]
	v_pk_mul_f32 v[112:113], v[112:113], v[192:193]
	v_pk_mul_f32 v[114:115], v[114:115], v[194:195]
	v_pk_mul_f32 v[116:117], v[116:117], v[196:197]
	v_pk_mul_f32 v[118:119], v[118:119], v[198:199]
	v_pk_mul_f32 v[120:121], v[120:121], v[200:201]
	v_pk_mul_f32 v[122:123], v[122:123], v[202:203]
	v_pk_mul_f32 v[124:125], v[124:125], v[204:205]
	v_pk_mul_f32 v[126:127], v[126:127], v[206:207]
	v_lshlrev_b32_e32 v28, 16, v44
	v_and_b32_e32 v29, 0xffff0000, v44
	v_lshlrev_b32_e32 v30, 16, v45
	v_and_b32_e32 v31, 0xffff0000, v45
	v_lshlrev_b32_e32 v32, 16, v46
	v_and_b32_e32 v33, 0xffff0000, v46
	v_lshlrev_b32_e32 v34, 16, v47
	v_and_b32_e32 v35, 0xffff0000, v47
	v_pk_fma_f32 v[112:113], v[54:55], v[28:29], v[112:113] op_sel_hi:[0,1,1]
	v_pk_fma_f32 v[114:115], v[54:55], v[30:31], v[114:115] op_sel_hi:[0,1,1]
	v_pk_fma_f32 v[116:117], v[54:55], v[32:33], v[116:117] op_sel_hi:[0,1,1]
	v_pk_fma_f32 v[118:119], v[54:55], v[34:35], v[118:119] op_sel_hi:[0,1,1]
	v_lshlrev_b32_e32 v28, 16, v48
	v_and_b32_e32 v29, 0xffff0000, v48
	v_lshlrev_b32_e32 v30, 16, v49
	v_and_b32_e32 v31, 0xffff0000, v49
	v_lshlrev_b32_e32 v32, 16, v50
	v_and_b32_e32 v33, 0xffff0000, v50
	v_lshlrev_b32_e32 v34, 16, v51
	v_and_b32_e32 v35, 0xffff0000, v51
	v_pk_fma_f32 v[120:121], v[54:55], v[28:29], v[120:121] op_sel_hi:[0,1,1]
	v_pk_fma_f32 v[122:123], v[54:55], v[30:31], v[122:123] op_sel_hi:[0,1,1]
	v_pk_fma_f32 v[124:125], v[54:55], v[32:33], v[124:125] op_sel_hi:[0,1,1]
	v_pk_fma_f32 v[126:127], v[54:55], v[34:35], v[126:127] op_sel_hi:[0,1,1]
	v_pk_mul_f32 v[134:135], v[112:113], v[112:113]
	v_pk_fma_f32 v[134:135], v[114:115], v[114:115], v[134:135]
	v_pk_fma_f32 v[134:135], v[116:117], v[116:117], v[134:135]
	v_pk_fma_f32 v[134:135], v[118:119], v[118:119], v[134:135]
	v_pk_fma_f32 v[134:135], v[120:121], v[120:121], v[134:135]
	v_pk_fma_f32 v[134:135], v[122:123], v[122:123], v[134:135]
	v_pk_fma_f32 v[134:135], v[124:125], v[124:125], v[134:135]
	v_pk_fma_f32 v[134:135], v[126:127], v[126:127], v[134:135]
	s_nop 0
	v_add_f32_e32 v134, v134, v135
	global_load_dword v52, v172, s[98:99]
	global_load_dwordx2 v[20:21], v170, s[98:99]
;     __device__ __forceinline__ float* out() const { return (float*)karg_in(33); }
; __device__ __forceinline__ const float* xrow_ptr(const Ctx& C, int row) { return row < MPROMPT ? C.in(0) + (size_t)row * DM : C.in(1) + (size_t)(row - MPROMPT) * DM; }
; template <int R, bool BASE_F32, bool OUT_F32>
; __device__ __forceinline__ void rows_res(const Ctx& C, int m0, int stride, int mx, const float* gpost, float scale, int lane) {
;     ...
;     for (int r = 0; r < R; ++r) { mr[r] = (r == 4) ? mx : m0 + r * stride; ok[r] = (r == 4) ? (mx < M) : (mr[r] < MPROMPT); const int mm = ok[r] ? mr[r] : 0;
; #pragma unroll
;         for (int j = 0; j < 4; ++j) d[r][j] = ld4_bf16(D + (size_t)mm * DM + 4 * lane + 256 * j);
;         if (BASE_F32) { const float* x = xrow_ptr(C, mm);
; #pragma unroll
;             for (int j = 0; j < 4; ++j) b[r][j] = ld4_f32(x + 4 * lane + 256 * j);
;         } else { const float inv = C.RS()[mm];
; #pragma unroll
;             for (int j = 0; j < 4; ++j) b[r][j] = ld4_bf16(XN + (size_t)mm * DM + 4 * lane + 256 * j) * inv;
;         } }
; #pragma unroll
;     for (int r = 0; r < R; ++r) { float s = 0.f;
; #pragma unroll
;         for (int j = 0; j < 4; ++j) s += ssq4(d[r][j]);
;         r1[r] = s; }
; #pragma unroll
;     for (int r = 0; r < R; ++r) r1[r] = rsqrtf(wave_sum(r1[r]) * (1.f / DM) + EPS) * scale;
; #pragma unroll
;     for (int j = 0; j < 4; ++j) { const v4f gp = ld4_f32(gpost + 4 * lane + 256 * j);
; #pragma unroll
;         for (int r = 0; r < R; ++r) d[r][j] = b[r][j] + d[r][j] * r1[r] * gp; }
;     if (OUT_F32) { float* Y = C.out();
; #pragma unroll
;         for (int r = 0; r < R; ++r)
; #pragma unroll
;             for (int j = 0; j < 4; ++j) if (ok[r]) *(v4f*)(Y + (size_t)mr[r] * DM + 4 * lane + 256 * j) = d[r][j];
;     } else { float* rs = C.RS(); float t[R];
; #pragma unroll
;         for (int r = 0; r < R; ++r) { float s = 0.f;
; #pragma unroll
;             for (int j = 0; j < 4; ++j) s += ssq4(d[r][j]);
;             t[r] = s; }
; #pragma unroll
;         for (int r = 0; r < R; ++r) t[r] = wave_sum(t[r]) * (1.f / DM) + EPS;
; #pragma unroll
;         for (int r = 0; r < R; ++r) { const float rstd = rsqrtf(t[r]);
; #pragma unroll
;             for (int j = 0; j < 4; ++j) if (ok[r]) st4_bf16(XN + (size_t)mr[r] * DM + 4 * lane + 256 * j, d[r][j] * rstd);
;             if (lane == 0 && ok[r]) rs[mr[r]] = sqrtf(t[r]); }
	global_load_dwordx2 v[22:23], v170, s[98:99] offset:512
	global_load_dwordx2 v[24:25], v170, s[98:99] offset:1024
	global_load_dwordx2 v[26:27], v170, s[98:99] offset:1536
	global_load_dwordx2 v[36:37], v171, s[98:99]
	global_load_dwordx2 v[38:39], v171, s[98:99] offset:512
	global_load_dwordx2 v[40:41], v171, s[98:99] offset:1024
	global_load_dwordx2 v[42:43], v171, s[98:99] offset:1536
	v_add_u32_e32 v170, 0x400000, v170
	v_add_u32_e32 v171, 0x400000, v171
	v_add_u32_e32 v172, 0x2000, v172
	global_load_dword v54, v172, s[98:99]
	global_load_dwordx2 v[28:29], v170, s[98:99]
	global_load_dwordx2 v[30:31], v170, s[98:99] offset:512
	global_load_dwordx2 v[32:33], v170, s[98:99] offset:1024
	global_load_dwordx2 v[34:35], v170, s[98:99] offset:1536
	global_load_dwordx2 v[44:45], v171, s[98:99]
	global_load_dwordx2 v[46:47], v171, s[98:99] offset:512
	global_load_dwordx2 v[48:49], v171, s[98:99] offset:1024
	global_load_dwordx2 v[50:51], v171, s[98:99] offset:1536
	v_add_u32_e32 v170, 0x400000, v170
	v_add_u32_e32 v171, 0x400000, v171
	v_add_u32_e32 v172, 0x2000, v172
	s_nop 1
	v_add_f32_dpp v132, v132, v132 quad_perm:[1,0,3,2] row_mask:0xf bank_mask:0xf
	v_add_f32_dpp v134, v134, v134 quad_perm:[1,0,3,2] row_mask:0xf bank_mask:0xf
	s_nop 0
	v_add_f32_dpp v132, v132, v132 quad_perm:[2,3,0,1] row_mask:0xf bank_mask:0xf
	v_add_f32_dpp v134, v134, v134 quad_perm:[2,3,0,1] row_mask:0xf bank_mask:0xf
	s_nop 0
	v_add_f32_dpp v132, v132, v132 row_half_mirror row_mask:0xf bank_mask:0xf
	v_add_f32_dpp v134, v134, v134 row_half_mirror row_mask:0xf bank_mask:0xf
	s_nop 0
	v_add_f32_dpp v132, v132, v132 row_mirror row_mask:0xf bank_mask:0xf
	v_add_f32_dpp v134, v134, v134 row_mirror row_mask:0xf bank_mask:0xf
	s_nop 0
	ds_bpermute_b32 v136, v187, v132
	ds_bpermute_b32 v137, v187, v134
	s_waitcnt lgkmcnt(0)
	v_add_f32_e32 v132, v132, v136
	v_add_f32_e32 v134, v134, v137
	ds_bpermute_b32 v136, v188, v132
	ds_bpermute_b32 v137, v188, v134
	s_waitcnt lgkmcnt(0)
	v_add_f32_e32 v132, v132, v136
	v_add_f32_e32 v134, v134, v137
	v_fmamk_f32 v164, v132, 0x3a800000, v138
	v_fmamk_f32 v167, v134, 0x3a800000, v138
	s_nop 0
	v_rsq_f32_e32 v132, v164
	v_rsq_f32_e32 v134, v167
	v_sqrt_f32_e32 v165, v164
	v_sqrt_f32_e32 v168, v167
	s_nop 1
	v_pk_mul_f32 v[140:141], v[96:97], v[132:133] op_sel_hi:[1,0]
	v_cvt_pk_bf16_f32 v148, v140, v141
	v_pk_mul_f32 v[142:143], v[98:99], v[132:133] op_sel_hi:[1,0]
	v_cvt_pk_bf16_f32 v149, v142, v143
	v_pk_mul_f32 v[144:145], v[100:101], v[132:133] op_sel_hi:[1,0]
	v_cvt_pk_bf16_f32 v150, v144, v145
	v_pk_mul_f32 v[146:147], v[102:103], v[132:133] op_sel_hi:[1,0]
	v_cvt_pk_bf16_f32 v151, v146, v147
	v_pk_mul_f32 v[140:141], v[104:105], v[132:133] op_sel_hi:[1,0]
	v_cvt_pk_bf16_f32 v152, v140, v141
	v_pk_mul_f32 v[142:143], v[106:107], v[132:133] op_sel_hi:[1,0]
	v_cvt_pk_bf16_f32 v153, v142, v143
	v_pk_mul_f32 v[144:145], v[108:109], v[132:133] op_sel_hi:[1,0]
	v_cvt_pk_bf16_f32 v154, v144, v145
	v_pk_mul_f32 v[146:147], v[110:111], v[132:133] op_sel_hi:[1,0]
	v_cvt_pk_bf16_f32 v155, v146, v147
	global_store_dwordx2 v173, v[148:149], s[98:99]
	global_store_dwordx2 v173, v[150:151], s[98:99] offset:512
	global_store_dwordx2 v173, v[152:153], s[98:99] offset:1024
	global_store_dwordx2 v173, v[154:155], s[98:99] offset:1536
	v_add_u32_e32 v173, 0x400000, v173
	v_pk_mul_f32 v[140:141], v[112:113], v[134:135] op_sel_hi:[1,0]
	v_cvt_pk_bf16_f32 v156, v140, v141
	v_pk_mul_f32 v[142:143], v[114:115], v[134:135] op_sel_hi:[1,0]
	v_cvt_pk_bf16_f32 v157, v142, v143
	v_pk_mul_f32 v[144:145], v[116:117], v[134:135] op_sel_hi:[1,0]
	v_cvt_pk_bf16_f32 v158, v144, v145
	v_pk_mul_f32 v[146:147], v[118:119], v[134:135] op_sel_hi:[1,0]
	v_cvt_pk_bf16_f32 v159, v146, v147
	v_pk_mul_f32 v[140:141], v[120:121], v[134:135] op_sel_hi:[1,0]
	v_cvt_pk_bf16_f32 v160, v140, v141
	v_pk_mul_f32 v[142:143], v[122:123], v[134:135] op_sel_hi:[1,0]
	v_cvt_pk_bf16_f32 v161, v142, v143
	v_pk_mul_f32 v[144:145], v[124:125], v[134:135] op_sel_hi:[1,0]
	v_cvt_pk_bf16_f32 v162, v144, v145
	v_pk_mul_f32 v[146:147], v[126:127], v[134:135] op_sel_hi:[1,0]
	v_cvt_pk_bf16_f32 v163, v146, v147
	global_store_dwordx2 v173, v[156:157], s[98:99]
	global_store_dwordx2 v173, v[158:159], s[98:99] offset:512
	global_store_dwordx2 v173, v[160:161], s[98:99] offset:1024
	global_store_dwordx2 v173, v[162:163], s[98:99] offset:1536
	v_add_u32_e32 v173, 0x400000, v173
	v_add_u32_e32 v166, -1, v165
	v_fma_f32 v140, -v166, v165, v164
	v_cmp_ge_f32_e32 vcc, 0, v140
	v_add_u32_e32 v141, 1, v165
	v_cndmask_b32_e32 v166, v165, v166, vcc
	v_fma_f32 v140, -v141, v165, v164
	v_cmp_lt_f32_e32 vcc, 0, v140
	s_nop 1
	v_cndmask_b32_e32 v165, v166, v141, vcc
	v_add_u32_e32 v169, -1, v168
	v_fma_f32 v142, -v169, v168, v167
	v_cmp_ge_f32_e32 vcc, 0, v142
	v_add_u32_e32 v143, 1, v168
	v_cndmask_b32_e32 v169, v168, v169, vcc
	v_fma_f32 v142, -v143, v168, v167
	v_cmp_lt_f32_e32 vcc, 0, v142
	s_nop 1
	v_cndmask_b32_e32 v168, v169, v143, vcc
	s_mov_b64 exec, 1
	global_store_dword v174, v165, s[98:99]
	v_add_u32_e32 v174, 0x2000, v174
	global_store_dword v174, v168, s[98:99]
	v_add_u32_e32 v174, 0x2000, v174
	s_mov_b64 exec, -1
	s_waitcnt vmcnt(51)
;     __device__ __forceinline__ float* out() const { return (float*)karg_in(33); }
; __device__ __forceinline__ float ssq4(v4f v) { return (v.x * v.x + v.y * v.y) + (v.z * v.z + v.w * v.w); }
; template <int R, bool BASE_F32, bool OUT_F32>
; __device__ __forceinline__ void rows_res(const Ctx& C, int m0, int stride, int mx, const float* gpost, float scale, int lane) {
;     ...
;     for (int r = 0; r < R; ++r) { float s = 0.f;
; #pragma unroll
;         for (int j = 0; j < 4; ++j) s += ssq4(d[r][j]);
;         r1[r] = s; }
; #pragma unroll
;     for (int r = 0; r < R; ++r) r1[r] = rsqrtf(wave_sum(r1[r]) * (1.f / DM) + EPS) * scale;
; #pragma unroll
;     for (int j = 0; j < 4; ++j) { const v4f gp = ld4_f32(gpost + 4 * lane + 256 * j);
; #pragma unroll
;         for (int r = 0; r < R; ++r) d[r][j] = b[r][j] + d[r][j] * r1[r] * gp; }
;     if (OUT_F32) { float* Y = C.out();
; #pragma unroll
;         for (int r = 0; r < R; ++r)
; #pragma unroll
;             for (int j = 0; j < 4; ++j) if (ok[r]) *(v4f*)(Y + (size_t)mr[r] * DM + 4 * lane + 256 * j) = d[r][j];
;     } else { float* rs = C.RS(); float t[R];
; #pragma unroll
;         for (int r = 0; r < R; ++r) { float s = 0.f;
; #pragma unroll
;             for (int j = 0; j < 4; ++j) s += ssq4(d[r][j]);
;             t[r] = s; }
; #pragma unroll
;         for (int r = 0; r < R; ++r) t[r] = wave_sum(t[r]) * (1.f / DM) + EPS;
	v_lshlrev_b32_e32 v96, 16, v56
	v_and_b32_e32 v97, 0xffff0000, v56
	v_lshlrev_b32_e32 v98, 16, v57
	v_and_b32_e32 v99, 0xffff0000, v57
	v_lshlrev_b32_e32 v100, 16, v58
	v_and_b32_e32 v101, 0xffff0000, v58
	v_lshlrev_b32_e32 v102, 16, v59
	v_and_b32_e32 v103, 0xffff0000, v59
	v_lshlrev_b32_e32 v104, 16, v60
	v_and_b32_e32 v105, 0xffff0000, v60
	v_lshlrev_b32_e32 v106, 16, v61
	v_and_b32_e32 v107, 0xffff0000, v61
	v_lshlrev_b32_e32 v108, 16, v62
	v_and_b32_e32 v109, 0xffff0000, v62
	v_lshlrev_b32_e32 v110, 16, v63
	v_and_b32_e32 v111, 0xffff0000, v63
	v_pk_mul_f32 v[128:129], v[96:97], v[96:97]
	v_pk_fma_f32 v[128:129], v[98:99], v[98:99], v[128:129]
	v_pk_fma_f32 v[128:129], v[100:101], v[100:101], v[128:129]
	v_pk_fma_f32 v[128:129], v[102:103], v[102:103], v[128:129]
	v_pk_fma_f32 v[128:129], v[104:105], v[104:105], v[128:129]
	v_pk_fma_f32 v[128:129], v[106:107], v[106:107], v[128:129]
	v_pk_fma_f32 v[128:129], v[108:109], v[108:109], v[128:129]
	v_pk_fma_f32 v[128:129], v[110:111], v[110:111], v[128:129]
	s_nop 0
	v_add_f32_e32 v128, v128, v129
	s_waitcnt vmcnt(42)
	v_lshlrev_b32_e32 v112, 16, v64
	v_and_b32_e32 v113, 0xffff0000, v64
	v_lshlrev_b32_e32 v114, 16, v65
	v_and_b32_e32 v115, 0xffff0000, v65
	v_lshlrev_b32_e32 v116, 16, v66
	v_and_b32_e32 v117, 0xffff0000, v66
	v_lshlrev_b32_e32 v118, 16, v67
	v_and_b32_e32 v119, 0xffff0000, v67
	v_lshlrev_b32_e32 v120, 16, v68
	v_and_b32_e32 v121, 0xffff0000, v68
	v_lshlrev_b32_e32 v122, 16, v69
	v_and_b32_e32 v123, 0xffff0000, v69
	v_lshlrev_b32_e32 v124, 16, v70
	v_and_b32_e32 v125, 0xffff0000, v70
	v_lshlrev_b32_e32 v126, 16, v71
	v_and_b32_e32 v127, 0xffff0000, v71
	v_pk_mul_f32 v[130:131], v[112:113], v[112:113]
	v_pk_fma_f32 v[130:131], v[114:115], v[114:115], v[130:131]
	v_pk_fma_f32 v[130:131], v[116:117], v[116:117], v[130:131]
	v_pk_fma_f32 v[130:131], v[118:119], v[118:119], v[130:131]
	v_pk_fma_f32 v[130:131], v[120:121], v[120:121], v[130:131]
	v_pk_fma_f32 v[130:131], v[122:123], v[122:123], v[130:131]
	v_pk_fma_f32 v[130:131], v[124:125], v[124:125], v[130:131]
	v_pk_fma_f32 v[130:131], v[126:127], v[126:127], v[130:131]
	s_nop 0
	v_add_f32_e32 v130, v130, v131
	s_nop 1
	v_add_f32_dpp v128, v128, v128 quad_perm:[1,0,3,2] row_mask:0xf bank_mask:0xf
	v_add_f32_dpp v130, v130, v130 quad_perm:[1,0,3,2] row_mask:0xf bank_mask:0xf
	s_nop 0
	v_add_f32_dpp v128, v128, v128 quad_perm:[2,3,0,1] row_mask:0xf bank_mask:0xf
	v_add_f32_dpp v130, v130, v130 quad_perm:[2,3,0,1] row_mask:0xf bank_mask:0xf
	s_nop 0
	v_add_f32_dpp v128, v128, v128 row_half_mirror row_mask:0xf bank_mask:0xf
	v_add_f32_dpp v130, v130, v130 row_half_mirror row_mask:0xf bank_mask:0xf
	s_nop 0
	v_add_f32_dpp v128, v128, v128 row_mirror row_mask:0xf bank_mask:0xf
	v_add_f32_dpp v130, v130, v130 row_mirror row_mask:0xf bank_mask:0xf
	s_nop 0
	ds_bpermute_b32 v136, v187, v128
	ds_bpermute_b32 v137, v187, v130
	s_waitcnt lgkmcnt(0)
	v_add_f32_e32 v128, v128, v136
	v_add_f32_e32 v130, v130, v137
	ds_bpermute_b32 v136, v188, v128
	ds_bpermute_b32 v137, v188, v130
	s_waitcnt lgkmcnt(0)
	v_add_f32_e32 v128, v128, v136
	v_add_f32_e32 v130, v130, v137
	v_fmamk_f32 v128, v128, 0x3a800000, v138
	v_fmamk_f32 v130, v130, 0x3a800000, v138
	s_nop 0
	v_rsq_f32_e32 v128, v128
	v_rsq_f32_e32 v130, v130
	s_nop 1
	v_mul_f32_e32 v128, 0.5, v128
	v_mul_f32_e32 v130, 0.5, v130
	s_waitcnt vmcnt(38)
	v_pk_mul_f32 v[96:97], v[128:129], v[96:97] op_sel_hi:[0,1]
	v_pk_mul_f32 v[98:99], v[128:129], v[98:99] op_sel_hi:[0,1]
	v_pk_mul_f32 v[100:101], v[128:129], v[100:101] op_sel_hi:[0,1]
	v_pk_mul_f32 v[102:103], v[128:129], v[102:103] op_sel_hi:[0,1]
	v_pk_mul_f32 v[104:105], v[128:129], v[104:105] op_sel_hi:[0,1]
	v_pk_mul_f32 v[106:107], v[128:129], v[106:107] op_sel_hi:[0,1]
	v_pk_mul_f32 v[108:109], v[128:129], v[108:109] op_sel_hi:[0,1]
	v_pk_mul_f32 v[110:111], v[128:129], v[110:111] op_sel_hi:[0,1]
	v_pk_mul_f32 v[96:97], v[96:97], v[192:193]
	v_pk_mul_f32 v[98:99], v[98:99], v[194:195]
	v_pk_mul_f32 v[100:101], v[100:101], v[196:197]
	v_pk_mul_f32 v[102:103], v[102:103], v[198:199]
	v_pk_mul_f32 v[104:105], v[104:105], v[200:201]
	v_pk_mul_f32 v[106:107], v[106:107], v[202:203]
	v_pk_mul_f32 v[108:109], v[108:109], v[204:205]
	v_pk_mul_f32 v[110:111], v[110:111], v[206:207]
	v_lshlrev_b32_e32 v56, 16, v72
	v_and_b32_e32 v57, 0xffff0000, v72
	v_lshlrev_b32_e32 v58, 16, v73
	v_and_b32_e32 v59, 0xffff0000, v73
	v_lshlrev_b32_e32 v60, 16, v74
	v_and_b32_e32 v61, 0xffff0000, v74
	v_lshlrev_b32_e32 v62, 16, v75
	v_and_b32_e32 v63, 0xffff0000, v75
	v_pk_fma_f32 v[96:97], v[88:89], v[56:57], v[96:97] op_sel_hi:[0,1,1]
	v_pk_fma_f32 v[98:99], v[88:89], v[58:59], v[98:99] op_sel_hi:[0,1,1]
	v_pk_fma_f32 v[100:101], v[88:89], v[60:61], v[100:101] op_sel_hi:[0,1,1]
	v_pk_fma_f32 v[102:103], v[88:89], v[62:63], v[102:103] op_sel_hi:[0,1,1]
	v_lshlrev_b32_e32 v56, 16, v76
	v_and_b32_e32 v57, 0xffff0000, v76
	v_lshlrev_b32_e32 v58, 16, v77
	v_and_b32_e32 v59, 0xffff0000, v77
	v_lshlrev_b32_e32 v60, 16, v78
	v_and_b32_e32 v61, 0xffff0000, v78
	v_lshlrev_b32_e32 v62, 16, v79
	v_and_b32_e32 v63, 0xffff0000, v79
	v_pk_fma_f32 v[104:105], v[88:89], v[56:57], v[104:105] op_sel_hi:[0,1,1]
	v_pk_fma_f32 v[106:107], v[88:89], v[58:59], v[106:107] op_sel_hi:[0,1,1]
	v_pk_fma_f32 v[108:109], v[88:89], v[60:61], v[108:109] op_sel_hi:[0,1,1]
	v_pk_fma_f32 v[110:111], v[88:89], v[62:63], v[110:111] op_sel_hi:[0,1,1]
	v_pk_mul_f32 v[132:133], v[96:97], v[96:97]
	v_pk_fma_f32 v[132:133], v[98:99], v[98:99], v[132:133]
	v_pk_fma_f32 v[132:133], v[100:101], v[100:101], v[132:133]
	v_pk_fma_f32 v[132:133], v[102:103], v[102:103], v[132:133]
;     __device__ __forceinline__ float* out() const { return (float*)karg_in(33); }
; __device__ __forceinline__ const float* xrow_ptr(const Ctx& C, int row) { return row < MPROMPT ? C.in(0) + (size_t)row * DM : C.in(1) + (size_t)(row - MPROMPT) * DM; }
; __device__ __forceinline__ v4f ld4_bf16(const bf16* p) { const v2u w = *(const v2u*)p; return (v4f){bf_lo(w.x), bf_hi(w.x), bf_lo(w.y), bf_hi(w.y)}; }
; __device__ __forceinline__ float ssq4(v4f v) { return (v.x * v.x + v.y * v.y) + (v.z * v.z + v.w * v.w); }
; template <int R, bool BASE_F32, bool OUT_F32>
; __device__ __forceinline__ void rows_res(const Ctx& C, int m0, int stride, int mx, const float* gpost, float scale, int lane) {
;     ...
;     for (int r = 0; r < R; ++r) { mr[r] = (r == 4) ? mx : m0 + r * stride; ok[r] = (r == 4) ? (mx < M) : (mr[r] < MPROMPT); const int mm = ok[r] ? mr[r] : 0;
; #pragma unroll
;         for (int j = 0; j < 4; ++j) d[r][j] = ld4_bf16(D + (size_t)mm * DM + 4 * lane + 256 * j);
;         if (BASE_F32) { const float* x = xrow_ptr(C, mm);
; #pragma unroll
;             for (int j = 0; j < 4; ++j) b[r][j] = ld4_f32(x + 4 * lane + 256 * j);
;         } else { const float inv = C.RS()[mm];
; #pragma unroll
;             for (int j = 0; j < 4; ++j) b[r][j] = ld4_bf16(XN + (size_t)mm * DM + 4 * lane + 256 * j) * inv;
;         } }
; #pragma unroll
;     for (int r = 0; r < R; ++r) { float s = 0.f;
; #pragma unroll
;         for (int j = 0; j < 4; ++j) s += ssq4(d[r][j]);
;         r1[r] = s; }
; #pragma unroll
;     for (int r = 0; r < R; ++r) r1[r] = rsqrtf(wave_sum(r1[r]) * (1.f / DM) + EPS) * scale;
; #pragma unroll
;     for (int j = 0; j < 4; ++j) { const v4f gp = ld4_f32(gpost + 4 * lane + 256 * j);
; #pragma unroll
;         for (int r = 0; r < R; ++r) d[r][j] = b[r][j] + d[r][j] * r1[r] * gp; }
;     if (OUT_F32) { float* Y = C.out();
; #pragma unroll
;         for (int r = 0; r < R; ++r)
; #pragma unroll
;             for (int j = 0; j < 4; ++j) if (ok[r]) *(v4f*)(Y + (size_t)mr[r] * DM + 4 * lane + 256 * j) = d[r][j];
;     } else { float* rs = C.RS(); float t[R];
; #pragma unroll
;         for (int r = 0; r < R; ++r) { float s = 0.f;
; #pragma unroll
;             for (int j = 0; j < 4; ++j) s += ssq4(d[r][j]);
;             t[r] = s; }
; #pragma unroll
;         for (int r = 0; r < R; ++r) t[r] = wave_sum(t[r]) * (1.f / DM) + EPS;
	v_pk_fma_f32 v[132:133], v[104:105], v[104:105], v[132:133]
	v_pk_fma_f32 v[132:133], v[106:107], v[106:107], v[132:133]
	v_pk_fma_f32 v[132:133], v[108:109], v[108:109], v[132:133]
	v_pk_fma_f32 v[132:133], v[110:111], v[110:111], v[132:133]
	s_nop 0
	v_add_f32_e32 v132, v132, v133
	v_pk_mul_f32 v[112:113], v[130:131], v[112:113] op_sel_hi:[0,1]
	v_pk_mul_f32 v[114:115], v[130:131], v[114:115] op_sel_hi:[0,1]
	v_pk_mul_f32 v[116:117], v[130:131], v[116:117] op_sel_hi:[0,1]
	v_pk_mul_f32 v[118:119], v[130:131], v[118:119] op_sel_hi:[0,1]
	v_pk_mul_f32 v[120:121], v[130:131], v[120:121] op_sel_hi:[0,1]
	v_pk_mul_f32 v[122:123], v[130:131], v[122:123] op_sel_hi:[0,1]
	v_pk_mul_f32 v[124:125], v[130:131], v[124:125] op_sel_hi:[0,1]
	v_pk_mul_f32 v[126:127], v[130:131], v[126:127] op_sel_hi:[0,1]
	v_pk_mul_f32 v[112:113], v[112:113], v[192:193]
	v_pk_mul_f32 v[114:115], v[114:115], v[194:195]
	v_pk_mul_f32 v[116:117], v[116:117], v[196:197]
	v_pk_mul_f32 v[118:119], v[118:119], v[198:199]
	v_pk_mul_f32 v[120:121], v[120:121], v[200:201]
	v_pk_mul_f32 v[122:123], v[122:123], v[202:203]
	v_pk_mul_f32 v[124:125], v[124:125], v[204:205]
	v_pk_mul_f32 v[126:127], v[126:127], v[206:207]
	v_lshlrev_b32_e32 v64, 16, v80
	v_and_b32_e32 v65, 0xffff0000, v80
	v_lshlrev_b32_e32 v66, 16, v81
	v_and_b32_e32 v67, 0xffff0000, v81
	v_lshlrev_b32_e32 v68, 16, v82
	v_and_b32_e32 v69, 0xffff0000, v82
	v_lshlrev_b32_e32 v70, 16, v83
	v_and_b32_e32 v71, 0xffff0000, v83
	v_pk_fma_f32 v[112:113], v[90:91], v[64:65], v[112:113] op_sel_hi:[0,1,1]
	v_pk_fma_f32 v[114:115], v[90:91], v[66:67], v[114:115] op_sel_hi:[0,1,1]
	v_pk_fma_f32 v[116:117], v[90:91], v[68:69], v[116:117] op_sel_hi:[0,1,1]
	v_pk_fma_f32 v[118:119], v[90:91], v[70:71], v[118:119] op_sel_hi:[0,1,1]
	v_lshlrev_b32_e32 v64, 16, v84
	v_and_b32_e32 v65, 0xffff0000, v84
	v_lshlrev_b32_e32 v66, 16, v85
	v_and_b32_e32 v67, 0xffff0000, v85
	v_lshlrev_b32_e32 v68, 16, v86
	v_and_b32_e32 v69, 0xffff0000, v86
	v_lshlrev_b32_e32 v70, 16, v87
	v_and_b32_e32 v71, 0xffff0000, v87
	v_pk_fma_f32 v[120:121], v[90:91], v[64:65], v[120:121] op_sel_hi:[0,1,1]
	v_pk_fma_f32 v[122:123], v[90:91], v[66:67], v[122:123] op_sel_hi:[0,1,1]
	v_pk_fma_f32 v[124:125], v[90:91], v[68:69], v[124:125] op_sel_hi:[0,1,1]
	v_pk_fma_f32 v[126:127], v[90:91], v[70:71], v[126:127] op_sel_hi:[0,1,1]
	v_pk_mul_f32 v[134:135], v[112:113], v[112:113]
	v_pk_fma_f32 v[134:135], v[114:115], v[114:115], v[134:135]
	v_pk_fma_f32 v[134:135], v[116:117], v[116:117], v[134:135]
	v_pk_fma_f32 v[134:135], v[118:119], v[118:119], v[134:135]
	v_pk_fma_f32 v[134:135], v[120:121], v[120:121], v[134:135]
	v_pk_fma_f32 v[134:135], v[122:123], v[122:123], v[134:135]
	v_pk_fma_f32 v[134:135], v[124:125], v[124:125], v[134:135]
	v_pk_fma_f32 v[134:135], v[126:127], v[126:127], v[134:135]
	s_nop 0
	v_add_f32_e32 v134, v134, v135
	global_load_dword v88, v172, s[98:99]
	global_load_dwordx2 v[56:57], v170, s[98:99]
	global_load_dwordx2 v[58:59], v170, s[98:99] offset:512
	global_load_dwordx2 v[60:61], v170, s[98:99] offset:1024
	global_load_dwordx2 v[62:63], v170, s[98:99] offset:1536
	global_load_dwordx2 v[72:73], v171, s[98:99]
	global_load_dwordx2 v[74:75], v171, s[98:99] offset:512
	global_load_dwordx2 v[76:77], v171, s[98:99] offset:1024
	global_load_dwordx2 v[78:79], v171, s[98:99] offset:1536
	v_add_u32_e32 v170, 0x400000, v170
	v_add_u32_e32 v171, 0x400000, v171
	v_add_u32_e32 v172, 0x2000, v172
	global_load_dword v90, v172, s[98:99]
	global_load_dwordx2 v[64:65], v170, s[98:99]
	global_load_dwordx2 v[66:67], v170, s[98:99] offset:512
	global_load_dwordx2 v[68:69], v170, s[98:99] offset:1024
	global_load_dwordx2 v[70:71], v170, s[98:99] offset:1536
	global_load_dwordx2 v[80:81], v171, s[98:99]
	global_load_dwordx2 v[82:83], v171, s[98:99] offset:512
	global_load_dwordx2 v[84:85], v171, s[98:99] offset:1024
	global_load_dwordx2 v[86:87], v171, s[98:99] offset:1536
	v_add_u32_e32 v170, 0x400000, v170
	v_add_u32_e32 v171, 0x400000, v171
	v_add_u32_e32 v172, 0x2000, v172
	s_nop 1
	v_add_f32_dpp v132, v132, v132 quad_perm:[1,0,3,2] row_mask:0xf bank_mask:0xf
	v_add_f32_dpp v134, v134, v134 quad_perm:[1,0,3,2] row_mask:0xf bank_mask:0xf
	s_nop 0
	v_add_f32_dpp v132, v132, v132 quad_perm:[2,3,0,1] row_mask:0xf bank_mask:0xf
	v_add_f32_dpp v134, v134, v134 quad_perm:[2,3,0,1] row_mask:0xf bank_mask:0xf
	s_nop 0
	v_add_f32_dpp v132, v132, v132 row_half_mirror row_mask:0xf bank_mask:0xf
	v_add_f32_dpp v134, v134, v134 row_half_mirror row_mask:0xf bank_mask:0xf
	s_nop 0
	v_add_f32_dpp v132, v132, v132 row_mirror row_mask:0xf bank_mask:0xf
	v_add_f32_dpp v134, v134, v134 row_mirror row_mask:0xf bank_mask:0xf
	s_nop 0
	ds_bpermute_b32 v136, v187, v132
	ds_bpermute_b32 v137, v187, v134
	s_waitcnt lgkmcnt(0)
	v_add_f32_e32 v132, v132, v136
	v_add_f32_e32 v134, v134, v137
	ds_bpermute_b32 v136, v188, v132
	ds_bpermute_b32 v137, v188, v134
	s_waitcnt lgkmcnt(0)
;     __device__ __forceinline__ float* out() const { return (float*)karg_in(33); }
; __device__ __forceinline__ void st4_bf16(bf16* p, v4f o) { v2u w; w.x = cvt_pk_nv(o.x, o.y); w.y = cvt_pk_nv(o.z, o.w); *(v2u*)p = w; }
; __device__ __forceinline__ float ssq4(v4f v) { return (v.x * v.x + v.y * v.y) + (v.z * v.z + v.w * v.w); }
; template <int R, bool BASE_F32, bool OUT_F32>
; __device__ __forceinline__ void rows_res(const Ctx& C, int m0, int stride, int mx, const float* gpost, float scale, int lane) {
;     ...
;     for (int r = 0; r < R; ++r) { float s = 0.f;
; #pragma unroll
;         for (int j = 0; j < 4; ++j) s += ssq4(d[r][j]);
;         r1[r] = s; }
; #pragma unroll
;     for (int r = 0; r < R; ++r) r1[r] = rsqrtf(wave_sum(r1[r]) * (1.f / DM) + EPS) * scale;
; #pragma unroll
;     for (int j = 0; j < 4; ++j) { const v4f gp = ld4_f32(gpost + 4 * lane + 256 * j);
; #pragma unroll
;         for (int r = 0; r < R; ++r) d[r][j] = b[r][j] + d[r][j] * r1[r] * gp; }
;     if (OUT_F32) { float* Y = C.out();
; #pragma unroll
;         for (int r = 0; r < R; ++r)
; #pragma unroll
;             for (int j = 0; j < 4; ++j) if (ok[r]) *(v4f*)(Y + (size_t)mr[r] * DM + 4 * lane + 256 * j) = d[r][j];
;     } else { float* rs = C.RS(); float t[R];
; #pragma unroll
;         for (int r = 0; r < R; ++r) { float s = 0.f;
; #pragma unroll
;             for (int j = 0; j < 4; ++j) s += ssq4(d[r][j]);
;             t[r] = s; }
; #pragma unroll
;         for (int r = 0; r < R; ++r) t[r] = wave_sum(t[r]) * (1.f / DM) + EPS;
; #pragma unroll
;         for (int r = 0; r < R; ++r) { const float rstd = rsqrtf(t[r]);
; #pragma unroll
;             for (int j = 0; j < 4; ++j) if (ok[r]) st4_bf16(XN + (size_t)mr[r] * DM + 4 * lane + 256 * j, d[r][j] * rstd);
;             if (lane == 0 && ok[r]) rs[mr[r]] = sqrtf(t[r]); }
	v_add_f32_e32 v132, v132, v136
	v_add_f32_e32 v134, v134, v137
	v_fmamk_f32 v164, v132, 0x3a800000, v138
	v_fmamk_f32 v167, v134, 0x3a800000, v138
	s_nop 0
	v_rsq_f32_e32 v132, v164
	v_rsq_f32_e32 v134, v167
	v_sqrt_f32_e32 v165, v164
	v_sqrt_f32_e32 v168, v167
	s_nop 1
	v_pk_mul_f32 v[140:141], v[96:97], v[132:133] op_sel_hi:[1,0]
	v_cvt_pk_bf16_f32 v148, v140, v141
	v_pk_mul_f32 v[142:143], v[98:99], v[132:133] op_sel_hi:[1,0]
	v_cvt_pk_bf16_f32 v149, v142, v143
	v_pk_mul_f32 v[144:145], v[100:101], v[132:133] op_sel_hi:[1,0]
	v_cvt_pk_bf16_f32 v150, v144, v145
	v_pk_mul_f32 v[146:147], v[102:103], v[132:133] op_sel_hi:[1,0]
	v_cvt_pk_bf16_f32 v151, v146, v147
	v_pk_mul_f32 v[140:141], v[104:105], v[132:133] op_sel_hi:[1,0]
	v_cvt_pk_bf16_f32 v152, v140, v141
	v_pk_mul_f32 v[142:143], v[106:107], v[132:133] op_sel_hi:[1,0]
	v_cvt_pk_bf16_f32 v153, v142, v143
	v_pk_mul_f32 v[144:145], v[108:109], v[132:133] op_sel_hi:[1,0]
	v_cvt_pk_bf16_f32 v154, v144, v145
	v_pk_mul_f32 v[146:147], v[110:111], v[132:133] op_sel_hi:[1,0]
	v_cvt_pk_bf16_f32 v155, v146, v147
	global_store_dwordx2 v173, v[148:149], s[98:99]
	global_store_dwordx2 v173, v[150:151], s[98:99] offset:512
	global_store_dwordx2 v173, v[152:153], s[98:99] offset:1024
	global_store_dwordx2 v173, v[154:155], s[98:99] offset:1536
	v_add_u32_e32 v173, 0x400000, v173
	v_pk_mul_f32 v[140:141], v[112:113], v[134:135] op_sel_hi:[1,0]
	v_cvt_pk_bf16_f32 v156, v140, v141
	v_pk_mul_f32 v[142:143], v[114:115], v[134:135] op_sel_hi:[1,0]
	v_cvt_pk_bf16_f32 v157, v142, v143
	v_pk_mul_f32 v[144:145], v[116:117], v[134:135] op_sel_hi:[1,0]
	v_cvt_pk_bf16_f32 v158, v144, v145
	v_pk_mul_f32 v[146:147], v[118:119], v[134:135] op_sel_hi:[1,0]
	v_cvt_pk_bf16_f32 v159, v146, v147
	v_pk_mul_f32 v[140:141], v[120:121], v[134:135] op_sel_hi:[1,0]
	v_cvt_pk_bf16_f32 v160, v140, v141
	v_pk_mul_f32 v[142:143], v[122:123], v[134:135] op_sel_hi:[1,0]
	v_cvt_pk_bf16_f32 v161, v142, v143
	v_pk_mul_f32 v[144:145], v[124:125], v[134:135] op_sel_hi:[1,0]
	v_cvt_pk_bf16_f32 v162, v144, v145
	v_pk_mul_f32 v[146:147], v[126:127], v[134:135] op_sel_hi:[1,0]
	v_cvt_pk_bf16_f32 v163, v146, v147
	global_store_dwordx2 v173, v[156:157], s[98:99]
	global_store_dwordx2 v173, v[158:159], s[98:99] offset:512
	global_store_dwordx2 v173, v[160:161], s[98:99] offset:1024
	global_store_dwordx2 v173, v[162:163], s[98:99] offset:1536
	v_add_u32_e32 v173, 0x400000, v173
	v_add_u32_e32 v166, -1, v165
	v_fma_f32 v140, -v166, v165, v164
	v_cmp_ge_f32_e32 vcc, 0, v140
	v_add_u32_e32 v141, 1, v165
	v_cndmask_b32_e32 v166, v165, v166, vcc
	v_fma_f32 v140, -v141, v165, v164
	v_cmp_lt_f32_e32 vcc, 0, v140
	s_nop 1
	v_cndmask_b32_e32 v165, v166, v141, vcc
	v_add_u32_e32 v169, -1, v168
	v_fma_f32 v142, -v169, v168, v167
	v_cmp_ge_f32_e32 vcc, 0, v142
	v_add_u32_e32 v143, 1, v168
	v_cndmask_b32_e32 v169, v168, v169, vcc
	v_fma_f32 v142, -v143, v168, v167
	v_cmp_lt_f32_e32 vcc, 0, v142
	s_nop 1
	v_cndmask_b32_e32 v168, v169, v143, vcc
	s_mov_b64 exec, 1
	global_store_dword v174, v165, s[98:99]
	v_add_u32_e32 v174, 0x2000, v174
	global_store_dword v174, v168, s[98:99]
	v_add_u32_e32 v174, 0x2000, v174
	s_mov_b64 exec, -1
	s_waitcnt vmcnt(51)
	v_lshlrev_b32_e32 v96, 16, v20
	v_and_b32_e32 v97, 0xffff0000, v20
	v_lshlrev_b32_e32 v98, 16, v21
	v_and_b32_e32 v99, 0xffff0000, v21
	v_lshlrev_b32_e32 v100, 16, v22
	v_and_b32_e32 v101, 0xffff0000, v22
	v_lshlrev_b32_e32 v102, 16, v23
	v_and_b32_e32 v103, 0xffff0000, v23
	v_lshlrev_b32_e32 v104, 16, v24
	v_and_b32_e32 v105, 0xffff0000, v24
	v_lshlrev_b32_e32 v106, 16, v25
	v_and_b32_e32 v107, 0xffff0000, v25
	v_lshlrev_b32_e32 v108, 16, v26
	v_and_b32_e32 v109, 0xffff0000, v26
	v_lshlrev_b32_e32 v110, 16, v27
	v_and_b32_e32 v111, 0xffff0000, v27
	v_pk_mul_f32 v[128:129], v[96:97], v[96:97]
	v_pk_fma_f32 v[128:129], v[98:99], v[98:99], v[128:129]
	v_pk_fma_f32 v[128:129], v[100:101], v[100:101], v[128:129]
	v_pk_fma_f32 v[128:129], v[102:103], v[102:103], v[128:129]
	v_pk_fma_f32 v[128:129], v[104:105], v[104:105], v[128:129]
	v_pk_fma_f32 v[128:129], v[106:107], v[106:107], v[128:129]
	v_pk_fma_f32 v[128:129], v[108:109], v[108:109], v[128:129]
	v_pk_fma_f32 v[128:129], v[110:111], v[110:111], v[128:129]
	s_nop 0
	v_add_f32_e32 v128, v128, v129
	s_waitcnt vmcnt(42)
	v_lshlrev_b32_e32 v112, 16, v28
	v_and_b32_e32 v113, 0xffff0000, v28
	v_lshlrev_b32_e32 v114, 16, v29
	v_and_b32_e32 v115, 0xffff0000, v29
	v_lshlrev_b32_e32 v116, 16, v30
	v_and_b32_e32 v117, 0xffff0000, v30
	v_lshlrev_b32_e32 v118, 16, v31
	v_and_b32_e32 v119, 0xffff0000, v31
	v_lshlrev_b32_e32 v120, 16, v32
	v_and_b32_e32 v121, 0xffff0000, v32
	v_lshlrev_b32_e32 v122, 16, v33
	v_and_b32_e32 v123, 0xffff0000, v33
	v_lshlrev_b32_e32 v124, 16, v34
	v_and_b32_e32 v125, 0xffff0000, v34
	v_lshlrev_b32_e32 v126, 16, v35
	v_and_b32_e32 v127, 0xffff0000, v35
	v_pk_mul_f32 v[130:131], v[112:113], v[112:113]
	v_pk_fma_f32 v[130:131], v[114:115], v[114:115], v[130:131]
	v_pk_fma_f32 v[130:131], v[116:117], v[116:117], v[130:131]
	v_pk_fma_f32 v[130:131], v[118:119], v[118:119], v[130:131]
	v_pk_fma_f32 v[130:131], v[120:121], v[120:121], v[130:131]
	v_pk_fma_f32 v[130:131], v[122:123], v[122:123], v[130:131]
	v_pk_fma_f32 v[130:131], v[124:125], v[124:125], v[130:131]
	v_pk_fma_f32 v[130:131], v[126:127], v[126:127], v[130:131]
	s_nop 0
	v_add_f32_e32 v130, v130, v131
	s_nop 1
	v_add_f32_dpp v128, v128, v128 quad_perm:[1,0,3,2] row_mask:0xf bank_mask:0xf
	v_add_f32_dpp v130, v130, v130 quad_perm:[1,0,3,2] row_mask:0xf bank_mask:0xf
	s_nop 0
	v_add_f32_dpp v128, v128, v128 quad_perm:[2,3,0,1] row_mask:0xf bank_mask:0xf
	v_add_f32_dpp v130, v130, v130 quad_perm:[2,3,0,1] row_mask:0xf bank_mask:0xf
	s_nop 0
	v_add_f32_dpp v128, v128, v128 row_half_mirror row_mask:0xf bank_mask:0xf
	v_add_f32_dpp v130, v130, v130 row_half_mirror row_mask:0xf bank_mask:0xf
	s_nop 0
	v_add_f32_dpp v128, v128, v128 row_mirror row_mask:0xf bank_mask:0xf
	v_add_f32_dpp v130, v130, v130 row_mirror row_mask:0xf bank_mask:0xf
	s_nop 0
	ds_bpermute_b32 v136, v187, v128
	ds_bpermute_b32 v137, v187, v130
	s_waitcnt lgkmcnt(0)
;     __device__ __forceinline__ float* out() const { return (float*)karg_in(33); }
; __device__ __forceinline__ const float* xrow_ptr(const Ctx& C, int row) { return row < MPROMPT ? C.in(0) + (size_t)row * DM : C.in(1) + (size_t)(row - MPROMPT) * DM; }
; __device__ __forceinline__ v4f ld4_bf16(const bf16* p) { const v2u w = *(const v2u*)p; return (v4f){bf_lo(w.x), bf_hi(w.x), bf_lo(w.y), bf_hi(w.y)}; }
; __device__ __forceinline__ float ssq4(v4f v) { return (v.x * v.x + v.y * v.y) + (v.z * v.z + v.w * v.w); }
; template <int R, bool BASE_F32, bool OUT_F32>
; __device__ __forceinline__ void rows_res(const Ctx& C, int m0, int stride, int mx, const float* gpost, float scale, int lane) {
;     ...
;     for (int r = 0; r < R; ++r) { mr[r] = (r == 4) ? mx : m0 + r * stride; ok[r] = (r == 4) ? (mx < M) : (mr[r] < MPROMPT); const int mm = ok[r] ? mr[r] : 0;
; #pragma unroll
;         for (int j = 0; j < 4; ++j) d[r][j] = ld4_bf16(D + (size_t)mm * DM + 4 * lane + 256 * j);
;         if (BASE_F32) { const float* x = xrow_ptr(C, mm);
; #pragma unroll
;             for (int j = 0; j < 4; ++j) b[r][j] = ld4_f32(x + 4 * lane + 256 * j);
;         } else { const float inv = C.RS()[mm];
; #pragma unroll
;             for (int j = 0; j < 4; ++j) b[r][j] = ld4_bf16(XN + (size_t)mm * DM + 4 * lane + 256 * j) * inv;
;         } }
; #pragma unroll
;     for (int r = 0; r < R; ++r) { float s = 0.f;
; #pragma unroll
;         for (int j = 0; j < 4; ++j) s += ssq4(d[r][j]);
;         r1[r] = s; }
; #pragma unroll
;     for (int r = 0; r < R; ++r) r1[r] = rsqrtf(wave_sum(r1[r]) * (1.f / DM) + EPS) * scale;
; #pragma unroll
;     for (int j = 0; j < 4; ++j) { const v4f gp = ld4_f32(gpost + 4 * lane + 256 * j);
; #pragma unroll
;         for (int r = 0; r < R; ++r) d[r][j] = b[r][j] + d[r][j] * r1[r] * gp; }
;     if (OUT_F32) { float* Y = C.out();
; #pragma unroll
;         for (int r = 0; r < R; ++r)
; #pragma unroll
;             for (int j = 0; j < 4; ++j) if (ok[r]) *(v4f*)(Y + (size_t)mr[r] * DM + 4 * lane + 256 * j) = d[r][j];
;     } else { float* rs = C.RS(); float t[R];
; #pragma unroll
;         for (int r = 0; r < R; ++r) { float s = 0.f;
; #pragma unroll
;             for (int j = 0; j < 4; ++j) s += ssq4(d[r][j]);
;             t[r] = s; }
; #pragma unroll
;         for (int r = 0; r < R; ++r) t[r] = wave_sum(t[r]) * (1.f / DM) + EPS;
	v_add_f32_e32 v128, v128, v136
	v_add_f32_e32 v130, v130, v137
	ds_bpermute_b32 v136, v188, v128
	ds_bpermute_b32 v137, v188, v130
	s_waitcnt lgkmcnt(0)
	v_add_f32_e32 v128, v128, v136
	v_add_f32_e32 v130, v130, v137
	v_fmamk_f32 v128, v128, 0x3a800000, v138
	v_fmamk_f32 v130, v130, 0x3a800000, v138
	s_nop 0
	v_rsq_f32_e32 v128, v128
	v_rsq_f32_e32 v130, v130
	s_nop 1
	v_mul_f32_e32 v128, 0.5, v128
	v_mul_f32_e32 v130, 0.5, v130
	s_waitcnt vmcnt(38)
	v_pk_mul_f32 v[96:97], v[128:129], v[96:97] op_sel_hi:[0,1]
	v_pk_mul_f32 v[98:99], v[128:129], v[98:99] op_sel_hi:[0,1]
	v_pk_mul_f32 v[100:101], v[128:129], v[100:101] op_sel_hi:[0,1]
	v_pk_mul_f32 v[102:103], v[128:129], v[102:103] op_sel_hi:[0,1]
	v_pk_mul_f32 v[104:105], v[128:129], v[104:105] op_sel_hi:[0,1]
	v_pk_mul_f32 v[106:107], v[128:129], v[106:107] op_sel_hi:[0,1]
	v_pk_mul_f32 v[108:109], v[128:129], v[108:109] op_sel_hi:[0,1]
	v_pk_mul_f32 v[110:111], v[128:129], v[110:111] op_sel_hi:[0,1]
	v_pk_mul_f32 v[96:97], v[96:97], v[192:193]
	v_pk_mul_f32 v[98:99], v[98:99], v[194:195]
	v_pk_mul_f32 v[100:101], v[100:101], v[196:197]
	v_pk_mul_f32 v[102:103], v[102:103], v[198:199]
	v_pk_mul_f32 v[104:105], v[104:105], v[200:201]
	v_pk_mul_f32 v[106:107], v[106:107], v[202:203]
	v_pk_mul_f32 v[108:109], v[108:109], v[204:205]
	v_pk_mul_f32 v[110:111], v[110:111], v[206:207]
	v_lshlrev_b32_e32 v20, 16, v36
	v_and_b32_e32 v21, 0xffff0000, v36
	v_lshlrev_b32_e32 v22, 16, v37
	v_and_b32_e32 v23, 0xffff0000, v37
	v_lshlrev_b32_e32 v24, 16, v38
	v_and_b32_e32 v25, 0xffff0000, v38
	v_lshlrev_b32_e32 v26, 16, v39
	v_and_b32_e32 v27, 0xffff0000, v39
	v_pk_fma_f32 v[96:97], v[52:53], v[20:21], v[96:97] op_sel_hi:[0,1,1]
	v_pk_fma_f32 v[98:99], v[52:53], v[22:23], v[98:99] op_sel_hi:[0,1,1]
	v_pk_fma_f32 v[100:101], v[52:53], v[24:25], v[100:101] op_sel_hi:[0,1,1]
	v_pk_fma_f32 v[102:103], v[52:53], v[26:27], v[102:103] op_sel_hi:[0,1,1]
	v_lshlrev_b32_e32 v20, 16, v40
	v_and_b32_e32 v21, 0xffff0000, v40
	v_lshlrev_b32_e32 v22, 16, v41
	v_and_b32_e32 v23, 0xffff0000, v41
	v_lshlrev_b32_e32 v24, 16, v42
	v_and_b32_e32 v25, 0xffff0000, v42
	v_lshlrev_b32_e32 v26, 16, v43
	v_and_b32_e32 v27, 0xffff0000, v43
	v_pk_fma_f32 v[104:105], v[52:53], v[20:21], v[104:105] op_sel_hi:[0,1,1]
	v_pk_fma_f32 v[106:107], v[52:53], v[22:23], v[106:107] op_sel_hi:[0,1,1]
	v_pk_fma_f32 v[108:109], v[52:53], v[24:25], v[108:109] op_sel_hi:[0,1,1]
	v_pk_fma_f32 v[110:111], v[52:53], v[26:27], v[110:111] op_sel_hi:[0,1,1]
	v_pk_mul_f32 v[132:133], v[96:97], v[96:97]
	v_pk_fma_f32 v[132:133], v[98:99], v[98:99], v[132:133]
	v_pk_fma_f32 v[132:133], v[100:101], v[100:101], v[132:133]
	v_pk_fma_f32 v[132:133], v[102:103], v[102:103], v[132:133]
	v_pk_fma_f32 v[132:133], v[104:105], v[104:105], v[132:133]
	v_pk_fma_f32 v[132:133], v[106:107], v[106:107], v[132:133]
	v_pk_fma_f32 v[132:133], v[108:109], v[108:109], v[132:133]
	v_pk_fma_f32 v[132:133], v[110:111], v[110:111], v[132:133]
	s_nop 0
	v_add_f32_e32 v132, v132, v133
	v_pk_mul_f32 v[112:113], v[130:131], v[112:113] op_sel_hi:[0,1]
	v_pk_mul_f32 v[114:115], v[130:131], v[114:115] op_sel_hi:[0,1]
	v_pk_mul_f32 v[116:117], v[130:131], v[116:117] op_sel_hi:[0,1]
	v_pk_mul_f32 v[118:119], v[130:131], v[118:119] op_sel_hi:[0,1]
	v_pk_mul_f32 v[120:121], v[130:131], v[120:121] op_sel_hi:[0,1]
	v_pk_mul_f32 v[122:123], v[130:131], v[122:123] op_sel_hi:[0,1]
	v_pk_mul_f32 v[124:125], v[130:131], v[124:125] op_sel_hi:[0,1]
	v_pk_mul_f32 v[126:127], v[130:131], v[126:127] op_sel_hi:[0,1]
	v_pk_mul_f32 v[112:113], v[112:113], v[192:193]
	v_pk_mul_f32 v[114:115], v[114:115], v[194:195]
	v_pk_mul_f32 v[116:117], v[116:117], v[196:197]
	v_pk_mul_f32 v[118:119], v[118:119], v[198:199]
	v_pk_mul_f32 v[120:121], v[120:121], v[200:201]
	v_pk_mul_f32 v[122:123], v[122:123], v[202:203]
	v_pk_mul_f32 v[124:125], v[124:125], v[204:205]
	v_pk_mul_f32 v[126:127], v[126:127], v[206:207]
	v_lshlrev_b32_e32 v28, 16, v44
	v_and_b32_e32 v29, 0xffff0000, v44
	v_lshlrev_b32_e32 v30, 16, v45
	v_and_b32_e32 v31, 0xffff0000, v45
	v_lshlrev_b32_e32 v32, 16, v46
	v_and_b32_e32 v33, 0xffff0000, v46
	v_lshlrev_b32_e32 v34, 16, v47
	v_and_b32_e32 v35, 0xffff0000, v47
	v_pk_fma_f32 v[112:113], v[54:55], v[28:29], v[112:113] op_sel_hi:[0,1,1]
	v_pk_fma_f32 v[114:115], v[54:55], v[30:31], v[114:115] op_sel_hi:[0,1,1]
	v_pk_fma_f32 v[116:117], v[54:55], v[32:33], v[116:117] op_sel_hi:[0,1,1]
	v_pk_fma_f32 v[118:119], v[54:55], v[34:35], v[118:119] op_sel_hi:[0,1,1]
	v_lshlrev_b32_e32 v28, 16, v48
	v_and_b32_e32 v29, 0xffff0000, v48
	v_lshlrev_b32_e32 v30, 16, v49
	v_and_b32_e32 v31, 0xffff0000, v49
	v_lshlrev_b32_e32 v32, 16, v50
	v_and_b32_e32 v33, 0xffff0000, v50
	v_lshlrev_b32_e32 v34, 16, v51
	v_and_b32_e32 v35, 0xffff0000, v51
	v_pk_fma_f32 v[120:121], v[54:55], v[28:29], v[120:121] op_sel_hi:[0,1,1]
	v_pk_fma_f32 v[122:123], v[54:55], v[30:31], v[122:123] op_sel_hi:[0,1,1]
	v_pk_fma_f32 v[124:125], v[54:55], v[32:33], v[124:125] op_sel_hi:[0,1,1]
	v_pk_fma_f32 v[126:127], v[54:55], v[34:35], v[126:127] op_sel_hi:[0,1,1]
	v_pk_mul_f32 v[134:135], v[112:113], v[112:113]
	v_pk_fma_f32 v[134:135], v[114:115], v[114:115], v[134:135]
	v_pk_fma_f32 v[134:135], v[116:117], v[116:117], v[134:135]
	v_pk_fma_f32 v[134:135], v[118:119], v[118:119], v[134:135]
	v_pk_fma_f32 v[134:135], v[120:121], v[120:121], v[134:135]
	v_pk_fma_f32 v[134:135], v[122:123], v[122:123], v[134:135]
	v_pk_fma_f32 v[134:135], v[124:125], v[124:125], v[134:135]
	v_pk_fma_f32 v[134:135], v[126:127], v[126:127], v[134:135]
	s_nop 0
	v_add_f32_e32 v134, v134, v135
	s_nop 1
	v_add_f32_dpp v132, v132, v132 quad_perm:[1,0,3,2] row_mask:0xf bank_mask:0xf
	v_add_f32_dpp v134, v134, v134 quad_perm:[1,0,3,2] row_mask:0xf bank_mask:0xf
	s_nop 0
	v_add_f32_dpp v132, v132, v132 quad_perm:[2,3,0,1] row_mask:0xf bank_mask:0xf
	v_add_f32_dpp v134, v134, v134 quad_perm:[2,3,0,1] row_mask:0xf bank_mask:0xf
	s_nop 0
	v_add_f32_dpp v132, v132, v132 row_half_mirror row_mask:0xf bank_mask:0xf
	v_add_f32_dpp v134, v134, v134 row_half_mirror row_mask:0xf bank_mask:0xf
	s_nop 0
	v_add_f32_dpp v132, v132, v132 row_mirror row_mask:0xf bank_mask:0xf
	v_add_f32_dpp v134, v134, v134 row_mirror row_mask:0xf bank_mask:0xf
	s_nop 0
	ds_bpermute_b32 v136, v187, v132
	ds_bpermute_b32 v137, v187, v134
	s_waitcnt lgkmcnt(0)
;     __device__ __forceinline__ float* out() const { return (float*)karg_in(33); }
; __device__ __forceinline__ void st4_bf16(bf16* p, v4f o) { v2u w; w.x = cvt_pk_nv(o.x, o.y); w.y = cvt_pk_nv(o.z, o.w); *(v2u*)p = w; }
; __device__ __forceinline__ float ssq4(v4f v) { return (v.x * v.x + v.y * v.y) + (v.z * v.z + v.w * v.w); }
; template <int R, bool BASE_F32, bool OUT_F32>
; __device__ __forceinline__ void rows_res(const Ctx& C, int m0, int stride, int mx, const float* gpost, float scale, int lane) {
;     ...
;     for (int r = 0; r < R; ++r) { float s = 0.f;
; #pragma unroll
;         for (int j = 0; j < 4; ++j) s += ssq4(d[r][j]);
;         r1[r] = s; }
; #pragma unroll
;     for (int r = 0; r < R; ++r) r1[r] = rsqrtf(wave_sum(r1[r]) * (1.f / DM) + EPS) * scale;
; #pragma unroll
;     for (int j = 0; j < 4; ++j) { const v4f gp = ld4_f32(gpost + 4 * lane + 256 * j);
; #pragma unroll
;         for (int r = 0; r < R; ++r) d[r][j] = b[r][j] + d[r][j] * r1[r] * gp; }
;     if (OUT_F32) { float* Y = C.out();
; #pragma unroll
;         for (int r = 0; r < R; ++r)
; #pragma unroll
;             for (int j = 0; j < 4; ++j) if (ok[r]) *(v4f*)(Y + (size_t)mr[r] * DM + 4 * lane + 256 * j) = d[r][j];
;     } else { float* rs = C.RS(); float t[R];
; #pragma unroll
;         for (int r = 0; r < R; ++r) { float s = 0.f;
; #pragma unroll
;             for (int j = 0; j < 4; ++j) s += ssq4(d[r][j]);
;             t[r] = s; }
; #pragma unroll
;         for (int r = 0; r < R; ++r) t[r] = wave_sum(t[r]) * (1.f / DM) + EPS;
; #pragma unroll
;         for (int r = 0; r < R; ++r) { const float rstd = rsqrtf(t[r]);
; #pragma unroll
;             for (int j = 0; j < 4; ++j) if (ok[r]) st4_bf16(XN + (size_t)mr[r] * DM + 4 * lane + 256 * j, d[r][j] * rstd);
;             if (lane == 0 && ok[r]) rs[mr[r]] = sqrtf(t[r]); }
	v_add_f32_e32 v132, v132, v136
	v_add_f32_e32 v134, v134, v137
	ds_bpermute_b32 v136, v188, v132
	ds_bpermute_b32 v137, v188, v134
	s_waitcnt lgkmcnt(0)
	v_add_f32_e32 v132, v132, v136
	v_add_f32_e32 v134, v134, v137
	v_fmamk_f32 v164, v132, 0x3a800000, v138
	v_fmamk_f32 v167, v134, 0x3a800000, v138
	s_nop 0
	v_rsq_f32_e32 v132, v164
	v_rsq_f32_e32 v134, v167
	v_sqrt_f32_e32 v165, v164
	v_sqrt_f32_e32 v168, v167
	s_nop 1
	v_pk_mul_f32 v[140:141], v[96:97], v[132:133] op_sel_hi:[1,0]
	v_cvt_pk_bf16_f32 v148, v140, v141
	v_pk_mul_f32 v[142:143], v[98:99], v[132:133] op_sel_hi:[1,0]
	v_cvt_pk_bf16_f32 v149, v142, v143
	v_pk_mul_f32 v[144:145], v[100:101], v[132:133] op_sel_hi:[1,0]
	v_cvt_pk_bf16_f32 v150, v144, v145
	v_pk_mul_f32 v[146:147], v[102:103], v[132:133] op_sel_hi:[1,0]
	v_cvt_pk_bf16_f32 v151, v146, v147
	v_pk_mul_f32 v[140:141], v[104:105], v[132:133] op_sel_hi:[1,0]
	v_cvt_pk_bf16_f32 v152, v140, v141
	v_pk_mul_f32 v[142:143], v[106:107], v[132:133] op_sel_hi:[1,0]
	v_cvt_pk_bf16_f32 v153, v142, v143
	v_pk_mul_f32 v[144:145], v[108:109], v[132:133] op_sel_hi:[1,0]
	v_cvt_pk_bf16_f32 v154, v144, v145
	v_pk_mul_f32 v[146:147], v[110:111], v[132:133] op_sel_hi:[1,0]
	v_cvt_pk_bf16_f32 v155, v146, v147
	global_store_dwordx2 v173, v[148:149], s[98:99]
	global_store_dwordx2 v173, v[150:151], s[98:99] offset:512
	global_store_dwordx2 v173, v[152:153], s[98:99] offset:1024
	global_store_dwordx2 v173, v[154:155], s[98:99] offset:1536
	v_add_u32_e32 v173, 0x400000, v173
	v_pk_mul_f32 v[140:141], v[112:113], v[134:135] op_sel_hi:[1,0]
	v_cvt_pk_bf16_f32 v156, v140, v141
	v_pk_mul_f32 v[142:143], v[114:115], v[134:135] op_sel_hi:[1,0]
	v_cvt_pk_bf16_f32 v157, v142, v143
	v_pk_mul_f32 v[144:145], v[116:117], v[134:135] op_sel_hi:[1,0]
	v_cvt_pk_bf16_f32 v158, v144, v145
	v_pk_mul_f32 v[146:147], v[118:119], v[134:135] op_sel_hi:[1,0]
	v_cvt_pk_bf16_f32 v159, v146, v147
	v_pk_mul_f32 v[140:141], v[120:121], v[134:135] op_sel_hi:[1,0]
	v_cvt_pk_bf16_f32 v160, v140, v141
	v_pk_mul_f32 v[142:143], v[122:123], v[134:135] op_sel_hi:[1,0]
	v_cvt_pk_bf16_f32 v161, v142, v143
	v_pk_mul_f32 v[144:145], v[124:125], v[134:135] op_sel_hi:[1,0]
	v_cvt_pk_bf16_f32 v162, v144, v145
	v_pk_mul_f32 v[146:147], v[126:127], v[134:135] op_sel_hi:[1,0]
	v_cvt_pk_bf16_f32 v163, v146, v147
	global_store_dwordx2 v173, v[156:157], s[98:99]
	global_store_dwordx2 v173, v[158:159], s[98:99] offset:512
	global_store_dwordx2 v173, v[160:161], s[98:99] offset:1024
	global_store_dwordx2 v173, v[162:163], s[98:99] offset:1536
	v_add_u32_e32 v173, 0x400000, v173
	v_add_u32_e32 v166, -1, v165
	v_fma_f32 v140, -v166, v165, v164
	v_cmp_ge_f32_e32 vcc, 0, v140
	v_add_u32_e32 v141, 1, v165
	v_cndmask_b32_e32 v166, v165, v166, vcc
	v_fma_f32 v140, -v141, v165, v164
	v_cmp_lt_f32_e32 vcc, 0, v140
	s_nop 1
	v_cndmask_b32_e32 v165, v166, v141, vcc
	v_add_u32_e32 v169, -1, v168
	v_fma_f32 v142, -v169, v168, v167
	v_cmp_ge_f32_e32 vcc, 0, v142
	v_add_u32_e32 v143, 1, v168
	v_cndmask_b32_e32 v169, v168, v169, vcc
	v_fma_f32 v142, -v143, v168, v167
	v_cmp_lt_f32_e32 vcc, 0, v142
	s_nop 1
	v_cndmask_b32_e32 v168, v169, v143, vcc
	s_mov_b64 exec, 1
	global_store_dword v174, v165, s[98:99]
	v_add_u32_e32 v174, 0x2000, v174
	global_store_dword v174, v168, s[98:99]
	v_add_u32_e32 v174, 0x2000, v174
	s_mov_b64 exec, -1
	s_waitcnt vmcnt(33)
	v_lshlrev_b32_e32 v96, 16, v56
	v_and_b32_e32 v97, 0xffff0000, v56
	v_lshlrev_b32_e32 v98, 16, v57
	v_and_b32_e32 v99, 0xffff0000, v57
	v_lshlrev_b32_e32 v100, 16, v58
	v_and_b32_e32 v101, 0xffff0000, v58
	v_lshlrev_b32_e32 v102, 16, v59
	v_and_b32_e32 v103, 0xffff0000, v59
	v_lshlrev_b32_e32 v104, 16, v60
	v_and_b32_e32 v105, 0xffff0000, v60
	v_lshlrev_b32_e32 v106, 16, v61
	v_and_b32_e32 v107, 0xffff0000, v61
	v_lshlrev_b32_e32 v108, 16, v62
	v_and_b32_e32 v109, 0xffff0000, v62
	v_lshlrev_b32_e32 v110, 16, v63
	v_and_b32_e32 v111, 0xffff0000, v63
	v_pk_mul_f32 v[128:129], v[96:97], v[96:97]
	v_pk_fma_f32 v[128:129], v[98:99], v[98:99], v[128:129]
	v_pk_fma_f32 v[128:129], v[100:101], v[100:101], v[128:129]
	v_pk_fma_f32 v[128:129], v[102:103], v[102:103], v[128:129]
	v_pk_fma_f32 v[128:129], v[104:105], v[104:105], v[128:129]
	v_pk_fma_f32 v[128:129], v[106:107], v[106:107], v[128:129]
	v_pk_fma_f32 v[128:129], v[108:109], v[108:109], v[128:129]
	v_pk_fma_f32 v[128:129], v[110:111], v[110:111], v[128:129]
	s_nop 0
	v_add_f32_e32 v128, v128, v129
	s_waitcnt vmcnt(24)
	v_lshlrev_b32_e32 v112, 16, v64
	v_and_b32_e32 v113, 0xffff0000, v64
	v_lshlrev_b32_e32 v114, 16, v65
	v_and_b32_e32 v115, 0xffff0000, v65
	v_lshlrev_b32_e32 v116, 16, v66
	v_and_b32_e32 v117, 0xffff0000, v66
	v_lshlrev_b32_e32 v118, 16, v67
	v_and_b32_e32 v119, 0xffff0000, v67
	v_lshlrev_b32_e32 v120, 16, v68
	v_and_b32_e32 v121, 0xffff0000, v68
	v_lshlrev_b32_e32 v122, 16, v69
	v_and_b32_e32 v123, 0xffff0000, v69
	v_lshlrev_b32_e32 v124, 16, v70
	v_and_b32_e32 v125, 0xffff0000, v70
	v_lshlrev_b32_e32 v126, 16, v71
	v_and_b32_e32 v127, 0xffff0000, v71
	v_pk_mul_f32 v[130:131], v[112:113], v[112:113]
	v_pk_fma_f32 v[130:131], v[114:115], v[114:115], v[130:131]
	v_pk_fma_f32 v[130:131], v[116:117], v[116:117], v[130:131]
	v_pk_fma_f32 v[130:131], v[118:119], v[118:119], v[130:131]
	v_pk_fma_f32 v[130:131], v[120:121], v[120:121], v[130:131]
	v_pk_fma_f32 v[130:131], v[122:123], v[122:123], v[130:131]
	v_pk_fma_f32 v[130:131], v[124:125], v[124:125], v[130:131]
	v_pk_fma_f32 v[130:131], v[126:127], v[126:127], v[130:131]
	s_nop 0
	v_add_f32_e32 v130, v130, v131
	s_nop 1
	v_add_f32_dpp v128, v128, v128 quad_perm:[1,0,3,2] row_mask:0xf bank_mask:0xf
	v_add_f32_dpp v130, v130, v130 quad_perm:[1,0,3,2] row_mask:0xf bank_mask:0xf
	s_nop 0
	v_add_f32_dpp v128, v128, v128 quad_perm:[2,3,0,1] row_mask:0xf bank_mask:0xf
	v_add_f32_dpp v130, v130, v130 quad_perm:[2,3,0,1] row_mask:0xf bank_mask:0xf
	s_nop 0
	v_add_f32_dpp v128, v128, v128 row_half_mirror row_mask:0xf bank_mask:0xf
	v_add_f32_dpp v130, v130, v130 row_half_mirror row_mask:0xf bank_mask:0xf
	s_nop 0
	v_add_f32_dpp v128, v128, v128 row_mirror row_mask:0xf bank_mask:0xf
	v_add_f32_dpp v130, v130, v130 row_mirror row_mask:0xf bank_mask:0xf
	s_nop 0
	ds_bpermute_b32 v136, v187, v128
	ds_bpermute_b32 v137, v187, v130
	s_waitcnt lgkmcnt(0)
;     __device__ __forceinline__ float* out() const { return (float*)karg_in(33); }
; __device__ __forceinline__ float ssq4(v4f v) { return (v.x * v.x + v.y * v.y) + (v.z * v.z + v.w * v.w); }
; template <int R, bool BASE_F32, bool OUT_F32>
; __device__ __forceinline__ void rows_res(const Ctx& C, int m0, int stride, int mx, const float* gpost, float scale, int lane) {
;     ...
;     for (int r = 0; r < R; ++r) r1[r] = rsqrtf(wave_sum(r1[r]) * (1.f / DM) + EPS) * scale;
; #pragma unroll
;     for (int j = 0; j < 4; ++j) { const v4f gp = ld4_f32(gpost + 4 * lane + 256 * j);
; #pragma unroll
;         for (int r = 0; r < R; ++r) d[r][j] = b[r][j] + d[r][j] * r1[r] * gp; }
;     if (OUT_F32) { float* Y = C.out();
; #pragma unroll
;         for (int r = 0; r < R; ++r)
; #pragma unroll
;             for (int j = 0; j < 4; ++j) if (ok[r]) *(v4f*)(Y + (size_t)mr[r] * DM + 4 * lane + 256 * j) = d[r][j];
;     } else { float* rs = C.RS(); float t[R];
; #pragma unroll
;         for (int r = 0; r < R; ++r) { float s = 0.f;
; #pragma unroll
;             for (int j = 0; j < 4; ++j) s += ssq4(d[r][j]);
;             t[r] = s; }
; #pragma unroll
;         for (int r = 0; r < R; ++r) t[r] = wave_sum(t[r]) * (1.f / DM) + EPS;
	v_add_f32_e32 v128, v128, v136
	v_add_f32_e32 v130, v130, v137
	ds_bpermute_b32 v136, v188, v128
	ds_bpermute_b32 v137, v188, v130
	s_waitcnt lgkmcnt(0)
	v_add_f32_e32 v128, v128, v136
	v_add_f32_e32 v130, v130, v137
	v_fmamk_f32 v128, v128, 0x3a800000, v138
	v_fmamk_f32 v130, v130, 0x3a800000, v138
	s_nop 0
	v_rsq_f32_e32 v128, v128
	v_rsq_f32_e32 v130, v130
	s_nop 1
	v_mul_f32_e32 v128, 0.5, v128
	v_mul_f32_e32 v130, 0.5, v130
	s_waitcnt vmcnt(20)
	v_pk_mul_f32 v[96:97], v[128:129], v[96:97] op_sel_hi:[0,1]
	v_pk_mul_f32 v[98:99], v[128:129], v[98:99] op_sel_hi:[0,1]
	v_pk_mul_f32 v[100:101], v[128:129], v[100:101] op_sel_hi:[0,1]
	v_pk_mul_f32 v[102:103], v[128:129], v[102:103] op_sel_hi:[0,1]
	v_pk_mul_f32 v[104:105], v[128:129], v[104:105] op_sel_hi:[0,1]
	v_pk_mul_f32 v[106:107], v[128:129], v[106:107] op_sel_hi:[0,1]
	v_pk_mul_f32 v[108:109], v[128:129], v[108:109] op_sel_hi:[0,1]
	v_pk_mul_f32 v[110:111], v[128:129], v[110:111] op_sel_hi:[0,1]
	v_pk_mul_f32 v[96:97], v[96:97], v[192:193]
	v_pk_mul_f32 v[98:99], v[98:99], v[194:195]
	v_pk_mul_f32 v[100:101], v[100:101], v[196:197]
	v_pk_mul_f32 v[102:103], v[102:103], v[198:199]
	v_pk_mul_f32 v[104:105], v[104:105], v[200:201]
	v_pk_mul_f32 v[106:107], v[106:107], v[202:203]
	v_pk_mul_f32 v[108:109], v[108:109], v[204:205]
	v_pk_mul_f32 v[110:111], v[110:111], v[206:207]
	v_lshlrev_b32_e32 v56, 16, v72
	v_and_b32_e32 v57, 0xffff0000, v72
	v_lshlrev_b32_e32 v58, 16, v73
	v_and_b32_e32 v59, 0xffff0000, v73
	v_lshlrev_b32_e32 v60, 16, v74
	v_and_b32_e32 v61, 0xffff0000, v74
	v_lshlrev_b32_e32 v62, 16, v75
	v_and_b32_e32 v63, 0xffff0000, v75
	v_pk_fma_f32 v[96:97], v[88:89], v[56:57], v[96:97] op_sel_hi:[0,1,1]
	v_pk_fma_f32 v[98:99], v[88:89], v[58:59], v[98:99] op_sel_hi:[0,1,1]
	v_pk_fma_f32 v[100:101], v[88:89], v[60:61], v[100:101] op_sel_hi:[0,1,1]
	v_pk_fma_f32 v[102:103], v[88:89], v[62:63], v[102:103] op_sel_hi:[0,1,1]
	v_lshlrev_b32_e32 v56, 16, v76
	v_and_b32_e32 v57, 0xffff0000, v76
	v_lshlrev_b32_e32 v58, 16, v77
	v_and_b32_e32 v59, 0xffff0000, v77
	v_lshlrev_b32_e32 v60, 16, v78
	v_and_b32_e32 v61, 0xffff0000, v78
	v_lshlrev_b32_e32 v62, 16, v79
	v_and_b32_e32 v63, 0xffff0000, v79
	v_pk_fma_f32 v[104:105], v[88:89], v[56:57], v[104:105] op_sel_hi:[0,1,1]
	v_pk_fma_f32 v[106:107], v[88:89], v[58:59], v[106:107] op_sel_hi:[0,1,1]
	v_pk_fma_f32 v[108:109], v[88:89], v[60:61], v[108:109] op_sel_hi:[0,1,1]
	v_pk_fma_f32 v[110:111], v[88:89], v[62:63], v[110:111] op_sel_hi:[0,1,1]
	v_pk_mul_f32 v[132:133], v[96:97], v[96:97]
	v_pk_fma_f32 v[132:133], v[98:99], v[98:99], v[132:133]
	v_pk_fma_f32 v[132:133], v[100:101], v[100:101], v[132:133]
	v_pk_fma_f32 v[132:133], v[102:103], v[102:103], v[132:133]
	v_pk_fma_f32 v[132:133], v[104:105], v[104:105], v[132:133]
	v_pk_fma_f32 v[132:133], v[106:107], v[106:107], v[132:133]
	v_pk_fma_f32 v[132:133], v[108:109], v[108:109], v[132:133]
	v_pk_fma_f32 v[132:133], v[110:111], v[110:111], v[132:133]
	s_nop 0
	v_add_f32_e32 v132, v132, v133
	v_pk_mul_f32 v[112:113], v[130:131], v[112:113] op_sel_hi:[0,1]
	v_pk_mul_f32 v[114:115], v[130:131], v[114:115] op_sel_hi:[0,1]
	v_pk_mul_f32 v[116:117], v[130:131], v[116:117] op_sel_hi:[0,1]
	v_pk_mul_f32 v[118:119], v[130:131], v[118:119] op_sel_hi:[0,1]
	v_pk_mul_f32 v[120:121], v[130:131], v[120:121] op_sel_hi:[0,1]
	v_pk_mul_f32 v[122:123], v[130:131], v[122:123] op_sel_hi:[0,1]
	v_pk_mul_f32 v[124:125], v[130:131], v[124:125] op_sel_hi:[0,1]
	v_pk_mul_f32 v[126:127], v[130:131], v[126:127] op_sel_hi:[0,1]
	v_pk_mul_f32 v[112:113], v[112:113], v[192:193]
	v_pk_mul_f32 v[114:115], v[114:115], v[194:195]
	v_pk_mul_f32 v[116:117], v[116:117], v[196:197]
	v_pk_mul_f32 v[118:119], v[118:119], v[198:199]
	v_pk_mul_f32 v[120:121], v[120:121], v[200:201]
	v_pk_mul_f32 v[122:123], v[122:123], v[202:203]
	v_pk_mul_f32 v[124:125], v[124:125], v[204:205]
	v_pk_mul_f32 v[126:127], v[126:127], v[206:207]
	v_lshlrev_b32_e32 v64, 16, v80
	v_and_b32_e32 v65, 0xffff0000, v80
	v_lshlrev_b32_e32 v66, 16, v81
	v_and_b32_e32 v67, 0xffff0000, v81
	v_lshlrev_b32_e32 v68, 16, v82
	v_and_b32_e32 v69, 0xffff0000, v82
	v_lshlrev_b32_e32 v70, 16, v83
	v_and_b32_e32 v71, 0xffff0000, v83
	v_pk_fma_f32 v[112:113], v[90:91], v[64:65], v[112:113] op_sel_hi:[0,1,1]
	v_pk_fma_f32 v[114:115], v[90:91], v[66:67], v[114:115] op_sel_hi:[0,1,1]
	v_pk_fma_f32 v[116:117], v[90:91], v[68:69], v[116:117] op_sel_hi:[0,1,1]
	v_pk_fma_f32 v[118:119], v[90:91], v[70:71], v[118:119] op_sel_hi:[0,1,1]
	v_lshlrev_b32_e32 v64, 16, v84
	v_and_b32_e32 v65, 0xffff0000, v84
	v_lshlrev_b32_e32 v66, 16, v85
	v_and_b32_e32 v67, 0xffff0000, v85
	v_lshlrev_b32_e32 v68, 16, v86
	v_and_b32_e32 v69, 0xffff0000, v86
	v_lshlrev_b32_e32 v70, 16, v87
	v_and_b32_e32 v71, 0xffff0000, v87
	v_pk_fma_f32 v[120:121], v[90:91], v[64:65], v[120:121] op_sel_hi:[0,1,1]
	v_pk_fma_f32 v[122:123], v[90:91], v[66:67], v[122:123] op_sel_hi:[0,1,1]
	v_pk_fma_f32 v[124:125], v[90:91], v[68:69], v[124:125] op_sel_hi:[0,1,1]
	v_pk_fma_f32 v[126:127], v[90:91], v[70:71], v[126:127] op_sel_hi:[0,1,1]
	v_pk_mul_f32 v[134:135], v[112:113], v[112:113]
	v_pk_fma_f32 v[134:135], v[114:115], v[114:115], v[134:135]
	v_pk_fma_f32 v[134:135], v[116:117], v[116:117], v[134:135]
	v_pk_fma_f32 v[134:135], v[118:119], v[118:119], v[134:135]
	v_pk_fma_f32 v[134:135], v[120:121], v[120:121], v[134:135]
	v_pk_fma_f32 v[134:135], v[122:123], v[122:123], v[134:135]
	v_pk_fma_f32 v[134:135], v[124:125], v[124:125], v[134:135]
	v_pk_fma_f32 v[134:135], v[126:127], v[126:127], v[134:135]
	s_nop 0
	v_add_f32_e32 v134, v134, v135
	s_nop 1
	v_add_f32_dpp v132, v132, v132 quad_perm:[1,0,3,2] row_mask:0xf bank_mask:0xf
	v_add_f32_dpp v134, v134, v134 quad_perm:[1,0,3,2] row_mask:0xf bank_mask:0xf
	s_nop 0
	v_add_f32_dpp v132, v132, v132 quad_perm:[2,3,0,1] row_mask:0xf bank_mask:0xf
	v_add_f32_dpp v134, v134, v134 quad_perm:[2,3,0,1] row_mask:0xf bank_mask:0xf
	s_nop 0
	v_add_f32_dpp v132, v132, v132 row_half_mirror row_mask:0xf bank_mask:0xf
	v_add_f32_dpp v134, v134, v134 row_half_mirror row_mask:0xf bank_mask:0xf
	s_nop 0
	v_add_f32_dpp v132, v132, v132 row_mirror row_mask:0xf bank_mask:0xf
	v_add_f32_dpp v134, v134, v134 row_mirror row_mask:0xf bank_mask:0xf
	s_nop 0
	ds_bpermute_b32 v136, v187, v132
	ds_bpermute_b32 v137, v187, v134
	s_waitcnt lgkmcnt(0)
; __device__ __forceinline__ void st4_bf16(bf16* p, v4f o) { v2u w; w.x = cvt_pk_nv(o.x, o.y); w.y = cvt_pk_nv(o.z, o.w); *(v2u*)p = w; }
; template <int R, bool BASE_F32, bool OUT_F32>
; __device__ __forceinline__ void rows_res(const Ctx& C, int m0, int stride, int mx, const float* gpost, float scale, int lane) {
;     ...
;         for (int r = 0; r < R; ++r) t[r] = wave_sum(t[r]) * (1.f / DM) + EPS;
; #pragma unroll
;         for (int r = 0; r < R; ++r) { const float rstd = rsqrtf(t[r]);
; #pragma unroll
;             for (int j = 0; j < 4; ++j) if (ok[r]) st4_bf16(XN + (size_t)mr[r] * DM + 4 * lane + 256 * j, d[r][j] * rstd);
;             if (lane == 0 && ok[r]) rs[mr[r]] = sqrtf(t[r]); }
	v_add_f32_e32 v132, v132, v136
	v_add_f32_e32 v134, v134, v137
	ds_bpermute_b32 v136, v188, v132
	ds_bpermute_b32 v137, v188, v134
	s_waitcnt lgkmcnt(0)
	v_add_f32_e32 v132, v132, v136
	v_add_f32_e32 v134, v134, v137
	v_fmamk_f32 v164, v132, 0x3a800000, v138
	v_fmamk_f32 v167, v134, 0x3a800000, v138
	s_nop 0
	v_rsq_f32_e32 v132, v164
	v_rsq_f32_e32 v134, v167
	v_sqrt_f32_e32 v165, v164
	v_sqrt_f32_e32 v168, v167
	s_nop 1
	v_pk_mul_f32 v[140:141], v[96:97], v[132:133] op_sel_hi:[1,0]
	v_cvt_pk_bf16_f32 v148, v140, v141
	v_pk_mul_f32 v[142:143], v[98:99], v[132:133] op_sel_hi:[1,0]
	v_cvt_pk_bf16_f32 v149, v142, v143
	v_pk_mul_f32 v[144:145], v[100:101], v[132:133] op_sel_hi:[1,0]
	v_cvt_pk_bf16_f32 v150, v144, v145
	v_pk_mul_f32 v[146:147], v[102:103], v[132:133] op_sel_hi:[1,0]
	v_cvt_pk_bf16_f32 v151, v146, v147
	v_pk_mul_f32 v[140:141], v[104:105], v[132:133] op_sel_hi:[1,0]
	v_cvt_pk_bf16_f32 v152, v140, v141
	v_pk_mul_f32 v[142:143], v[106:107], v[132:133] op_sel_hi:[1,0]
	v_cvt_pk_bf16_f32 v153, v142, v143
	v_pk_mul_f32 v[144:145], v[108:109], v[132:133] op_sel_hi:[1,0]
	v_cvt_pk_bf16_f32 v154, v144, v145
	v_pk_mul_f32 v[146:147], v[110:111], v[132:133] op_sel_hi:[1,0]
	v_cvt_pk_bf16_f32 v155, v146, v147
	global_store_dwordx2 v173, v[148:149], s[98:99]
	global_store_dwordx2 v173, v[150:151], s[98:99] offset:512
	global_store_dwordx2 v173, v[152:153], s[98:99] offset:1024
	global_store_dwordx2 v173, v[154:155], s[98:99] offset:1536
	v_add_u32_e32 v173, 0x400000, v173
	v_pk_mul_f32 v[140:141], v[112:113], v[134:135] op_sel_hi:[1,0]
	v_cvt_pk_bf16_f32 v156, v140, v141
	v_pk_mul_f32 v[142:143], v[114:115], v[134:135] op_sel_hi:[1,0]
	v_cvt_pk_bf16_f32 v157, v142, v143
	v_pk_mul_f32 v[144:145], v[116:117], v[134:135] op_sel_hi:[1,0]
	v_cvt_pk_bf16_f32 v158, v144, v145
	v_pk_mul_f32 v[146:147], v[118:119], v[134:135] op_sel_hi:[1,0]
	v_cvt_pk_bf16_f32 v159, v146, v147
	v_pk_mul_f32 v[140:141], v[120:121], v[134:135] op_sel_hi:[1,0]
	v_cvt_pk_bf16_f32 v160, v140, v141
	v_pk_mul_f32 v[142:143], v[122:123], v[134:135] op_sel_hi:[1,0]
	v_cvt_pk_bf16_f32 v161, v142, v143
	v_pk_mul_f32 v[144:145], v[124:125], v[134:135] op_sel_hi:[1,0]
	v_cvt_pk_bf16_f32 v162, v144, v145
	v_pk_mul_f32 v[146:147], v[126:127], v[134:135] op_sel_hi:[1,0]
	v_cvt_pk_bf16_f32 v163, v146, v147
	global_store_dwordx2 v173, v[156:157], s[98:99]
	global_store_dwordx2 v173, v[158:159], s[98:99] offset:512
	global_store_dwordx2 v173, v[160:161], s[98:99] offset:1024
	global_store_dwordx2 v173, v[162:163], s[98:99] offset:1536
	v_add_u32_e32 v173, 0x400000, v173
	v_add_u32_e32 v166, -1, v165
	v_fma_f32 v140, -v166, v165, v164
	v_cmp_ge_f32_e32 vcc, 0, v140
	v_add_u32_e32 v141, 1, v165
	v_cndmask_b32_e32 v166, v165, v166, vcc
	v_fma_f32 v140, -v141, v165, v164
	v_cmp_lt_f32_e32 vcc, 0, v140
	s_nop 1
	v_cndmask_b32_e32 v165, v166, v141, vcc
	v_add_u32_e32 v169, -1, v168
	v_fma_f32 v142, -v169, v168, v167
	v_cmp_ge_f32_e32 vcc, 0, v142
	v_add_u32_e32 v143, 1, v168
	v_cndmask_b32_e32 v169, v168, v169, vcc
	v_fma_f32 v142, -v143, v168, v167
	v_cmp_lt_f32_e32 vcc, 0, v142
	s_nop 1
	v_cndmask_b32_e32 v168, v169, v143, vcc
	s_mov_b64 exec, 1
	global_store_dword v174, v165, s[98:99]
	v_add_u32_e32 v174, 0x2000, v174
	global_store_dword v174, v168, s[98:99]
	v_add_u32_e32 v174, 0x2000, v174
	s_mov_b64 exec, -1
	s_branch .LBB0_385
	v_mov_b32_e32 v3, v1
	s_mov_b32 s0, 0x358637bd
	s_waitcnt lgkmcnt(0)
	v_lshl_add_u64 v[4:5], s[14:15], 0, v[2:3]
	s_mov_b64 s[12:13], 0x7100000
	s_mov_b64 s[16:17], 0x3000000
	v_mov_b32_e32 v3, 0x2a80000
	s_mov_b32 s18, 0x3a800000
	v_mov_b64_e32 v[6:7], s[0:1]
	s_mov_b32 s19, 0x800000
	v_mov_b32_e32 v37, 0x358637bd
	s_mov_b32 s43, 0xf800000
	v_mov_b32_e32 v148, 0x260
	s_mov_b32 s20, s42
	v_readlane_b32 s54, v232, 5
	s_branch .LBB0_369

;     __device__ __forceinline__ const float* in(int i) const { return karg_in(i); }
; __device__ __forceinline__ const float* xrow_ptr(const Ctx& C, int row) { return row < MPROMPT ? C.in(0) + (size_t)row * DM : C.in(1) + (size_t)(row - MPROMPT) * DM; }
; __device__ __forceinline__ v4f ld4_bf16(const bf16* p) { const v2u w = *(const v2u*)p; return (v4f){bf_lo(w.x), bf_hi(w.x), bf_lo(w.y), bf_hi(w.y)}; }
; __device__ __forceinline__ float ssq4(v4f v) { return (v.x * v.x + v.y * v.y) + (v.z * v.z + v.w * v.w); }
; #define FTID const int ftid_ = fresh_tid()
; template <int R, bool BASE_F32, bool OUT_F32>
; __device__ __forceinline__ void rows_res(const Ctx& C, int m0, int stride, int mx, const float* gpost, float scale, int lane) {
;     v4f d[R][4], b[R][4]; int mr[R]; bool ok[R]; float r1[R];
;     const bf16* D = C.D(); bf16* XN = C.XN();
; #pragma unroll
;     for (int r = 0; r < R; ++r) { mr[r] = (r == 4) ? mx : m0 + r * stride; ok[r] = (r == 4) ? (mx < M) : (mr[r] < MPROMPT); const int mm = ok[r] ? mr[r] : 0;
; #pragma unroll
;         for (int j = 0; j < 4; ++j) d[r][j] = ld4_bf16(D + (size_t)mm * DM + 4 * lane + 256 * j);
;         if (BASE_F32) { const float* x = xrow_ptr(C, mm);
; #pragma unroll
;             for (int j = 0; j < 4; ++j) b[r][j] = ld4_f32(x + 4 * lane + 256 * j);
;         } else { const float inv = C.RS()[mm];
; #pragma unroll
;             for (int j = 0; j < 4; ++j) b[r][j] = ld4_bf16(XN + (size_t)mm * DM + 4 * lane + 256 * j) * inv;
;         } }
; #pragma unroll
;     for (int r = 0; r < R; ++r) { float s = 0.f;
; #pragma unroll
;         for (int j = 0; j < 4; ++j) s += ssq4(d[r][j]);
;         r1[r] = s; }
; #pragma unroll
;     for (int r = 0; r < R; ++r) r1[r] = rsqrtf(wave_sum(r1[r]) * (1.f / DM) + EPS) * scale;
; __global__ void __launch_bounds__(NTHREADS, 2) fwd_kernel(Args args) {
;     ...
;     { FTID; const float* gp = C.in(27); { const int gw_ = GWV, ngw_ = NGWV, nit = (MPROMPT + 4 * ngw_ - 1) / (4 * ngw_);
;       for (int it = 0; it < nit - 1; ++it) rows_res<4, false, false>(C, gw_ + 4 * it * ngw_, ngw_, M, gp, 1.0f, LANE);
.LBB0_994:
	s_or_b64 exec, exec, s[10:11]
	s_waitcnt lgkmcnt(0)
	v_mov_b32_e32 v0, v182
	s_mov_b64 s[0:1], s[80:81]
	s_barrier
	s_load_dwordx2 s[16:17], s[0:1], 0xd8
	v_readfirstlane_b32 s0, v0
	v_and_b32_e32 v189, 63, v0
	s_ashr_i32 s47, s0, 6
	v_readlane_b32 s0, v232, 0
	v_lshlrev_b32_e32 v0, 2, v189
	s_add_i32 s23, s47, s0
	v_mov_b32_e32 v1, 0
	s_and_b64 vcc, exec, s[6:7]
	v_lshlrev_b32_e32 v2, 2, v0
	v_cmp_ne_u32_e64 s[10:11], 0, v189
	v_lshlrev_b32_e32 v0, 1, v0
	s_load_dwordx2 s[98:99], s[80:81], 0x110
	s_load_dwordx2 s[100:101], s[80:81], 0xd8
	v_and_b32_e32 v176, 63, v182
	v_lshlrev_b32_e32 v170, 3, v176
	s_lshl_b32 vcc_lo, s23, 11
	v_add_u32_e32 v170, vcc_lo, v170
	v_add_u32_e32 v171, 0x3000000, v170
	v_add_u32_e32 v170, 0x7100000, v170
	v_mov_b32_e32 v173, v171
	s_lshl_b32 vcc_lo, s23, 2
	v_mov_b32_e32 v172, 0x2a80000
	v_add_u32_e32 v172, vcc_lo, v172
	v_mov_b32_e32 v174, v172
	v_lshlrev_b32_e32 v176, 4, v176
	v_mov_b32_e32 v138, 0x358637bd
	s_waitcnt lgkmcnt(0)
	global_load_dwordx4 v[192:195], v176, s[100:101]
	global_load_dwordx4 v[196:199], v176, s[100:101] offset:1024
	global_load_dwordx4 v[200:203], v176, s[100:101] offset:2048
	global_load_dwordx4 v[204:207], v176, s[100:101] offset:3072
	global_load_dword v52, v172, s[98:99]
	global_load_dwordx2 v[20:21], v170, s[98:99]
	global_load_dwordx2 v[22:23], v170, s[98:99] offset:512
	global_load_dwordx2 v[24:25], v170, s[98:99] offset:1024
	global_load_dwordx2 v[26:27], v170, s[98:99] offset:1536
	global_load_dwordx2 v[36:37], v171, s[98:99]
	global_load_dwordx2 v[38:39], v171, s[98:99] offset:512
	global_load_dwordx2 v[40:41], v171, s[98:99] offset:1024
	global_load_dwordx2 v[42:43], v171, s[98:99] offset:1536
	v_add_u32_e32 v170, 0x400000, v170
	v_add_u32_e32 v171, 0x400000, v171
	v_add_u32_e32 v172, 0x2000, v172
	global_load_dword v54, v172, s[98:99]
	global_load_dwordx2 v[28:29], v170, s[98:99]
	global_load_dwordx2 v[30:31], v170, s[98:99] offset:512
	global_load_dwordx2 v[32:33], v170, s[98:99] offset:1024
	global_load_dwordx2 v[34:35], v170, s[98:99] offset:1536
	global_load_dwordx2 v[44:45], v171, s[98:99]
	global_load_dwordx2 v[46:47], v171, s[98:99] offset:512
	global_load_dwordx2 v[48:49], v171, s[98:99] offset:1024
	global_load_dwordx2 v[50:51], v171, s[98:99] offset:1536
	v_add_u32_e32 v170, 0x400000, v170
	v_add_u32_e32 v171, 0x400000, v171
	v_add_u32_e32 v172, 0x2000, v172
	global_load_dword v88, v172, s[98:99]
	global_load_dwordx2 v[56:57], v170, s[98:99]
	global_load_dwordx2 v[58:59], v170, s[98:99] offset:512
	global_load_dwordx2 v[60:61], v170, s[98:99] offset:1024
	global_load_dwordx2 v[62:63], v170, s[98:99] offset:1536
	global_load_dwordx2 v[72:73], v171, s[98:99]
	global_load_dwordx2 v[74:75], v171, s[98:99] offset:512
	global_load_dwordx2 v[76:77], v171, s[98:99] offset:1024
	global_load_dwordx2 v[78:79], v171, s[98:99] offset:1536
	v_add_u32_e32 v170, 0x400000, v170
	v_add_u32_e32 v171, 0x400000, v171
	v_add_u32_e32 v172, 0x2000, v172
	global_load_dword v90, v172, s[98:99]
	global_load_dwordx2 v[64:65], v170, s[98:99]
	global_load_dwordx2 v[66:67], v170, s[98:99] offset:512
	global_load_dwordx2 v[68:69], v170, s[98:99] offset:1024
	global_load_dwordx2 v[70:71], v170, s[98:99] offset:1536
	global_load_dwordx2 v[80:81], v171, s[98:99]
	global_load_dwordx2 v[82:83], v171, s[98:99] offset:512
	global_load_dwordx2 v[84:85], v171, s[98:99] offset:1024
	global_load_dwordx2 v[86:87], v171, s[98:99] offset:1536
	v_add_u32_e32 v170, 0x400000, v170
	v_add_u32_e32 v171, 0x400000, v171
	v_add_u32_e32 v172, 0x2000, v172
	s_waitcnt vmcnt(31)
	v_lshlrev_b32_e32 v96, 16, v20
	v_and_b32_e32 v97, 0xffff0000, v20
	v_lshlrev_b32_e32 v98, 16, v21
	v_and_b32_e32 v99, 0xffff0000, v21
	v_lshlrev_b32_e32 v100, 16, v22
	v_and_b32_e32 v101, 0xffff0000, v22
	v_lshlrev_b32_e32 v102, 16, v23
	v_and_b32_e32 v103, 0xffff0000, v23
	v_lshlrev_b32_e32 v104, 16, v24
	v_and_b32_e32 v105, 0xffff0000, v24
	v_lshlrev_b32_e32 v106, 16, v25
	v_and_b32_e32 v107, 0xffff0000, v25
	v_lshlrev_b32_e32 v108, 16, v26
	v_and_b32_e32 v109, 0xffff0000, v26
	v_lshlrev_b32_e32 v110, 16, v27
	v_and_b32_e32 v111, 0xffff0000, v27
	v_pk_mul_f32 v[128:129], v[96:97], v[96:97]
	v_pk_fma_f32 v[128:129], v[98:99], v[98:99], v[128:129]
	v_pk_fma_f32 v[128:129], v[100:101], v[100:101], v[128:129]
	v_pk_fma_f32 v[128:129], v[102:103], v[102:103], v[128:129]
	v_pk_fma_f32 v[128:129], v[104:105], v[104:105], v[128:129]
	v_pk_fma_f32 v[128:129], v[106:107], v[106:107], v[128:129]
	v_pk_fma_f32 v[128:129], v[108:109], v[108:109], v[128:129]
	v_pk_fma_f32 v[128:129], v[110:111], v[110:111], v[128:129]
	s_nop 0
	v_add_f32_e32 v128, v128, v129
	s_waitcnt vmcnt(22)
	v_lshlrev_b32_e32 v112, 16, v28
	v_and_b32_e32 v113, 0xffff0000, v28
	v_lshlrev_b32_e32 v114, 16, v29
	v_and_b32_e32 v115, 0xffff0000, v29
	v_lshlrev_b32_e32 v116, 16, v30
	v_and_b32_e32 v117, 0xffff0000, v30
	v_lshlrev_b32_e32 v118, 16, v31
	v_and_b32_e32 v119, 0xffff0000, v31
	v_lshlrev_b32_e32 v120, 16, v32
	v_and_b32_e32 v121, 0xffff0000, v32
	v_lshlrev_b32_e32 v122, 16, v33
	v_and_b32_e32 v123, 0xffff0000, v33
	v_lshlrev_b32_e32 v124, 16, v34
	v_and_b32_e32 v125, 0xffff0000, v34
	v_lshlrev_b32_e32 v126, 16, v35
	v_and_b32_e32 v127, 0xffff0000, v35
	v_pk_mul_f32 v[130:131], v[112:113], v[112:113]
	v_pk_fma_f32 v[130:131], v[114:115], v[114:115], v[130:131]
	v_pk_fma_f32 v[130:131], v[116:117], v[116:117], v[130:131]
	v_pk_fma_f32 v[130:131], v[118:119], v[118:119], v[130:131]
	v_pk_fma_f32 v[130:131], v[120:121], v[120:121], v[130:131]
	v_pk_fma_f32 v[130:131], v[122:123], v[122:123], v[130:131]
	v_pk_fma_f32 v[130:131], v[124:125], v[124:125], v[130:131]
	v_pk_fma_f32 v[130:131], v[126:127], v[126:127], v[130:131]
	s_nop 0
	v_add_f32_e32 v130, v130, v131
	s_nop 1
	v_add_f32_dpp v128, v128, v128 quad_perm:[1,0,3,2] row_mask:0xf bank_mask:0xf
	v_add_f32_dpp v130, v130, v130 quad_perm:[1,0,3,2] row_mask:0xf bank_mask:0xf
	s_nop 0
	v_add_f32_dpp v128, v128, v128 quad_perm:[2,3,0,1] row_mask:0xf bank_mask:0xf
	v_add_f32_dpp v130, v130, v130 quad_perm:[2,3,0,1] row_mask:0xf bank_mask:0xf
	s_nop 0
	v_add_f32_dpp v128, v128, v128 row_half_mirror row_mask:0xf bank_mask:0xf
	v_add_f32_dpp v130, v130, v130 row_half_mirror row_mask:0xf bank_mask:0xf
	s_nop 0
	v_add_f32_dpp v128, v128, v128 row_mirror row_mask:0xf bank_mask:0xf
	v_add_f32_dpp v130, v130, v130 row_mirror row_mask:0xf bank_mask:0xf
	s_nop 0
	ds_bpermute_b32 v136, v187, v128
	ds_bpermute_b32 v137, v187, v130
	s_waitcnt lgkmcnt(0)
;     __device__ __forceinline__ float* out() const { return (float*)karg_in(33); }
; __device__ __forceinline__ const float* xrow_ptr(const Ctx& C, int row) { return row < MPROMPT ? C.in(0) + (size_t)row * DM : C.in(1) + (size_t)(row - MPROMPT) * DM; }
; __device__ __forceinline__ v4f ld4_bf16(const bf16* p) { const v2u w = *(const v2u*)p; return (v4f){bf_lo(w.x), bf_hi(w.x), bf_lo(w.y), bf_hi(w.y)}; }
; __device__ __forceinline__ float ssq4(v4f v) { return (v.x * v.x + v.y * v.y) + (v.z * v.z + v.w * v.w); }
; template <int R, bool BASE_F32, bool OUT_F32>
; __device__ __forceinline__ void rows_res(const Ctx& C, int m0, int stride, int mx, const float* gpost, float scale, int lane) {
;     ...
;     for (int r = 0; r < R; ++r) { mr[r] = (r == 4) ? mx : m0 + r * stride; ok[r] = (r == 4) ? (mx < M) : (mr[r] < MPROMPT); const int mm = ok[r] ? mr[r] : 0;
; #pragma unroll
;         for (int j = 0; j < 4; ++j) d[r][j] = ld4_bf16(D + (size_t)mm * DM + 4 * lane + 256 * j);
;         if (BASE_F32) { const float* x = xrow_ptr(C, mm);
; #pragma unroll
;             for (int j = 0; j < 4; ++j) b[r][j] = ld4_f32(x + 4 * lane + 256 * j);
;         } else { const float inv = C.RS()[mm];
; #pragma unroll
;             for (int j = 0; j < 4; ++j) b[r][j] = ld4_bf16(XN + (size_t)mm * DM + 4 * lane + 256 * j) * inv;
;         } }
; #pragma unroll
;     for (int r = 0; r < R; ++r) { float s = 0.f;
; #pragma unroll
;         for (int j = 0; j < 4; ++j) s += ssq4(d[r][j]);
;         r1[r] = s; }
; #pragma unroll
;     for (int r = 0; r < R; ++r) r1[r] = rsqrtf(wave_sum(r1[r]) * (1.f / DM) + EPS) * scale;
; #pragma unroll
;     for (int j = 0; j < 4; ++j) { const v4f gp = ld4_f32(gpost + 4 * lane + 256 * j);
; #pragma unroll
;         for (int r = 0; r < R; ++r) d[r][j] = b[r][j] + d[r][j] * r1[r] * gp; }
;     if (OUT_F32) { float* Y = C.out();
; #pragma unroll
;         for (int r = 0; r < R; ++r)
; #pragma unroll
;             for (int j = 0; j < 4; ++j) if (ok[r]) *(v4f*)(Y + (size_t)mr[r] * DM + 4 * lane + 256 * j) = d[r][j];
;     } else { float* rs = C.RS(); float t[R];
; #pragma unroll
;         for (int r = 0; r < R; ++r) { float s = 0.f;
; #pragma unroll
;             for (int j = 0; j < 4; ++j) s += ssq4(d[r][j]);
;             t[r] = s; }
; #pragma unroll
;         for (int r = 0; r < R; ++r) t[r] = wave_sum(t[r]) * (1.f / DM) + EPS;
	v_add_f32_e32 v128, v128, v136
	v_add_f32_e32 v130, v130, v137
	ds_bpermute_b32 v136, v188, v128
	ds_bpermute_b32 v137, v188, v130
	s_waitcnt lgkmcnt(0)
	v_add_f32_e32 v128, v128, v136
	v_add_f32_e32 v130, v130, v137
	v_fmamk_f32 v128, v128, 0x3a800000, v138
	v_fmamk_f32 v130, v130, 0x3a800000, v138
	s_nop 0
	v_rsq_f32_e32 v128, v128
	v_rsq_f32_e32 v130, v130
	s_nop 1
	s_waitcnt vmcnt(18)
	v_pk_mul_f32 v[96:97], v[128:129], v[96:97] op_sel_hi:[0,1]
	v_pk_mul_f32 v[98:99], v[128:129], v[98:99] op_sel_hi:[0,1]
	v_pk_mul_f32 v[100:101], v[128:129], v[100:101] op_sel_hi:[0,1]
	v_pk_mul_f32 v[102:103], v[128:129], v[102:103] op_sel_hi:[0,1]
	v_pk_mul_f32 v[104:105], v[128:129], v[104:105] op_sel_hi:[0,1]
	v_pk_mul_f32 v[106:107], v[128:129], v[106:107] op_sel_hi:[0,1]
	v_pk_mul_f32 v[108:109], v[128:129], v[108:109] op_sel_hi:[0,1]
	v_pk_mul_f32 v[110:111], v[128:129], v[110:111] op_sel_hi:[0,1]
	v_pk_mul_f32 v[96:97], v[96:97], v[192:193]
	v_pk_mul_f32 v[98:99], v[98:99], v[194:195]
	v_pk_mul_f32 v[100:101], v[100:101], v[196:197]
	v_pk_mul_f32 v[102:103], v[102:103], v[198:199]
	v_pk_mul_f32 v[104:105], v[104:105], v[200:201]
	v_pk_mul_f32 v[106:107], v[106:107], v[202:203]
	v_pk_mul_f32 v[108:109], v[108:109], v[204:205]
	v_pk_mul_f32 v[110:111], v[110:111], v[206:207]
	v_lshlrev_b32_e32 v20, 16, v36
	v_and_b32_e32 v21, 0xffff0000, v36
	v_lshlrev_b32_e32 v22, 16, v37
	v_and_b32_e32 v23, 0xffff0000, v37
	v_lshlrev_b32_e32 v24, 16, v38
	v_and_b32_e32 v25, 0xffff0000, v38
	v_lshlrev_b32_e32 v26, 16, v39
	v_and_b32_e32 v27, 0xffff0000, v39
	v_pk_fma_f32 v[96:97], v[52:53], v[20:21], v[96:97] op_sel_hi:[0,1,1]
	v_pk_fma_f32 v[98:99], v[52:53], v[22:23], v[98:99] op_sel_hi:[0,1,1]
	v_pk_fma_f32 v[100:101], v[52:53], v[24:25], v[100:101] op_sel_hi:[0,1,1]
	v_pk_fma_f32 v[102:103], v[52:53], v[26:27], v[102:103] op_sel_hi:[0,1,1]
	v_lshlrev_b32_e32 v20, 16, v40
	v_and_b32_e32 v21, 0xffff0000, v40
	v_lshlrev_b32_e32 v22, 16, v41
	v_and_b32_e32 v23, 0xffff0000, v41
	v_lshlrev_b32_e32 v24, 16, v42
	v_and_b32_e32 v25, 0xffff0000, v42
	v_lshlrev_b32_e32 v26, 16, v43
	v_and_b32_e32 v27, 0xffff0000, v43
	v_pk_fma_f32 v[104:105], v[52:53], v[20:21], v[104:105] op_sel_hi:[0,1,1]
	v_pk_fma_f32 v[106:107], v[52:53], v[22:23], v[106:107] op_sel_hi:[0,1,1]
	v_pk_fma_f32 v[108:109], v[52:53], v[24:25], v[108:109] op_sel_hi:[0,1,1]
	v_pk_fma_f32 v[110:111], v[52:53], v[26:27], v[110:111] op_sel_hi:[0,1,1]
	v_pk_mul_f32 v[132:133], v[96:97], v[96:97]
	v_pk_fma_f32 v[132:133], v[98:99], v[98:99], v[132:133]
	v_pk_fma_f32 v[132:133], v[100:101], v[100:101], v[132:133]
	v_pk_fma_f32 v[132:133], v[102:103], v[102:103], v[132:133]
	v_pk_fma_f32 v[132:133], v[104:105], v[104:105], v[132:133]
	v_pk_fma_f32 v[132:133], v[106:107], v[106:107], v[132:133]
	v_pk_fma_f32 v[132:133], v[108:109], v[108:109], v[132:133]
	v_pk_fma_f32 v[132:133], v[110:111], v[110:111], v[132:133]
	s_nop 0
	v_add_f32_e32 v132, v132, v133
	v_pk_mul_f32 v[112:113], v[130:131], v[112:113] op_sel_hi:[0,1]
	v_pk_mul_f32 v[114:115], v[130:131], v[114:115] op_sel_hi:[0,1]
	v_pk_mul_f32 v[116:117], v[130:131], v[116:117] op_sel_hi:[0,1]
	v_pk_mul_f32 v[118:119], v[130:131], v[118:119] op_sel_hi:[0,1]
	v_pk_mul_f32 v[120:121], v[130:131], v[120:121] op_sel_hi:[0,1]
	v_pk_mul_f32 v[122:123], v[130:131], v[122:123] op_sel_hi:[0,1]
	v_pk_mul_f32 v[124:125], v[130:131], v[124:125] op_sel_hi:[0,1]
	v_pk_mul_f32 v[126:127], v[130:131], v[126:127] op_sel_hi:[0,1]
	v_pk_mul_f32 v[112:113], v[112:113], v[192:193]
	v_pk_mul_f32 v[114:115], v[114:115], v[194:195]
	v_pk_mul_f32 v[116:117], v[116:117], v[196:197]
	v_pk_mul_f32 v[118:119], v[118:119], v[198:199]
	v_pk_mul_f32 v[120:121], v[120:121], v[200:201]
	v_pk_mul_f32 v[122:123], v[122:123], v[202:203]
	v_pk_mul_f32 v[124:125], v[124:125], v[204:205]
	v_pk_mul_f32 v[126:127], v[126:127], v[206:207]
	v_lshlrev_b32_e32 v28, 16, v44
	v_and_b32_e32 v29, 0xffff0000, v44
	v_lshlrev_b32_e32 v30, 16, v45
	v_and_b32_e32 v31, 0xffff0000, v45
	v_lshlrev_b32_e32 v32, 16, v46
	v_and_b32_e32 v33, 0xffff0000, v46
	v_lshlrev_b32_e32 v34, 16, v47
	v_and_b32_e32 v35, 0xffff0000, v47
	v_pk_fma_f32 v[112:113], v[54:55], v[28:29], v[112:113] op_sel_hi:[0,1,1]
	v_pk_fma_f32 v[114:115], v[54:55], v[30:31], v[114:115] op_sel_hi:[0,1,1]
	v_pk_fma_f32 v[116:117], v[54:55], v[32:33], v[116:117] op_sel_hi:[0,1,1]
	v_pk_fma_f32 v[118:119], v[54:55], v[34:35], v[118:119] op_sel_hi:[0,1,1]
	v_lshlrev_b32_e32 v28, 16, v48
	v_and_b32_e32 v29, 0xffff0000, v48
	v_lshlrev_b32_e32 v30, 16, v49
	v_and_b32_e32 v31, 0xffff0000, v49
	v_lshlrev_b32_e32 v32, 16, v50
	v_and_b32_e32 v33, 0xffff0000, v50
	v_lshlrev_b32_e32 v34, 16, v51
	v_and_b32_e32 v35, 0xffff0000, v51
	v_pk_fma_f32 v[120:121], v[54:55], v[28:29], v[120:121] op_sel_hi:[0,1,1]
	v_pk_fma_f32 v[122:123], v[54:55], v[30:31], v[122:123] op_sel_hi:[0,1,1]
	v_pk_fma_f32 v[124:125], v[54:55], v[32:33], v[124:125] op_sel_hi:[0,1,1]
	v_pk_fma_f32 v[126:127], v[54:55], v[34:35], v[126:127] op_sel_hi:[0,1,1]
	v_pk_mul_f32 v[134:135], v[112:113], v[112:113]
	v_pk_fma_f32 v[134:135], v[114:115], v[114:115], v[134:135]
	v_pk_fma_f32 v[134:135], v[116:117], v[116:117], v[134:135]
	v_pk_fma_f32 v[134:135], v[118:119], v[118:119], v[134:135]
	v_pk_fma_f32 v[134:135], v[120:121], v[120:121], v[134:135]
	v_pk_fma_f32 v[134:135], v[122:123], v[122:123], v[134:135]
	v_pk_fma_f32 v[134:135], v[124:125], v[124:125], v[134:135]
	v_pk_fma_f32 v[134:135], v[126:127], v[126:127], v[134:135]
	s_nop 0
	v_add_f32_e32 v134, v134, v135
	global_load_dword v52, v172, s[98:99]
	global_load_dwordx2 v[20:21], v170, s[98:99]
	global_load_dwordx2 v[22:23], v170, s[98:99] offset:512
;     __device__ __forceinline__ float* out() const { return (float*)karg_in(33); }
; __device__ __forceinline__ const float* xrow_ptr(const Ctx& C, int row) { return row < MPROMPT ? C.in(0) + (size_t)row * DM : C.in(1) + (size_t)(row - MPROMPT) * DM; }
; template <int R, bool BASE_F32, bool OUT_F32>
; __device__ __forceinline__ void rows_res(const Ctx& C, int m0, int stride, int mx, const float* gpost, float scale, int lane) {
;     ...
;     for (int r = 0; r < R; ++r) { mr[r] = (r == 4) ? mx : m0 + r * stride; ok[r] = (r == 4) ? (mx < M) : (mr[r] < MPROMPT); const int mm = ok[r] ? mr[r] : 0;
; #pragma unroll
;         for (int j = 0; j < 4; ++j) d[r][j] = ld4_bf16(D + (size_t)mm * DM + 4 * lane + 256 * j);
;         if (BASE_F32) { const float* x = xrow_ptr(C, mm);
; #pragma unroll
;             for (int j = 0; j < 4; ++j) b[r][j] = ld4_f32(x + 4 * lane + 256 * j);
;         } else { const float inv = C.RS()[mm];
; #pragma unroll
;             for (int j = 0; j < 4; ++j) b[r][j] = ld4_bf16(XN + (size_t)mm * DM + 4 * lane + 256 * j) * inv;
;         } }
; #pragma unroll
;     for (int r = 0; r < R; ++r) { float s = 0.f;
; #pragma unroll
;         for (int j = 0; j < 4; ++j) s += ssq4(d[r][j]);
;         r1[r] = s; }
; #pragma unroll
;     for (int r = 0; r < R; ++r) r1[r] = rsqrtf(wave_sum(r1[r]) * (1.f / DM) + EPS) * scale;
; #pragma unroll
;     for (int j = 0; j < 4; ++j) { const v4f gp = ld4_f32(gpost + 4 * lane + 256 * j);
; #pragma unroll
;         for (int r = 0; r < R; ++r) d[r][j] = b[r][j] + d[r][j] * r1[r] * gp; }
;     if (OUT_F32) { float* Y = C.out();
; #pragma unroll
;         for (int r = 0; r < R; ++r)
; #pragma unroll
;             for (int j = 0; j < 4; ++j) if (ok[r]) *(v4f*)(Y + (size_t)mr[r] * DM + 4 * lane + 256 * j) = d[r][j];
;     } else { float* rs = C.RS(); float t[R];
; #pragma unroll
;         for (int r = 0; r < R; ++r) { float s = 0.f;
; #pragma unroll
;             for (int j = 0; j < 4; ++j) s += ssq4(d[r][j]);
;             t[r] = s; }
; #pragma unroll
;         for (int r = 0; r < R; ++r) t[r] = wave_sum(t[r]) * (1.f / DM) + EPS;
; #pragma unroll
;         for (int r = 0; r < R; ++r) { const float rstd = rsqrtf(t[r]);
; #pragma unroll
;             for (int j = 0; j < 4; ++j) if (ok[r]) st4_bf16(XN + (size_t)mr[r] * DM + 4 * lane + 256 * j, d[r][j] * rstd);
;             if (lane == 0 && ok[r]) rs[mr[r]] = sqrtf(t[r]); }
	global_load_dwordx2 v[24:25], v170, s[98:99] offset:1024
	global_load_dwordx2 v[26:27], v170, s[98:99] offset:1536
	global_load_dwordx2 v[36:37], v171, s[98:99]
	global_load_dwordx2 v[38:39], v171, s[98:99] offset:512
	global_load_dwordx2 v[40:41], v171, s[98:99] offset:1024
	global_load_dwordx2 v[42:43], v171, s[98:99] offset:1536
	v_add_u32_e32 v170, 0x400000, v170
	v_add_u32_e32 v171, 0x400000, v171
	v_add_u32_e32 v172, 0x2000, v172
	global_load_dword v54, v172, s[98:99]
	global_load_dwordx2 v[28:29], v170, s[98:99]
	global_load_dwordx2 v[30:31], v170, s[98:99] offset:512
	global_load_dwordx2 v[32:33], v170, s[98:99] offset:1024
	global_load_dwordx2 v[34:35], v170, s[98:99] offset:1536
	global_load_dwordx2 v[44:45], v171, s[98:99]
	global_load_dwordx2 v[46:47], v171, s[98:99] offset:512
	global_load_dwordx2 v[48:49], v171, s[98:99] offset:1024
	global_load_dwordx2 v[50:51], v171, s[98:99] offset:1536
	v_add_u32_e32 v170, 0x400000, v170
	v_add_u32_e32 v171, 0x400000, v171
	v_add_u32_e32 v172, 0x2000, v172
	s_nop 1
	v_add_f32_dpp v132, v132, v132 quad_perm:[1,0,3,2] row_mask:0xf bank_mask:0xf
	v_add_f32_dpp v134, v134, v134 quad_perm:[1,0,3,2] row_mask:0xf bank_mask:0xf
	s_nop 0
	v_add_f32_dpp v132, v132, v132 quad_perm:[2,3,0,1] row_mask:0xf bank_mask:0xf
	v_add_f32_dpp v134, v134, v134 quad_perm:[2,3,0,1] row_mask:0xf bank_mask:0xf
	s_nop 0
	v_add_f32_dpp v132, v132, v132 row_half_mirror row_mask:0xf bank_mask:0xf
	v_add_f32_dpp v134, v134, v134 row_half_mirror row_mask:0xf bank_mask:0xf
	s_nop 0
	v_add_f32_dpp v132, v132, v132 row_mirror row_mask:0xf bank_mask:0xf
	v_add_f32_dpp v134, v134, v134 row_mirror row_mask:0xf bank_mask:0xf
	s_nop 0
	ds_bpermute_b32 v136, v187, v132
	ds_bpermute_b32 v137, v187, v134
	s_waitcnt lgkmcnt(0)
	v_add_f32_e32 v132, v132, v136
	v_add_f32_e32 v134, v134, v137
	ds_bpermute_b32 v136, v188, v132
	ds_bpermute_b32 v137, v188, v134
	s_waitcnt lgkmcnt(0)
	v_add_f32_e32 v132, v132, v136
	v_add_f32_e32 v134, v134, v137
	v_fmamk_f32 v164, v132, 0x3a800000, v138
	v_fmamk_f32 v167, v134, 0x3a800000, v138
	s_nop 0
	v_rsq_f32_e32 v132, v164
	v_rsq_f32_e32 v134, v167
	v_sqrt_f32_e32 v165, v164
	v_sqrt_f32_e32 v168, v167
	s_nop 1
	v_pk_mul_f32 v[140:141], v[96:97], v[132:133] op_sel_hi:[1,0]
	v_cvt_pk_bf16_f32 v148, v140, v141
	v_pk_mul_f32 v[142:143], v[98:99], v[132:133] op_sel_hi:[1,0]
	v_cvt_pk_bf16_f32 v149, v142, v143
	v_pk_mul_f32 v[144:145], v[100:101], v[132:133] op_sel_hi:[1,0]
	v_cvt_pk_bf16_f32 v150, v144, v145
	v_pk_mul_f32 v[146:147], v[102:103], v[132:133] op_sel_hi:[1,0]
	v_cvt_pk_bf16_f32 v151, v146, v147
	v_pk_mul_f32 v[140:141], v[104:105], v[132:133] op_sel_hi:[1,0]
	v_cvt_pk_bf16_f32 v152, v140, v141
	v_pk_mul_f32 v[142:143], v[106:107], v[132:133] op_sel_hi:[1,0]
	v_cvt_pk_bf16_f32 v153, v142, v143
	v_pk_mul_f32 v[144:145], v[108:109], v[132:133] op_sel_hi:[1,0]
	v_cvt_pk_bf16_f32 v154, v144, v145
	v_pk_mul_f32 v[146:147], v[110:111], v[132:133] op_sel_hi:[1,0]
	v_cvt_pk_bf16_f32 v155, v146, v147
	global_store_dwordx2 v173, v[148:149], s[98:99]
	global_store_dwordx2 v173, v[150:151], s[98:99] offset:512
	global_store_dwordx2 v173, v[152:153], s[98:99] offset:1024
	global_store_dwordx2 v173, v[154:155], s[98:99] offset:1536
	v_add_u32_e32 v173, 0x400000, v173
	v_pk_mul_f32 v[140:141], v[112:113], v[134:135] op_sel_hi:[1,0]
	v_cvt_pk_bf16_f32 v156, v140, v141
	v_pk_mul_f32 v[142:143], v[114:115], v[134:135] op_sel_hi:[1,0]
	v_cvt_pk_bf16_f32 v157, v142, v143
	v_pk_mul_f32 v[144:145], v[116:117], v[134:135] op_sel_hi:[1,0]
	v_cvt_pk_bf16_f32 v158, v144, v145
	v_pk_mul_f32 v[146:147], v[118:119], v[134:135] op_sel_hi:[1,0]
	v_cvt_pk_bf16_f32 v159, v146, v147
	v_pk_mul_f32 v[140:141], v[120:121], v[134:135] op_sel_hi:[1,0]
	v_cvt_pk_bf16_f32 v160, v140, v141
	v_pk_mul_f32 v[142:143], v[122:123], v[134:135] op_sel_hi:[1,0]
	v_cvt_pk_bf16_f32 v161, v142, v143
	v_pk_mul_f32 v[144:145], v[124:125], v[134:135] op_sel_hi:[1,0]
	v_cvt_pk_bf16_f32 v162, v144, v145
	v_pk_mul_f32 v[146:147], v[126:127], v[134:135] op_sel_hi:[1,0]
	v_cvt_pk_bf16_f32 v163, v146, v147
	global_store_dwordx2 v173, v[156:157], s[98:99]
	global_store_dwordx2 v173, v[158:159], s[98:99] offset:512
	global_store_dwordx2 v173, v[160:161], s[98:99] offset:1024
	global_store_dwordx2 v173, v[162:163], s[98:99] offset:1536
	v_add_u32_e32 v173, 0x400000, v173
	v_add_u32_e32 v166, -1, v165
	v_fma_f32 v140, -v166, v165, v164
	v_cmp_ge_f32_e32 vcc, 0, v140
	v_add_u32_e32 v141, 1, v165
	v_cndmask_b32_e32 v166, v165, v166, vcc
	v_fma_f32 v140, -v141, v165, v164
	v_cmp_lt_f32_e32 vcc, 0, v140
	s_nop 1
	v_cndmask_b32_e32 v165, v166, v141, vcc
	v_add_u32_e32 v169, -1, v168
	v_fma_f32 v142, -v169, v168, v167
	v_cmp_ge_f32_e32 vcc, 0, v142
	v_add_u32_e32 v143, 1, v168
	v_cndmask_b32_e32 v169, v168, v169, vcc
	v_fma_f32 v142, -v143, v168, v167
	v_cmp_lt_f32_e32 vcc, 0, v142
	s_nop 1
	v_cndmask_b32_e32 v168, v169, v143, vcc
	s_mov_b64 exec, 1
	global_store_dword v174, v165, s[98:99]
	v_add_u32_e32 v174, 0x2000, v174
	global_store_dword v174, v168, s[98:99]
	v_add_u32_e32 v174, 0x2000, v174
	s_mov_b64 exec, -1
	s_waitcnt vmcnt(41)
;     __device__ __forceinline__ float* out() const { return (float*)karg_in(33); }
; __device__ __forceinline__ float ssq4(v4f v) { return (v.x * v.x + v.y * v.y) + (v.z * v.z + v.w * v.w); }
; template <int R, bool BASE_F32, bool OUT_F32>
; __device__ __forceinline__ void rows_res(const Ctx& C, int m0, int stride, int mx, const float* gpost, float scale, int lane) {
;     ...
;     for (int r = 0; r < R; ++r) { float s = 0.f;
; #pragma unroll
;         for (int j = 0; j < 4; ++j) s += ssq4(d[r][j]);
;         r1[r] = s; }
; #pragma unroll
;     for (int r = 0; r < R; ++r) r1[r] = rsqrtf(wave_sum(r1[r]) * (1.f / DM) + EPS) * scale;
; #pragma unroll
;     for (int j = 0; j < 4; ++j) { const v4f gp = ld4_f32(gpost + 4 * lane + 256 * j);
; #pragma unroll
;         for (int r = 0; r < R; ++r) d[r][j] = b[r][j] + d[r][j] * r1[r] * gp; }
;     if (OUT_F32) { float* Y = C.out();
; #pragma unroll
;         for (int r = 0; r < R; ++r)
; #pragma unroll
;             for (int j = 0; j < 4; ++j) if (ok[r]) *(v4f*)(Y + (size_t)mr[r] * DM + 4 * lane + 256 * j) = d[r][j];
;     } else { float* rs = C.RS(); float t[R];
; #pragma unroll
;         for (int r = 0; r < R; ++r) { float s = 0.f;
; #pragma unroll
;             for (int j = 0; j < 4; ++j) s += ssq4(d[r][j]);
;             t[r] = s; }
; #pragma unroll
;         for (int r = 0; r < R; ++r) t[r] = wave_sum(t[r]) * (1.f / DM) + EPS;
	v_lshlrev_b32_e32 v96, 16, v56
	v_and_b32_e32 v97, 0xffff0000, v56
	v_lshlrev_b32_e32 v98, 16, v57
	v_and_b32_e32 v99, 0xffff0000, v57
	v_lshlrev_b32_e32 v100, 16, v58
	v_and_b32_e32 v101, 0xffff0000, v58
	v_lshlrev_b32_e32 v102, 16, v59
	v_and_b32_e32 v103, 0xffff0000, v59
	v_lshlrev_b32_e32 v104, 16, v60
	v_and_b32_e32 v105, 0xffff0000, v60
	v_lshlrev_b32_e32 v106, 16, v61
	v_and_b32_e32 v107, 0xffff0000, v61
	v_lshlrev_b32_e32 v108, 16, v62
	v_and_b32_e32 v109, 0xffff0000, v62
	v_lshlrev_b32_e32 v110, 16, v63
	v_and_b32_e32 v111, 0xffff0000, v63
	v_pk_mul_f32 v[128:129], v[96:97], v[96:97]
	v_pk_fma_f32 v[128:129], v[98:99], v[98:99], v[128:129]
	v_pk_fma_f32 v[128:129], v[100:101], v[100:101], v[128:129]
	v_pk_fma_f32 v[128:129], v[102:103], v[102:103], v[128:129]
	v_pk_fma_f32 v[128:129], v[104:105], v[104:105], v[128:129]
	v_pk_fma_f32 v[128:129], v[106:107], v[106:107], v[128:129]
	v_pk_fma_f32 v[128:129], v[108:109], v[108:109], v[128:129]
	v_pk_fma_f32 v[128:129], v[110:111], v[110:111], v[128:129]
	s_nop 0
	v_add_f32_e32 v128, v128, v129
	s_waitcnt vmcnt(32)
	v_lshlrev_b32_e32 v112, 16, v64
	v_and_b32_e32 v113, 0xffff0000, v64
	v_lshlrev_b32_e32 v114, 16, v65
	v_and_b32_e32 v115, 0xffff0000, v65
	v_lshlrev_b32_e32 v116, 16, v66
	v_and_b32_e32 v117, 0xffff0000, v66
	v_lshlrev_b32_e32 v118, 16, v67
	v_and_b32_e32 v119, 0xffff0000, v67
	v_lshlrev_b32_e32 v120, 16, v68
	v_and_b32_e32 v121, 0xffff0000, v68
	v_lshlrev_b32_e32 v122, 16, v69
	v_and_b32_e32 v123, 0xffff0000, v69
	v_lshlrev_b32_e32 v124, 16, v70
	v_and_b32_e32 v125, 0xffff0000, v70
	v_lshlrev_b32_e32 v126, 16, v71
	v_and_b32_e32 v127, 0xffff0000, v71
	v_pk_mul_f32 v[130:131], v[112:113], v[112:113]
	v_pk_fma_f32 v[130:131], v[114:115], v[114:115], v[130:131]
	v_pk_fma_f32 v[130:131], v[116:117], v[116:117], v[130:131]
	v_pk_fma_f32 v[130:131], v[118:119], v[118:119], v[130:131]
	v_pk_fma_f32 v[130:131], v[120:121], v[120:121], v[130:131]
	v_pk_fma_f32 v[130:131], v[122:123], v[122:123], v[130:131]
	v_pk_fma_f32 v[130:131], v[124:125], v[124:125], v[130:131]
	v_pk_fma_f32 v[130:131], v[126:127], v[126:127], v[130:131]
	s_nop 0
	v_add_f32_e32 v130, v130, v131
	s_nop 1
	v_add_f32_dpp v128, v128, v128 quad_perm:[1,0,3,2] row_mask:0xf bank_mask:0xf
	v_add_f32_dpp v130, v130, v130 quad_perm:[1,0,3,2] row_mask:0xf bank_mask:0xf
	s_nop 0
	v_add_f32_dpp v128, v128, v128 quad_perm:[2,3,0,1] row_mask:0xf bank_mask:0xf
	v_add_f32_dpp v130, v130, v130 quad_perm:[2,3,0,1] row_mask:0xf bank_mask:0xf
	s_nop 0
	v_add_f32_dpp v128, v128, v128 row_half_mirror row_mask:0xf bank_mask:0xf
	v_add_f32_dpp v130, v130, v130 row_half_mirror row_mask:0xf bank_mask:0xf
	s_nop 0
	v_add_f32_dpp v128, v128, v128 row_mirror row_mask:0xf bank_mask:0xf
	v_add_f32_dpp v130, v130, v130 row_mirror row_mask:0xf bank_mask:0xf
	s_nop 0
	ds_bpermute_b32 v136, v187, v128
	ds_bpermute_b32 v137, v187, v130
	s_waitcnt lgkmcnt(0)
	v_add_f32_e32 v128, v128, v136
	v_add_f32_e32 v130, v130, v137
	ds_bpermute_b32 v136, v188, v128
	ds_bpermute_b32 v137, v188, v130
	s_waitcnt lgkmcnt(0)
	v_add_f32_e32 v128, v128, v136
	v_add_f32_e32 v130, v130, v137
	v_fmamk_f32 v128, v128, 0x3a800000, v138
	v_fmamk_f32 v130, v130, 0x3a800000, v138
	s_nop 0
	v_rsq_f32_e32 v128, v128
	v_rsq_f32_e32 v130, v130
	s_nop 1
	s_waitcnt vmcnt(28)
	v_pk_mul_f32 v[96:97], v[128:129], v[96:97] op_sel_hi:[0,1]
	v_pk_mul_f32 v[98:99], v[128:129], v[98:99] op_sel_hi:[0,1]
	v_pk_mul_f32 v[100:101], v[128:129], v[100:101] op_sel_hi:[0,1]
	v_pk_mul_f32 v[102:103], v[128:129], v[102:103] op_sel_hi:[0,1]
	v_pk_mul_f32 v[104:105], v[128:129], v[104:105] op_sel_hi:[0,1]
	v_pk_mul_f32 v[106:107], v[128:129], v[106:107] op_sel_hi:[0,1]
	v_pk_mul_f32 v[108:109], v[128:129], v[108:109] op_sel_hi:[0,1]
	v_pk_mul_f32 v[110:111], v[128:129], v[110:111] op_sel_hi:[0,1]
	v_pk_mul_f32 v[96:97], v[96:97], v[192:193]
	v_pk_mul_f32 v[98:99], v[98:99], v[194:195]
	v_pk_mul_f32 v[100:101], v[100:101], v[196:197]
	v_pk_mul_f32 v[102:103], v[102:103], v[198:199]
	v_pk_mul_f32 v[104:105], v[104:105], v[200:201]
	v_pk_mul_f32 v[106:107], v[106:107], v[202:203]
	v_pk_mul_f32 v[108:109], v[108:109], v[204:205]
	v_pk_mul_f32 v[110:111], v[110:111], v[206:207]
	v_lshlrev_b32_e32 v56, 16, v72
	v_and_b32_e32 v57, 0xffff0000, v72
	v_lshlrev_b32_e32 v58, 16, v73
	v_and_b32_e32 v59, 0xffff0000, v73
	v_lshlrev_b32_e32 v60, 16, v74
	v_and_b32_e32 v61, 0xffff0000, v74
	v_lshlrev_b32_e32 v62, 16, v75
	v_and_b32_e32 v63, 0xffff0000, v75
	v_pk_fma_f32 v[96:97], v[88:89], v[56:57], v[96:97] op_sel_hi:[0,1,1]
	v_pk_fma_f32 v[98:99], v[88:89], v[58:59], v[98:99] op_sel_hi:[0,1,1]
	v_pk_fma_f32 v[100:101], v[88:89], v[60:61], v[100:101] op_sel_hi:[0,1,1]
	v_pk_fma_f32 v[102:103], v[88:89], v[62:63], v[102:103] op_sel_hi:[0,1,1]
	v_lshlrev_b32_e32 v56, 16, v76
	v_and_b32_e32 v57, 0xffff0000, v76
	v_lshlrev_b32_e32 v58, 16, v77
	v_and_b32_e32 v59, 0xffff0000, v77
	v_lshlrev_b32_e32 v60, 16, v78
	v_and_b32_e32 v61, 0xffff0000, v78
	v_lshlrev_b32_e32 v62, 16, v79
	v_and_b32_e32 v63, 0xffff0000, v79
	v_pk_fma_f32 v[104:105], v[88:89], v[56:57], v[104:105] op_sel_hi:[0,1,1]
	v_pk_fma_f32 v[106:107], v[88:89], v[58:59], v[106:107] op_sel_hi:[0,1,1]
	v_pk_fma_f32 v[108:109], v[88:89], v[60:61], v[108:109] op_sel_hi:[0,1,1]
	v_pk_fma_f32 v[110:111], v[88:89], v[62:63], v[110:111] op_sel_hi:[0,1,1]
	v_pk_mul_f32 v[132:133], v[96:97], v[96:97]
	v_pk_fma_f32 v[132:133], v[98:99], v[98:99], v[132:133]
	v_pk_fma_f32 v[132:133], v[100:101], v[100:101], v[132:133]
	v_pk_fma_f32 v[132:133], v[102:103], v[102:103], v[132:133]
	v_pk_fma_f32 v[132:133], v[104:105], v[104:105], v[132:133]
;     __device__ __forceinline__ float* out() const { return (float*)karg_in(33); }
; __device__ __forceinline__ const float* xrow_ptr(const Ctx& C, int row) { return row < MPROMPT ? C.in(0) + (size_t)row * DM : C.in(1) + (size_t)(row - MPROMPT) * DM; }
; __device__ __forceinline__ v4f ld4_bf16(const bf16* p) { const v2u w = *(const v2u*)p; return (v4f){bf_lo(w.x), bf_hi(w.x), bf_lo(w.y), bf_hi(w.y)}; }
; __device__ __forceinline__ float ssq4(v4f v) { return (v.x * v.x + v.y * v.y) + (v.z * v.z + v.w * v.w); }
; template <int R, bool BASE_F32, bool OUT_F32>
; __device__ __forceinline__ void rows_res(const Ctx& C, int m0, int stride, int mx, const float* gpost, float scale, int lane) {
;     ...
;     for (int r = 0; r < R; ++r) { mr[r] = (r == 4) ? mx : m0 + r * stride; ok[r] = (r == 4) ? (mx < M) : (mr[r] < MPROMPT); const int mm = ok[r] ? mr[r] : 0;
; #pragma unroll
;         for (int j = 0; j < 4; ++j) d[r][j] = ld4_bf16(D + (size_t)mm * DM + 4 * lane + 256 * j);
;         if (BASE_F32) { const float* x = xrow_ptr(C, mm);
; #pragma unroll
;             for (int j = 0; j < 4; ++j) b[r][j] = ld4_f32(x + 4 * lane + 256 * j);
;         } else { const float inv = C.RS()[mm];
; #pragma unroll
;             for (int j = 0; j < 4; ++j) b[r][j] = ld4_bf16(XN + (size_t)mm * DM + 4 * lane + 256 * j) * inv;
;         } }
; #pragma unroll
;     for (int r = 0; r < R; ++r) { float s = 0.f;
; #pragma unroll
;         for (int j = 0; j < 4; ++j) s += ssq4(d[r][j]);
;         r1[r] = s; }
; #pragma unroll
;     for (int r = 0; r < R; ++r) r1[r] = rsqrtf(wave_sum(r1[r]) * (1.f / DM) + EPS) * scale;
; #pragma unroll
;     for (int j = 0; j < 4; ++j) { const v4f gp = ld4_f32(gpost + 4 * lane + 256 * j);
; #pragma unroll
;         for (int r = 0; r < R; ++r) d[r][j] = b[r][j] + d[r][j] * r1[r] * gp; }
;     if (OUT_F32) { float* Y = C.out();
; #pragma unroll
;         for (int r = 0; r < R; ++r)
; #pragma unroll
;             for (int j = 0; j < 4; ++j) if (ok[r]) *(v4f*)(Y + (size_t)mr[r] * DM + 4 * lane + 256 * j) = d[r][j];
;     } else { float* rs = C.RS(); float t[R];
; #pragma unroll
;         for (int r = 0; r < R; ++r) { float s = 0.f;
; #pragma unroll
;             for (int j = 0; j < 4; ++j) s += ssq4(d[r][j]);
;             t[r] = s; }
; #pragma unroll
;         for (int r = 0; r < R; ++r) t[r] = wave_sum(t[r]) * (1.f / DM) + EPS;
	v_pk_fma_f32 v[132:133], v[106:107], v[106:107], v[132:133]
	v_pk_fma_f32 v[132:133], v[108:109], v[108:109], v[132:133]
	v_pk_fma_f32 v[132:133], v[110:111], v[110:111], v[132:133]
	s_nop 0
	v_add_f32_e32 v132, v132, v133
	v_pk_mul_f32 v[112:113], v[130:131], v[112:113] op_sel_hi:[0,1]
	v_pk_mul_f32 v[114:115], v[130:131], v[114:115] op_sel_hi:[0,1]
	v_pk_mul_f32 v[116:117], v[130:131], v[116:117] op_sel_hi:[0,1]
	v_pk_mul_f32 v[118:119], v[130:131], v[118:119] op_sel_hi:[0,1]
	v_pk_mul_f32 v[120:121], v[130:131], v[120:121] op_sel_hi:[0,1]
	v_pk_mul_f32 v[122:123], v[130:131], v[122:123] op_sel_hi:[0,1]
	v_pk_mul_f32 v[124:125], v[130:131], v[124:125] op_sel_hi:[0,1]
	v_pk_mul_f32 v[126:127], v[130:131], v[126:127] op_sel_hi:[0,1]
	v_pk_mul_f32 v[112:113], v[112:113], v[192:193]
	v_pk_mul_f32 v[114:115], v[114:115], v[194:195]
	v_pk_mul_f32 v[116:117], v[116:117], v[196:197]
	v_pk_mul_f32 v[118:119], v[118:119], v[198:199]
	v_pk_mul_f32 v[120:121], v[120:121], v[200:201]
	v_pk_mul_f32 v[122:123], v[122:123], v[202:203]
	v_pk_mul_f32 v[124:125], v[124:125], v[204:205]
	v_pk_mul_f32 v[126:127], v[126:127], v[206:207]
	v_lshlrev_b32_e32 v64, 16, v80
	v_and_b32_e32 v65, 0xffff0000, v80
	v_lshlrev_b32_e32 v66, 16, v81
	v_and_b32_e32 v67, 0xffff0000, v81
	v_lshlrev_b32_e32 v68, 16, v82
	v_and_b32_e32 v69, 0xffff0000, v82
	v_lshlrev_b32_e32 v70, 16, v83
	v_and_b32_e32 v71, 0xffff0000, v83
	v_pk_fma_f32 v[112:113], v[90:91], v[64:65], v[112:113] op_sel_hi:[0,1,1]
	v_pk_fma_f32 v[114:115], v[90:91], v[66:67], v[114:115] op_sel_hi:[0,1,1]
	v_pk_fma_f32 v[116:117], v[90:91], v[68:69], v[116:117] op_sel_hi:[0,1,1]
	v_pk_fma_f32 v[118:119], v[90:91], v[70:71], v[118:119] op_sel_hi:[0,1,1]
	v_lshlrev_b32_e32 v64, 16, v84
	v_and_b32_e32 v65, 0xffff0000, v84
	v_lshlrev_b32_e32 v66, 16, v85
	v_and_b32_e32 v67, 0xffff0000, v85
	v_lshlrev_b32_e32 v68, 16, v86
	v_and_b32_e32 v69, 0xffff0000, v86
	v_lshlrev_b32_e32 v70, 16, v87
	v_and_b32_e32 v71, 0xffff0000, v87
	v_pk_fma_f32 v[120:121], v[90:91], v[64:65], v[120:121] op_sel_hi:[0,1,1]
	v_pk_fma_f32 v[122:123], v[90:91], v[66:67], v[122:123] op_sel_hi:[0,1,1]
	v_pk_fma_f32 v[124:125], v[90:91], v[68:69], v[124:125] op_sel_hi:[0,1,1]
	v_pk_fma_f32 v[126:127], v[90:91], v[70:71], v[126:127] op_sel_hi:[0,1,1]
	v_pk_mul_f32 v[134:135], v[112:113], v[112:113]
	v_pk_fma_f32 v[134:135], v[114:115], v[114:115], v[134:135]
	v_pk_fma_f32 v[134:135], v[116:117], v[116:117], v[134:135]
	v_pk_fma_f32 v[134:135], v[118:119], v[118:119], v[134:135]
	v_pk_fma_f32 v[134:135], v[120:121], v[120:121], v[134:135]
	v_pk_fma_f32 v[134:135], v[122:123], v[122:123], v[134:135]
	v_pk_fma_f32 v[134:135], v[124:125], v[124:125], v[134:135]
	v_pk_fma_f32 v[134:135], v[126:127], v[126:127], v[134:135]
	s_nop 0
	v_add_f32_e32 v134, v134, v135
	global_load_dword v88, v172, s[98:99]
	global_load_dwordx2 v[56:57], v170, s[98:99]
	global_load_dwordx2 v[58:59], v170, s[98:99] offset:512
	global_load_dwordx2 v[60:61], v170, s[98:99] offset:1024
	global_load_dwordx2 v[62:63], v170, s[98:99] offset:1536
	global_load_dwordx2 v[72:73], v171, s[98:99]
	global_load_dwordx2 v[74:75], v171, s[98:99] offset:512
	global_load_dwordx2 v[76:77], v171, s[98:99] offset:1024
	global_load_dwordx2 v[78:79], v171, s[98:99] offset:1536
	v_add_u32_e32 v170, 0x400000, v170
	v_add_u32_e32 v171, 0x400000, v171
	v_add_u32_e32 v172, 0x2000, v172
	global_load_dword v90, v172, s[98:99]
	global_load_dwordx2 v[64:65], v170, s[98:99]
	global_load_dwordx2 v[66:67], v170, s[98:99] offset:512
	global_load_dwordx2 v[68:69], v170, s[98:99] offset:1024
	global_load_dwordx2 v[70:71], v170, s[98:99] offset:1536
	global_load_dwordx2 v[80:81], v171, s[98:99]
	global_load_dwordx2 v[82:83], v171, s[98:99] offset:512
	global_load_dwordx2 v[84:85], v171, s[98:99] offset:1024
	global_load_dwordx2 v[86:87], v171, s[98:99] offset:1536
	v_add_u32_e32 v170, 0x400000, v170
	v_add_u32_e32 v171, 0x400000, v171
	v_add_u32_e32 v172, 0x2000, v172
	s_nop 1
	v_add_f32_dpp v132, v132, v132 quad_perm:[1,0,3,2] row_mask:0xf bank_mask:0xf
	v_add_f32_dpp v134, v134, v134 quad_perm:[1,0,3,2] row_mask:0xf bank_mask:0xf
	s_nop 0
	v_add_f32_dpp v132, v132, v132 quad_perm:[2,3,0,1] row_mask:0xf bank_mask:0xf
	v_add_f32_dpp v134, v134, v134 quad_perm:[2,3,0,1] row_mask:0xf bank_mask:0xf
	s_nop 0
	v_add_f32_dpp v132, v132, v132 row_half_mirror row_mask:0xf bank_mask:0xf
	v_add_f32_dpp v134, v134, v134 row_half_mirror row_mask:0xf bank_mask:0xf
	s_nop 0
	v_add_f32_dpp v132, v132, v132 row_mirror row_mask:0xf bank_mask:0xf
	v_add_f32_dpp v134, v134, v134 row_mirror row_mask:0xf bank_mask:0xf
	s_nop 0
	ds_bpermute_b32 v136, v187, v132
	ds_bpermute_b32 v137, v187, v134
	s_waitcnt lgkmcnt(0)
	v_add_f32_e32 v132, v132, v136
	v_add_f32_e32 v134, v134, v137
	ds_bpermute_b32 v136, v188, v132
	ds_bpermute_b32 v137, v188, v134
	s_waitcnt lgkmcnt(0)
;     __device__ __forceinline__ float* out() const { return (float*)karg_in(33); }
; __device__ __forceinline__ void st4_bf16(bf16* p, v4f o) { v2u w; w.x = cvt_pk_nv(o.x, o.y); w.y = cvt_pk_nv(o.z, o.w); *(v2u*)p = w; }
; __device__ __forceinline__ float ssq4(v4f v) { return (v.x * v.x + v.y * v.y) + (v.z * v.z + v.w * v.w); }
; template <int R, bool BASE_F32, bool OUT_F32>
; __device__ __forceinline__ void rows_res(const Ctx& C, int m0, int stride, int mx, const float* gpost, float scale, int lane) {
;     ...
;     for (int r = 0; r < R; ++r) { float s = 0.f;
; #pragma unroll
;         for (int j = 0; j < 4; ++j) s += ssq4(d[r][j]);
;         r1[r] = s; }
; #pragma unroll
;     for (int r = 0; r < R; ++r) r1[r] = rsqrtf(wave_sum(r1[r]) * (1.f / DM) + EPS) * scale;
; #pragma unroll
;     for (int j = 0; j < 4; ++j) { const v4f gp = ld4_f32(gpost + 4 * lane + 256 * j);
; #pragma unroll
;         for (int r = 0; r < R; ++r) d[r][j] = b[r][j] + d[r][j] * r1[r] * gp; }
;     if (OUT_F32) { float* Y = C.out();
; #pragma unroll
;         for (int r = 0; r < R; ++r)
; #pragma unroll
;             for (int j = 0; j < 4; ++j) if (ok[r]) *(v4f*)(Y + (size_t)mr[r] * DM + 4 * lane + 256 * j) = d[r][j];
;     } else { float* rs = C.RS(); float t[R];
; #pragma unroll
;         for (int r = 0; r < R; ++r) { float s = 0.f;
; #pragma unroll
;             for (int j = 0; j < 4; ++j) s += ssq4(d[r][j]);
;             t[r] = s; }
; #pragma unroll
;         for (int r = 0; r < R; ++r) t[r] = wave_sum(t[r]) * (1.f / DM) + EPS;
; #pragma unroll
;         for (int r = 0; r < R; ++r) { const float rstd = rsqrtf(t[r]);
; #pragma unroll
;             for (int j = 0; j < 4; ++j) if (ok[r]) st4_bf16(XN + (size_t)mr[r] * DM + 4 * lane + 256 * j, d[r][j] * rstd);
;             if (lane == 0 && ok[r]) rs[mr[r]] = sqrtf(t[r]); }
	v_add_f32_e32 v132, v132, v136
	v_add_f32_e32 v134, v134, v137
	v_fmamk_f32 v164, v132, 0x3a800000, v138
	v_fmamk_f32 v167, v134, 0x3a800000, v138
	s_nop 0
	v_rsq_f32_e32 v132, v164
	v_rsq_f32_e32 v134, v167
	v_sqrt_f32_e32 v165, v164
	v_sqrt_f32_e32 v168, v167
	s_nop 1
	v_pk_mul_f32 v[140:141], v[96:97], v[132:133] op_sel_hi:[1,0]
	v_cvt_pk_bf16_f32 v148, v140, v141
	v_pk_mul_f32 v[142:143], v[98:99], v[132:133] op_sel_hi:[1,0]
	v_cvt_pk_bf16_f32 v149, v142, v143
	v_pk_mul_f32 v[144:145], v[100:101], v[132:133] op_sel_hi:[1,0]
	v_cvt_pk_bf16_f32 v150, v144, v145
	v_pk_mul_f32 v[146:147], v[102:103], v[132:133] op_sel_hi:[1,0]
	v_cvt_pk_bf16_f32 v151, v146, v147
	v_pk_mul_f32 v[140:141], v[104:105], v[132:133] op_sel_hi:[1,0]
	v_cvt_pk_bf16_f32 v152, v140, v141
	v_pk_mul_f32 v[142:143], v[106:107], v[132:133] op_sel_hi:[1,0]
	v_cvt_pk_bf16_f32 v153, v142, v143
	v_pk_mul_f32 v[144:145], v[108:109], v[132:133] op_sel_hi:[1,0]
	v_cvt_pk_bf16_f32 v154, v144, v145
	v_pk_mul_f32 v[146:147], v[110:111], v[132:133] op_sel_hi:[1,0]
	v_cvt_pk_bf16_f32 v155, v146, v147
	global_store_dwordx2 v173, v[148:149], s[98:99]
	global_store_dwordx2 v173, v[150:151], s[98:99] offset:512
	global_store_dwordx2 v173, v[152:153], s[98:99] offset:1024
	global_store_dwordx2 v173, v[154:155], s[98:99] offset:1536
	v_add_u32_e32 v173, 0x400000, v173
	v_pk_mul_f32 v[140:141], v[112:113], v[134:135] op_sel_hi:[1,0]
	v_cvt_pk_bf16_f32 v156, v140, v141
	v_pk_mul_f32 v[142:143], v[114:115], v[134:135] op_sel_hi:[1,0]
	v_cvt_pk_bf16_f32 v157, v142, v143
	v_pk_mul_f32 v[144:145], v[116:117], v[134:135] op_sel_hi:[1,0]
	v_cvt_pk_bf16_f32 v158, v144, v145
	v_pk_mul_f32 v[146:147], v[118:119], v[134:135] op_sel_hi:[1,0]
	v_cvt_pk_bf16_f32 v159, v146, v147
	v_pk_mul_f32 v[140:141], v[120:121], v[134:135] op_sel_hi:[1,0]
	v_cvt_pk_bf16_f32 v160, v140, v141
	v_pk_mul_f32 v[142:143], v[122:123], v[134:135] op_sel_hi:[1,0]
	v_cvt_pk_bf16_f32 v161, v142, v143
	v_pk_mul_f32 v[144:145], v[124:125], v[134:135] op_sel_hi:[1,0]
	v_cvt_pk_bf16_f32 v162, v144, v145
	v_pk_mul_f32 v[146:147], v[126:127], v[134:135] op_sel_hi:[1,0]
	v_cvt_pk_bf16_f32 v163, v146, v147
	global_store_dwordx2 v173, v[156:157], s[98:99]
	global_store_dwordx2 v173, v[158:159], s[98:99] offset:512
	global_store_dwordx2 v173, v[160:161], s[98:99] offset:1024
	global_store_dwordx2 v173, v[162:163], s[98:99] offset:1536
	v_add_u32_e32 v173, 0x400000, v173
	v_add_u32_e32 v166, -1, v165
	v_fma_f32 v140, -v166, v165, v164
	v_cmp_ge_f32_e32 vcc, 0, v140
	v_add_u32_e32 v141, 1, v165
	v_cndmask_b32_e32 v166, v165, v166, vcc
	v_fma_f32 v140, -v141, v165, v164
	v_cmp_lt_f32_e32 vcc, 0, v140
	s_nop 1
	v_cndmask_b32_e32 v165, v166, v141, vcc
	v_add_u32_e32 v169, -1, v168
	v_fma_f32 v142, -v169, v168, v167
	v_cmp_ge_f32_e32 vcc, 0, v142
	v_add_u32_e32 v143, 1, v168
	v_cndmask_b32_e32 v169, v168, v169, vcc
	v_fma_f32 v142, -v143, v168, v167
	v_cmp_lt_f32_e32 vcc, 0, v142
	s_nop 1
	v_cndmask_b32_e32 v168, v169, v143, vcc
	s_mov_b64 exec, 1
	global_store_dword v174, v165, s[98:99]
	v_add_u32_e32 v174, 0x2000, v174
	global_store_dword v174, v168, s[98:99]
	v_add_u32_e32 v174, 0x2000, v174
	s_mov_b64 exec, -1
	s_waitcnt vmcnt(51)
	v_lshlrev_b32_e32 v96, 16, v20
	v_and_b32_e32 v97, 0xffff0000, v20
	v_lshlrev_b32_e32 v98, 16, v21
	v_and_b32_e32 v99, 0xffff0000, v21
	v_lshlrev_b32_e32 v100, 16, v22
	v_and_b32_e32 v101, 0xffff0000, v22
	v_lshlrev_b32_e32 v102, 16, v23
	v_and_b32_e32 v103, 0xffff0000, v23
	v_lshlrev_b32_e32 v104, 16, v24
	v_and_b32_e32 v105, 0xffff0000, v24
	v_lshlrev_b32_e32 v106, 16, v25
	v_and_b32_e32 v107, 0xffff0000, v25
	v_lshlrev_b32_e32 v108, 16, v26
	v_and_b32_e32 v109, 0xffff0000, v26
	v_lshlrev_b32_e32 v110, 16, v27
	v_and_b32_e32 v111, 0xffff0000, v27
	v_pk_mul_f32 v[128:129], v[96:97], v[96:97]
	v_pk_fma_f32 v[128:129], v[98:99], v[98:99], v[128:129]
	v_pk_fma_f32 v[128:129], v[100:101], v[100:101], v[128:129]
	v_pk_fma_f32 v[128:129], v[102:103], v[102:103], v[128:129]
	v_pk_fma_f32 v[128:129], v[104:105], v[104:105], v[128:129]
	v_pk_fma_f32 v[128:129], v[106:107], v[106:107], v[128:129]
	v_pk_fma_f32 v[128:129], v[108:109], v[108:109], v[128:129]
	v_pk_fma_f32 v[128:129], v[110:111], v[110:111], v[128:129]
	s_nop 0
	v_add_f32_e32 v128, v128, v129
	s_waitcnt vmcnt(42)
	v_lshlrev_b32_e32 v112, 16, v28
	v_and_b32_e32 v113, 0xffff0000, v28
	v_lshlrev_b32_e32 v114, 16, v29
	v_and_b32_e32 v115, 0xffff0000, v29
	v_lshlrev_b32_e32 v116, 16, v30
	v_and_b32_e32 v117, 0xffff0000, v30
	v_lshlrev_b32_e32 v118, 16, v31
	v_and_b32_e32 v119, 0xffff0000, v31
	v_lshlrev_b32_e32 v120, 16, v32
	v_and_b32_e32 v121, 0xffff0000, v32
	v_lshlrev_b32_e32 v122, 16, v33
	v_and_b32_e32 v123, 0xffff0000, v33
	v_lshlrev_b32_e32 v124, 16, v34
	v_and_b32_e32 v125, 0xffff0000, v34
	v_lshlrev_b32_e32 v126, 16, v35
	v_and_b32_e32 v127, 0xffff0000, v35
	v_pk_mul_f32 v[130:131], v[112:113], v[112:113]
	v_pk_fma_f32 v[130:131], v[114:115], v[114:115], v[130:131]
	v_pk_fma_f32 v[130:131], v[116:117], v[116:117], v[130:131]
	v_pk_fma_f32 v[130:131], v[118:119], v[118:119], v[130:131]
	v_pk_fma_f32 v[130:131], v[120:121], v[120:121], v[130:131]
	v_pk_fma_f32 v[130:131], v[122:123], v[122:123], v[130:131]
	v_pk_fma_f32 v[130:131], v[124:125], v[124:125], v[130:131]
	v_pk_fma_f32 v[130:131], v[126:127], v[126:127], v[130:131]
	s_nop 0
	v_add_f32_e32 v130, v130, v131
	s_nop 1
	v_add_f32_dpp v128, v128, v128 quad_perm:[1,0,3,2] row_mask:0xf bank_mask:0xf
	v_add_f32_dpp v130, v130, v130 quad_perm:[1,0,3,2] row_mask:0xf bank_mask:0xf
	s_nop 0
	v_add_f32_dpp v128, v128, v128 quad_perm:[2,3,0,1] row_mask:0xf bank_mask:0xf
	v_add_f32_dpp v130, v130, v130 quad_perm:[2,3,0,1] row_mask:0xf bank_mask:0xf
	s_nop 0
	v_add_f32_dpp v128, v128, v128 row_half_mirror row_mask:0xf bank_mask:0xf
	v_add_f32_dpp v130, v130, v130 row_half_mirror row_mask:0xf bank_mask:0xf
	s_nop 0
	v_add_f32_dpp v128, v128, v128 row_mirror row_mask:0xf bank_mask:0xf
	v_add_f32_dpp v130, v130, v130 row_mirror row_mask:0xf bank_mask:0xf
	s_nop 0
	ds_bpermute_b32 v136, v187, v128
	ds_bpermute_b32 v137, v187, v130
	s_waitcnt lgkmcnt(0)
;     __device__ __forceinline__ float* out() const { return (float*)karg_in(33); }
; __device__ __forceinline__ const float* xrow_ptr(const Ctx& C, int row) { return row < MPROMPT ? C.in(0) + (size_t)row * DM : C.in(1) + (size_t)(row - MPROMPT) * DM; }
; __device__ __forceinline__ v4f ld4_bf16(const bf16* p) { const v2u w = *(const v2u*)p; return (v4f){bf_lo(w.x), bf_hi(w.x), bf_lo(w.y), bf_hi(w.y)}; }
; __device__ __forceinline__ float ssq4(v4f v) { return (v.x * v.x + v.y * v.y) + (v.z * v.z + v.w * v.w); }
; template <int R, bool BASE_F32, bool OUT_F32>
; __device__ __forceinline__ void rows_res(const Ctx& C, int m0, int stride, int mx, const float* gpost, float scale, int lane) {
;     ...
;     for (int r = 0; r < R; ++r) { mr[r] = (r == 4) ? mx : m0 + r * stride; ok[r] = (r == 4) ? (mx < M) : (mr[r] < MPROMPT); const int mm = ok[r] ? mr[r] : 0;
; #pragma unroll
;         for (int j = 0; j < 4; ++j) d[r][j] = ld4_bf16(D + (size_t)mm * DM + 4 * lane + 256 * j);
;         if (BASE_F32) { const float* x = xrow_ptr(C, mm);
; #pragma unroll
;             for (int j = 0; j < 4; ++j) b[r][j] = ld4_f32(x + 4 * lane + 256 * j);
;         } else { const float inv = C.RS()[mm];
; #pragma unroll
;             for (int j = 0; j < 4; ++j) b[r][j] = ld4_bf16(XN + (size_t)mm * DM + 4 * lane + 256 * j) * inv;
;         } }
; #pragma unroll
;     for (int r = 0; r < R; ++r) { float s = 0.f;
; #pragma unroll
;         for (int j = 0; j < 4; ++j) s += ssq4(d[r][j]);
;         r1[r] = s; }
; #pragma unroll
;     for (int r = 0; r < R; ++r) r1[r] = rsqrtf(wave_sum(r1[r]) * (1.f / DM) + EPS) * scale;
; #pragma unroll
;     for (int j = 0; j < 4; ++j) { const v4f gp = ld4_f32(gpost + 4 * lane + 256 * j);
; #pragma unroll
;         for (int r = 0; r < R; ++r) d[r][j] = b[r][j] + d[r][j] * r1[r] * gp; }
;     if (OUT_F32) { float* Y = C.out();
; #pragma unroll
;         for (int r = 0; r < R; ++r)
; #pragma unroll
;             for (int j = 0; j < 4; ++j) if (ok[r]) *(v4f*)(Y + (size_t)mr[r] * DM + 4 * lane + 256 * j) = d[r][j];
;     } else { float* rs = C.RS(); float t[R];
; #pragma unroll
;         for (int r = 0; r < R; ++r) { float s = 0.f;
; #pragma unroll
;             for (int j = 0; j < 4; ++j) s += ssq4(d[r][j]);
;             t[r] = s; }
; #pragma unroll
;         for (int r = 0; r < R; ++r) t[r] = wave_sum(t[r]) * (1.f / DM) + EPS;
	v_add_f32_e32 v128, v128, v136
	v_add_f32_e32 v130, v130, v137
	ds_bpermute_b32 v136, v188, v128
	ds_bpermute_b32 v137, v188, v130
	s_waitcnt lgkmcnt(0)
	v_add_f32_e32 v128, v128, v136
	v_add_f32_e32 v130, v130, v137
	v_fmamk_f32 v128, v128, 0x3a800000, v138
	v_fmamk_f32 v130, v130, 0x3a800000, v138
	s_nop 0
	v_rsq_f32_e32 v128, v128
	v_rsq_f32_e32 v130, v130
	s_nop 1
	s_waitcnt vmcnt(38)
	v_pk_mul_f32 v[96:97], v[128:129], v[96:97] op_sel_hi:[0,1]
	v_pk_mul_f32 v[98:99], v[128:129], v[98:99] op_sel_hi:[0,1]
	v_pk_mul_f32 v[100:101], v[128:129], v[100:101] op_sel_hi:[0,1]
	v_pk_mul_f32 v[102:103], v[128:129], v[102:103] op_sel_hi:[0,1]
	v_pk_mul_f32 v[104:105], v[128:129], v[104:105] op_sel_hi:[0,1]
	v_pk_mul_f32 v[106:107], v[128:129], v[106:107] op_sel_hi:[0,1]
	v_pk_mul_f32 v[108:109], v[128:129], v[108:109] op_sel_hi:[0,1]
	v_pk_mul_f32 v[110:111], v[128:129], v[110:111] op_sel_hi:[0,1]
	v_pk_mul_f32 v[96:97], v[96:97], v[192:193]
	v_pk_mul_f32 v[98:99], v[98:99], v[194:195]
	v_pk_mul_f32 v[100:101], v[100:101], v[196:197]
	v_pk_mul_f32 v[102:103], v[102:103], v[198:199]
	v_pk_mul_f32 v[104:105], v[104:105], v[200:201]
	v_pk_mul_f32 v[106:107], v[106:107], v[202:203]
	v_pk_mul_f32 v[108:109], v[108:109], v[204:205]
	v_pk_mul_f32 v[110:111], v[110:111], v[206:207]
	v_lshlrev_b32_e32 v20, 16, v36
	v_and_b32_e32 v21, 0xffff0000, v36
	v_lshlrev_b32_e32 v22, 16, v37
	v_and_b32_e32 v23, 0xffff0000, v37
	v_lshlrev_b32_e32 v24, 16, v38
	v_and_b32_e32 v25, 0xffff0000, v38
	v_lshlrev_b32_e32 v26, 16, v39
	v_and_b32_e32 v27, 0xffff0000, v39
	v_pk_fma_f32 v[96:97], v[52:53], v[20:21], v[96:97] op_sel_hi:[0,1,1]
	v_pk_fma_f32 v[98:99], v[52:53], v[22:23], v[98:99] op_sel_hi:[0,1,1]
	v_pk_fma_f32 v[100:101], v[52:53], v[24:25], v[100:101] op_sel_hi:[0,1,1]
	v_pk_fma_f32 v[102:103], v[52:53], v[26:27], v[102:103] op_sel_hi:[0,1,1]
	v_lshlrev_b32_e32 v20, 16, v40
	v_and_b32_e32 v21, 0xffff0000, v40
	v_lshlrev_b32_e32 v22, 16, v41
	v_and_b32_e32 v23, 0xffff0000, v41
	v_lshlrev_b32_e32 v24, 16, v42
	v_and_b32_e32 v25, 0xffff0000, v42
	v_lshlrev_b32_e32 v26, 16, v43
	v_and_b32_e32 v27, 0xffff0000, v43
	v_pk_fma_f32 v[104:105], v[52:53], v[20:21], v[104:105] op_sel_hi:[0,1,1]
	v_pk_fma_f32 v[106:107], v[52:53], v[22:23], v[106:107] op_sel_hi:[0,1,1]
	v_pk_fma_f32 v[108:109], v[52:53], v[24:25], v[108:109] op_sel_hi:[0,1,1]
	v_pk_fma_f32 v[110:111], v[52:53], v[26:27], v[110:111] op_sel_hi:[0,1,1]
	v_pk_mul_f32 v[132:133], v[96:97], v[96:97]
	v_pk_fma_f32 v[132:133], v[98:99], v[98:99], v[132:133]
	v_pk_fma_f32 v[132:133], v[100:101], v[100:101], v[132:133]
	v_pk_fma_f32 v[132:133], v[102:103], v[102:103], v[132:133]
	v_pk_fma_f32 v[132:133], v[104:105], v[104:105], v[132:133]
	v_pk_fma_f32 v[132:133], v[106:107], v[106:107], v[132:133]
	v_pk_fma_f32 v[132:133], v[108:109], v[108:109], v[132:133]
	v_pk_fma_f32 v[132:133], v[110:111], v[110:111], v[132:133]
	s_nop 0
	v_add_f32_e32 v132, v132, v133
	v_pk_mul_f32 v[112:113], v[130:131], v[112:113] op_sel_hi:[0,1]
	v_pk_mul_f32 v[114:115], v[130:131], v[114:115] op_sel_hi:[0,1]
	v_pk_mul_f32 v[116:117], v[130:131], v[116:117] op_sel_hi:[0,1]
	v_pk_mul_f32 v[118:119], v[130:131], v[118:119] op_sel_hi:[0,1]
	v_pk_mul_f32 v[120:121], v[130:131], v[120:121] op_sel_hi:[0,1]
	v_pk_mul_f32 v[122:123], v[130:131], v[122:123] op_sel_hi:[0,1]
	v_pk_mul_f32 v[124:125], v[130:131], v[124:125] op_sel_hi:[0,1]
	v_pk_mul_f32 v[126:127], v[130:131], v[126:127] op_sel_hi:[0,1]
	v_pk_mul_f32 v[112:113], v[112:113], v[192:193]
	v_pk_mul_f32 v[114:115], v[114:115], v[194:195]
	v_pk_mul_f32 v[116:117], v[116:117], v[196:197]
	v_pk_mul_f32 v[118:119], v[118:119], v[198:199]
	v_pk_mul_f32 v[120:121], v[120:121], v[200:201]
	v_pk_mul_f32 v[122:123], v[122:123], v[202:203]
	v_pk_mul_f32 v[124:125], v[124:125], v[204:205]
	v_pk_mul_f32 v[126:127], v[126:127], v[206:207]
	v_lshlrev_b32_e32 v28, 16, v44
	v_and_b32_e32 v29, 0xffff0000, v44
	v_lshlrev_b32_e32 v30, 16, v45
	v_and_b32_e32 v31, 0xffff0000, v45
	v_lshlrev_b32_e32 v32, 16, v46
	v_and_b32_e32 v33, 0xffff0000, v46
	v_lshlrev_b32_e32 v34, 16, v47
	v_and_b32_e32 v35, 0xffff0000, v47
	v_pk_fma_f32 v[112:113], v[54:55], v[28:29], v[112:113] op_sel_hi:[0,1,1]
	v_pk_fma_f32 v[114:115], v[54:55], v[30:31], v[114:115] op_sel_hi:[0,1,1]
	v_pk_fma_f32 v[116:117], v[54:55], v[32:33], v[116:117] op_sel_hi:[0,1,1]
	v_pk_fma_f32 v[118:119], v[54:55], v[34:35], v[118:119] op_sel_hi:[0,1,1]
	v_lshlrev_b32_e32 v28, 16, v48
	v_and_b32_e32 v29, 0xffff0000, v48
	v_lshlrev_b32_e32 v30, 16, v49
	v_and_b32_e32 v31, 0xffff0000, v49
	v_lshlrev_b32_e32 v32, 16, v50
	v_and_b32_e32 v33, 0xffff0000, v50
	v_lshlrev_b32_e32 v34, 16, v51
	v_and_b32_e32 v35, 0xffff0000, v51
	v_pk_fma_f32 v[120:121], v[54:55], v[28:29], v[120:121] op_sel_hi:[0,1,1]
	v_pk_fma_f32 v[122:123], v[54:55], v[30:31], v[122:123] op_sel_hi:[0,1,1]
	v_pk_fma_f32 v[124:125], v[54:55], v[32:33], v[124:125] op_sel_hi:[0,1,1]
	v_pk_fma_f32 v[126:127], v[54:55], v[34:35], v[126:127] op_sel_hi:[0,1,1]
	v_pk_mul_f32 v[134:135], v[112:113], v[112:113]
	v_pk_fma_f32 v[134:135], v[114:115], v[114:115], v[134:135]
	v_pk_fma_f32 v[134:135], v[116:117], v[116:117], v[134:135]
	v_pk_fma_f32 v[134:135], v[118:119], v[118:119], v[134:135]
	v_pk_fma_f32 v[134:135], v[120:121], v[120:121], v[134:135]
	v_pk_fma_f32 v[134:135], v[122:123], v[122:123], v[134:135]
	v_pk_fma_f32 v[134:135], v[124:125], v[124:125], v[134:135]
	v_pk_fma_f32 v[134:135], v[126:127], v[126:127], v[134:135]
	s_nop 0
	v_add_f32_e32 v134, v134, v135
	global_load_dword v52, v172, s[98:99]
	global_load_dwordx2 v[20:21], v170, s[98:99]
	global_load_dwordx2 v[22:23], v170, s[98:99] offset:512
;     __device__ __forceinline__ float* out() const { return (float*)karg_in(33); }
; __device__ __forceinline__ const float* xrow_ptr(const Ctx& C, int row) { return row < MPROMPT ? C.in(0) + (size_t)row * DM : C.in(1) + (size_t)(row - MPROMPT) * DM; }
; template <int R, bool BASE_F32, bool OUT_F32>
; __device__ __forceinline__ void rows_res(const Ctx& C, int m0, int stride, int mx, const float* gpost, float scale, int lane) {
;     ...
;     for (int r = 0; r < R; ++r) { mr[r] = (r == 4) ? mx : m0 + r * stride; ok[r] = (r == 4) ? (mx < M) : (mr[r] < MPROMPT); const int mm = ok[r] ? mr[r] : 0;
; #pragma unroll
;         for (int j = 0; j < 4; ++j) d[r][j] = ld4_bf16(D + (size_t)mm * DM + 4 * lane + 256 * j);
;         if (BASE_F32) { const float* x = xrow_ptr(C, mm);
; #pragma unroll
;             for (int j = 0; j < 4; ++j) b[r][j] = ld4_f32(x + 4 * lane + 256 * j);
;         } else { const float inv = C.RS()[mm];
; #pragma unroll
;             for (int j = 0; j < 4; ++j) b[r][j] = ld4_bf16(XN + (size_t)mm * DM + 4 * lane + 256 * j) * inv;
;         } }
; #pragma unroll
;     for (int r = 0; r < R; ++r) { float s = 0.f;
; #pragma unroll
;         for (int j = 0; j < 4; ++j) s += ssq4(d[r][j]);
;         r1[r] = s; }
; #pragma unroll
;     for (int r = 0; r < R; ++r) r1[r] = rsqrtf(wave_sum(r1[r]) * (1.f / DM) + EPS) * scale;
; #pragma unroll
;     for (int j = 0; j < 4; ++j) { const v4f gp = ld4_f32(gpost + 4 * lane + 256 * j);
; #pragma unroll
;         for (int r = 0; r < R; ++r) d[r][j] = b[r][j] + d[r][j] * r1[r] * gp; }
;     if (OUT_F32) { float* Y = C.out();
; #pragma unroll
;         for (int r = 0; r < R; ++r)
; #pragma unroll
;             for (int j = 0; j < 4; ++j) if (ok[r]) *(v4f*)(Y + (size_t)mr[r] * DM + 4 * lane + 256 * j) = d[r][j];
;     } else { float* rs = C.RS(); float t[R];
; #pragma unroll
;         for (int r = 0; r < R; ++r) { float s = 0.f;
; #pragma unroll
;             for (int j = 0; j < 4; ++j) s += ssq4(d[r][j]);
;             t[r] = s; }
; #pragma unroll
;         for (int r = 0; r < R; ++r) t[r] = wave_sum(t[r]) * (1.f / DM) + EPS;
; #pragma unroll
;         for (int r = 0; r < R; ++r) { const float rstd = rsqrtf(t[r]);
; #pragma unroll
;             for (int j = 0; j < 4; ++j) if (ok[r]) st4_bf16(XN + (size_t)mr[r] * DM + 4 * lane + 256 * j, d[r][j] * rstd);
;             if (lane == 0 && ok[r]) rs[mr[r]] = sqrtf(t[r]); }
	global_load_dwordx2 v[24:25], v170, s[98:99] offset:1024
	global_load_dwordx2 v[26:27], v170, s[98:99] offset:1536
	global_load_dwordx2 v[36:37], v171, s[98:99]
	global_load_dwordx2 v[38:39], v171, s[98:99] offset:512
	global_load_dwordx2 v[40:41], v171, s[98:99] offset:1024
	global_load_dwordx2 v[42:43], v171, s[98:99] offset:1536
	v_add_u32_e32 v170, 0x400000, v170
	v_add_u32_e32 v171, 0x400000, v171
	v_add_u32_e32 v172, 0x2000, v172
	global_load_dword v54, v172, s[98:99]
	global_load_dwordx2 v[28:29], v170, s[98:99]
	global_load_dwordx2 v[30:31], v170, s[98:99] offset:512
	global_load_dwordx2 v[32:33], v170, s[98:99] offset:1024
	global_load_dwordx2 v[34:35], v170, s[98:99] offset:1536
	global_load_dwordx2 v[44:45], v171, s[98:99]
	global_load_dwordx2 v[46:47], v171, s[98:99] offset:512
	global_load_dwordx2 v[48:49], v171, s[98:99] offset:1024
	global_load_dwordx2 v[50:51], v171, s[98:99] offset:1536
	v_add_u32_e32 v170, 0x400000, v170
	v_add_u32_e32 v171, 0x400000, v171
	v_add_u32_e32 v172, 0x2000, v172
	s_nop 1
	v_add_f32_dpp v132, v132, v132 quad_perm:[1,0,3,2] row_mask:0xf bank_mask:0xf
	v_add_f32_dpp v134, v134, v134 quad_perm:[1,0,3,2] row_mask:0xf bank_mask:0xf
	s_nop 0
	v_add_f32_dpp v132, v132, v132 quad_perm:[2,3,0,1] row_mask:0xf bank_mask:0xf
	v_add_f32_dpp v134, v134, v134 quad_perm:[2,3,0,1] row_mask:0xf bank_mask:0xf
	s_nop 0
	v_add_f32_dpp v132, v132, v132 row_half_mirror row_mask:0xf bank_mask:0xf
	v_add_f32_dpp v134, v134, v134 row_half_mirror row_mask:0xf bank_mask:0xf
	s_nop 0
	v_add_f32_dpp v132, v132, v132 row_mirror row_mask:0xf bank_mask:0xf
	v_add_f32_dpp v134, v134, v134 row_mirror row_mask:0xf bank_mask:0xf
	s_nop 0
	ds_bpermute_b32 v136, v187, v132
	ds_bpermute_b32 v137, v187, v134
	s_waitcnt lgkmcnt(0)
	v_add_f32_e32 v132, v132, v136
	v_add_f32_e32 v134, v134, v137
	ds_bpermute_b32 v136, v188, v132
	ds_bpermute_b32 v137, v188, v134
	s_waitcnt lgkmcnt(0)
	v_add_f32_e32 v132, v132, v136
	v_add_f32_e32 v134, v134, v137
	v_fmamk_f32 v164, v132, 0x3a800000, v138
	v_fmamk_f32 v167, v134, 0x3a800000, v138
	s_nop 0
	v_rsq_f32_e32 v132, v164
	v_rsq_f32_e32 v134, v167
	v_sqrt_f32_e32 v165, v164
	v_sqrt_f32_e32 v168, v167
	s_nop 1
	v_pk_mul_f32 v[140:141], v[96:97], v[132:133] op_sel_hi:[1,0]
	v_cvt_pk_bf16_f32 v148, v140, v141
	v_pk_mul_f32 v[142:143], v[98:99], v[132:133] op_sel_hi:[1,0]
	v_cvt_pk_bf16_f32 v149, v142, v143
	v_pk_mul_f32 v[144:145], v[100:101], v[132:133] op_sel_hi:[1,0]
	v_cvt_pk_bf16_f32 v150, v144, v145
	v_pk_mul_f32 v[146:147], v[102:103], v[132:133] op_sel_hi:[1,0]
	v_cvt_pk_bf16_f32 v151, v146, v147
	v_pk_mul_f32 v[140:141], v[104:105], v[132:133] op_sel_hi:[1,0]
	v_cvt_pk_bf16_f32 v152, v140, v141
	v_pk_mul_f32 v[142:143], v[106:107], v[132:133] op_sel_hi:[1,0]
	v_cvt_pk_bf16_f32 v153, v142, v143
	v_pk_mul_f32 v[144:145], v[108:109], v[132:133] op_sel_hi:[1,0]
	v_cvt_pk_bf16_f32 v154, v144, v145
	v_pk_mul_f32 v[146:147], v[110:111], v[132:133] op_sel_hi:[1,0]
	v_cvt_pk_bf16_f32 v155, v146, v147
	global_store_dwordx2 v173, v[148:149], s[98:99]
	global_store_dwordx2 v173, v[150:151], s[98:99] offset:512
	global_store_dwordx2 v173, v[152:153], s[98:99] offset:1024
	global_store_dwordx2 v173, v[154:155], s[98:99] offset:1536
	v_add_u32_e32 v173, 0x400000, v173
	v_pk_mul_f32 v[140:141], v[112:113], v[134:135] op_sel_hi:[1,0]
	v_cvt_pk_bf16_f32 v156, v140, v141
	v_pk_mul_f32 v[142:143], v[114:115], v[134:135] op_sel_hi:[1,0]
	v_cvt_pk_bf16_f32 v157, v142, v143
	v_pk_mul_f32 v[144:145], v[116:117], v[134:135] op_sel_hi:[1,0]
	v_cvt_pk_bf16_f32 v158, v144, v145
	v_pk_mul_f32 v[146:147], v[118:119], v[134:135] op_sel_hi:[1,0]
	v_cvt_pk_bf16_f32 v159, v146, v147
	v_pk_mul_f32 v[140:141], v[120:121], v[134:135] op_sel_hi:[1,0]
	v_cvt_pk_bf16_f32 v160, v140, v141
	v_pk_mul_f32 v[142:143], v[122:123], v[134:135] op_sel_hi:[1,0]
	v_cvt_pk_bf16_f32 v161, v142, v143
	v_pk_mul_f32 v[144:145], v[124:125], v[134:135] op_sel_hi:[1,0]
	v_cvt_pk_bf16_f32 v162, v144, v145
	v_pk_mul_f32 v[146:147], v[126:127], v[134:135] op_sel_hi:[1,0]
	v_cvt_pk_bf16_f32 v163, v146, v147
	global_store_dwordx2 v173, v[156:157], s[98:99]
	global_store_dwordx2 v173, v[158:159], s[98:99] offset:512
	global_store_dwordx2 v173, v[160:161], s[98:99] offset:1024
	global_store_dwordx2 v173, v[162:163], s[98:99] offset:1536
	v_add_u32_e32 v173, 0x400000, v173
	v_add_u32_e32 v166, -1, v165
	v_fma_f32 v140, -v166, v165, v164
	v_cmp_ge_f32_e32 vcc, 0, v140
	v_add_u32_e32 v141, 1, v165
	v_cndmask_b32_e32 v166, v165, v166, vcc
	v_fma_f32 v140, -v141, v165, v164
	v_cmp_lt_f32_e32 vcc, 0, v140
	s_nop 1
	v_cndmask_b32_e32 v165, v166, v141, vcc
	v_add_u32_e32 v169, -1, v168
	v_fma_f32 v142, -v169, v168, v167
	v_cmp_ge_f32_e32 vcc, 0, v142
	v_add_u32_e32 v143, 1, v168
	v_cndmask_b32_e32 v169, v168, v169, vcc
	v_fma_f32 v142, -v143, v168, v167
	v_cmp_lt_f32_e32 vcc, 0, v142
	s_nop 1
	v_cndmask_b32_e32 v168, v169, v143, vcc
	s_mov_b64 exec, 1
	global_store_dword v174, v165, s[98:99]
	v_add_u32_e32 v174, 0x2000, v174
	global_store_dword v174, v168, s[98:99]
	v_add_u32_e32 v174, 0x2000, v174
	s_mov_b64 exec, -1
	s_waitcnt vmcnt(51)
;     __device__ __forceinline__ float* out() const { return (float*)karg_in(33); }
; __device__ __forceinline__ float ssq4(v4f v) { return (v.x * v.x + v.y * v.y) + (v.z * v.z + v.w * v.w); }
; template <int R, bool BASE_F32, bool OUT_F32>
; __device__ __forceinline__ void rows_res(const Ctx& C, int m0, int stride, int mx, const float* gpost, float scale, int lane) {
;     ...
;     for (int r = 0; r < R; ++r) { float s = 0.f;
; #pragma unroll
;         for (int j = 0; j < 4; ++j) s += ssq4(d[r][j]);
;         r1[r] = s; }
; #pragma unroll
;     for (int r = 0; r < R; ++r) r1[r] = rsqrtf(wave_sum(r1[r]) * (1.f / DM) + EPS) * scale;
; #pragma unroll
;     for (int j = 0; j < 4; ++j) { const v4f gp = ld4_f32(gpost + 4 * lane + 256 * j);
; #pragma unroll
;         for (int r = 0; r < R; ++r) d[r][j] = b[r][j] + d[r][j] * r1[r] * gp; }
;     if (OUT_F32) { float* Y = C.out();
; #pragma unroll
;         for (int r = 0; r < R; ++r)
; #pragma unroll
;             for (int j = 0; j < 4; ++j) if (ok[r]) *(v4f*)(Y + (size_t)mr[r] * DM + 4 * lane + 256 * j) = d[r][j];
;     } else { float* rs = C.RS(); float t[R];
; #pragma unroll
;         for (int r = 0; r < R; ++r) { float s = 0.f;
; #pragma unroll
;             for (int j = 0; j < 4; ++j) s += ssq4(d[r][j]);
;             t[r] = s; }
; #pragma unroll
;         for (int r = 0; r < R; ++r) t[r] = wave_sum(t[r]) * (1.f / DM) + EPS;
	v_lshlrev_b32_e32 v96, 16, v56
	v_and_b32_e32 v97, 0xffff0000, v56
	v_lshlrev_b32_e32 v98, 16, v57
	v_and_b32_e32 v99, 0xffff0000, v57
	v_lshlrev_b32_e32 v100, 16, v58
	v_and_b32_e32 v101, 0xffff0000, v58
	v_lshlrev_b32_e32 v102, 16, v59
	v_and_b32_e32 v103, 0xffff0000, v59
	v_lshlrev_b32_e32 v104, 16, v60
	v_and_b32_e32 v105, 0xffff0000, v60
	v_lshlrev_b32_e32 v106, 16, v61
	v_and_b32_e32 v107, 0xffff0000, v61
	v_lshlrev_b32_e32 v108, 16, v62
	v_and_b32_e32 v109, 0xffff0000, v62
	v_lshlrev_b32_e32 v110, 16, v63
	v_and_b32_e32 v111, 0xffff0000, v63
	v_pk_mul_f32 v[128:129], v[96:97], v[96:97]
	v_pk_fma_f32 v[128:129], v[98:99], v[98:99], v[128:129]
	v_pk_fma_f32 v[128:129], v[100:101], v[100:101], v[128:129]
	v_pk_fma_f32 v[128:129], v[102:103], v[102:103], v[128:129]
	v_pk_fma_f32 v[128:129], v[104:105], v[104:105], v[128:129]
	v_pk_fma_f32 v[128:129], v[106:107], v[106:107], v[128:129]
	v_pk_fma_f32 v[128:129], v[108:109], v[108:109], v[128:129]
	v_pk_fma_f32 v[128:129], v[110:111], v[110:111], v[128:129]
	s_nop 0
	v_add_f32_e32 v128, v128, v129
	s_waitcnt vmcnt(42)
	v_lshlrev_b32_e32 v112, 16, v64
	v_and_b32_e32 v113, 0xffff0000, v64
	v_lshlrev_b32_e32 v114, 16, v65
	v_and_b32_e32 v115, 0xffff0000, v65
	v_lshlrev_b32_e32 v116, 16, v66
	v_and_b32_e32 v117, 0xffff0000, v66
	v_lshlrev_b32_e32 v118, 16, v67
	v_and_b32_e32 v119, 0xffff0000, v67
	v_lshlrev_b32_e32 v120, 16, v68
	v_and_b32_e32 v121, 0xffff0000, v68
	v_lshlrev_b32_e32 v122, 16, v69
	v_and_b32_e32 v123, 0xffff0000, v69
	v_lshlrev_b32_e32 v124, 16, v70
	v_and_b32_e32 v125, 0xffff0000, v70
	v_lshlrev_b32_e32 v126, 16, v71
	v_and_b32_e32 v127, 0xffff0000, v71
	v_pk_mul_f32 v[130:131], v[112:113], v[112:113]
	v_pk_fma_f32 v[130:131], v[114:115], v[114:115], v[130:131]
	v_pk_fma_f32 v[130:131], v[116:117], v[116:117], v[130:131]
	v_pk_fma_f32 v[130:131], v[118:119], v[118:119], v[130:131]
	v_pk_fma_f32 v[130:131], v[120:121], v[120:121], v[130:131]
	v_pk_fma_f32 v[130:131], v[122:123], v[122:123], v[130:131]
	v_pk_fma_f32 v[130:131], v[124:125], v[124:125], v[130:131]
	v_pk_fma_f32 v[130:131], v[126:127], v[126:127], v[130:131]
	s_nop 0
	v_add_f32_e32 v130, v130, v131
	s_nop 1
	v_add_f32_dpp v128, v128, v128 quad_perm:[1,0,3,2] row_mask:0xf bank_mask:0xf
	v_add_f32_dpp v130, v130, v130 quad_perm:[1,0,3,2] row_mask:0xf bank_mask:0xf
	s_nop 0
	v_add_f32_dpp v128, v128, v128 quad_perm:[2,3,0,1] row_mask:0xf bank_mask:0xf
	v_add_f32_dpp v130, v130, v130 quad_perm:[2,3,0,1] row_mask:0xf bank_mask:0xf
	s_nop 0
	v_add_f32_dpp v128, v128, v128 row_half_mirror row_mask:0xf bank_mask:0xf
	v_add_f32_dpp v130, v130, v130 row_half_mirror row_mask:0xf bank_mask:0xf
	s_nop 0
	v_add_f32_dpp v128, v128, v128 row_mirror row_mask:0xf bank_mask:0xf
	v_add_f32_dpp v130, v130, v130 row_mirror row_mask:0xf bank_mask:0xf
	s_nop 0
	ds_bpermute_b32 v136, v187, v128
	ds_bpermute_b32 v137, v187, v130
	s_waitcnt lgkmcnt(0)
	v_add_f32_e32 v128, v128, v136
	v_add_f32_e32 v130, v130, v137
	ds_bpermute_b32 v136, v188, v128
	ds_bpermute_b32 v137, v188, v130
	s_waitcnt lgkmcnt(0)
	v_add_f32_e32 v128, v128, v136
	v_add_f32_e32 v130, v130, v137
	v_fmamk_f32 v128, v128, 0x3a800000, v138
	v_fmamk_f32 v130, v130, 0x3a800000, v138
	s_nop 0
	v_rsq_f32_e32 v128, v128
	v_rsq_f32_e32 v130, v130
	s_nop 1
	s_waitcnt vmcnt(38)
	v_pk_mul_f32 v[96:97], v[128:129], v[96:97] op_sel_hi:[0,1]
	v_pk_mul_f32 v[98:99], v[128:129], v[98:99] op_sel_hi:[0,1]
	v_pk_mul_f32 v[100:101], v[128:129], v[100:101] op_sel_hi:[0,1]
	v_pk_mul_f32 v[102:103], v[128:129], v[102:103] op_sel_hi:[0,1]
	v_pk_mul_f32 v[104:105], v[128:129], v[104:105] op_sel_hi:[0,1]
	v_pk_mul_f32 v[106:107], v[128:129], v[106:107] op_sel_hi:[0,1]
	v_pk_mul_f32 v[108:109], v[128:129], v[108:109] op_sel_hi:[0,1]
	v_pk_mul_f32 v[110:111], v[128:129], v[110:111] op_sel_hi:[0,1]
	v_pk_mul_f32 v[96:97], v[96:97], v[192:193]
	v_pk_mul_f32 v[98:99], v[98:99], v[194:195]
	v_pk_mul_f32 v[100:101], v[100:101], v[196:197]
	v_pk_mul_f32 v[102:103], v[102:103], v[198:199]
	v_pk_mul_f32 v[104:105], v[104:105], v[200:201]
	v_pk_mul_f32 v[106:107], v[106:107], v[202:203]
	v_pk_mul_f32 v[108:109], v[108:109], v[204:205]
	v_pk_mul_f32 v[110:111], v[110:111], v[206:207]
	v_lshlrev_b32_e32 v56, 16, v72
	v_and_b32_e32 v57, 0xffff0000, v72
	v_lshlrev_b32_e32 v58, 16, v73
	v_and_b32_e32 v59, 0xffff0000, v73
	v_lshlrev_b32_e32 v60, 16, v74
	v_and_b32_e32 v61, 0xffff0000, v74
	v_lshlrev_b32_e32 v62, 16, v75
	v_and_b32_e32 v63, 0xffff0000, v75
	v_pk_fma_f32 v[96:97], v[88:89], v[56:57], v[96:97] op_sel_hi:[0,1,1]
	v_pk_fma_f32 v[98:99], v[88:89], v[58:59], v[98:99] op_sel_hi:[0,1,1]
	v_pk_fma_f32 v[100:101], v[88:89], v[60:61], v[100:101] op_sel_hi:[0,1,1]
	v_pk_fma_f32 v[102:103], v[88:89], v[62:63], v[102:103] op_sel_hi:[0,1,1]
	v_lshlrev_b32_e32 v56, 16, v76
	v_and_b32_e32 v57, 0xffff0000, v76
	v_lshlrev_b32_e32 v58, 16, v77
	v_and_b32_e32 v59, 0xffff0000, v77
	v_lshlrev_b32_e32 v60, 16, v78
	v_and_b32_e32 v61, 0xffff0000, v78
	v_lshlrev_b32_e32 v62, 16, v79
	v_and_b32_e32 v63, 0xffff0000, v79
	v_pk_fma_f32 v[104:105], v[88:89], v[56:57], v[104:105] op_sel_hi:[0,1,1]
	v_pk_fma_f32 v[106:107], v[88:89], v[58:59], v[106:107] op_sel_hi:[0,1,1]
	v_pk_fma_f32 v[108:109], v[88:89], v[60:61], v[108:109] op_sel_hi:[0,1,1]
	v_pk_fma_f32 v[110:111], v[88:89], v[62:63], v[110:111] op_sel_hi:[0,1,1]
	v_pk_mul_f32 v[132:133], v[96:97], v[96:97]
	v_pk_fma_f32 v[132:133], v[98:99], v[98:99], v[132:133]
	v_pk_fma_f32 v[132:133], v[100:101], v[100:101], v[132:133]
	v_pk_fma_f32 v[132:133], v[102:103], v[102:103], v[132:133]
	v_pk_fma_f32 v[132:133], v[104:105], v[104:105], v[132:133]
;     __device__ __forceinline__ float* out() const { return (float*)karg_in(33); }
; __device__ __forceinline__ const float* xrow_ptr(const Ctx& C, int row) { return row < MPROMPT ? C.in(0) + (size_t)row * DM : C.in(1) + (size_t)(row - MPROMPT) * DM; }
; __device__ __forceinline__ v4f ld4_bf16(const bf16* p) { const v2u w = *(const v2u*)p; return (v4f){bf_lo(w.x), bf_hi(w.x), bf_lo(w.y), bf_hi(w.y)}; }
; __device__ __forceinline__ float ssq4(v4f v) { return (v.x * v.x + v.y * v.y) + (v.z * v.z + v.w * v.w); }
; template <int R, bool BASE_F32, bool OUT_F32>
; __device__ __forceinline__ void rows_res(const Ctx& C, int m0, int stride, int mx, const float* gpost, float scale, int lane) {
;     ...
;     for (int r = 0; r < R; ++r) { mr[r] = (r == 4) ? mx : m0 + r * stride; ok[r] = (r == 4) ? (mx < M) : (mr[r] < MPROMPT); const int mm = ok[r] ? mr[r] : 0;
; #pragma unroll
;         for (int j = 0; j < 4; ++j) d[r][j] = ld4_bf16(D + (size_t)mm * DM + 4 * lane + 256 * j);
;         if (BASE_F32) { const float* x = xrow_ptr(C, mm);
; #pragma unroll
;             for (int j = 0; j < 4; ++j) b[r][j] = ld4_f32(x + 4 * lane + 256 * j);
;         } else { const float inv = C.RS()[mm];
; #pragma unroll
;             for (int j = 0; j < 4; ++j) b[r][j] = ld4_bf16(XN + (size_t)mm * DM + 4 * lane + 256 * j) * inv;
;         } }
; #pragma unroll
;     for (int r = 0; r < R; ++r) { float s = 0.f;
; #pragma unroll
;         for (int j = 0; j < 4; ++j) s += ssq4(d[r][j]);
;         r1[r] = s; }
; #pragma unroll
;     for (int r = 0; r < R; ++r) r1[r] = rsqrtf(wave_sum(r1[r]) * (1.f / DM) + EPS) * scale;
; #pragma unroll
;     for (int j = 0; j < 4; ++j) { const v4f gp = ld4_f32(gpost + 4 * lane + 256 * j);
; #pragma unroll
;         for (int r = 0; r < R; ++r) d[r][j] = b[r][j] + d[r][j] * r1[r] * gp; }
;     if (OUT_F32) { float* Y = C.out();
; #pragma unroll
;         for (int r = 0; r < R; ++r)
; #pragma unroll
;             for (int j = 0; j < 4; ++j) if (ok[r]) *(v4f*)(Y + (size_t)mr[r] * DM + 4 * lane + 256 * j) = d[r][j];
;     } else { float* rs = C.RS(); float t[R];
; #pragma unroll
;         for (int r = 0; r < R; ++r) { float s = 0.f;
; #pragma unroll
;             for (int j = 0; j < 4; ++j) s += ssq4(d[r][j]);
;             t[r] = s; }
; #pragma unroll
;         for (int r = 0; r < R; ++r) t[r] = wave_sum(t[r]) * (1.f / DM) + EPS;
	v_pk_fma_f32 v[132:133], v[106:107], v[106:107], v[132:133]
	v_pk_fma_f32 v[132:133], v[108:109], v[108:109], v[132:133]
	v_pk_fma_f32 v[132:133], v[110:111], v[110:111], v[132:133]
	s_nop 0
	v_add_f32_e32 v132, v132, v133
	v_pk_mul_f32 v[112:113], v[130:131], v[112:113] op_sel_hi:[0,1]
	v_pk_mul_f32 v[114:115], v[130:131], v[114:115] op_sel_hi:[0,1]
	v_pk_mul_f32 v[116:117], v[130:131], v[116:117] op_sel_hi:[0,1]
	v_pk_mul_f32 v[118:119], v[130:131], v[118:119] op_sel_hi:[0,1]
	v_pk_mul_f32 v[120:121], v[130:131], v[120:121] op_sel_hi:[0,1]
	v_pk_mul_f32 v[122:123], v[130:131], v[122:123] op_sel_hi:[0,1]
	v_pk_mul_f32 v[124:125], v[130:131], v[124:125] op_sel_hi:[0,1]
	v_pk_mul_f32 v[126:127], v[130:131], v[126:127] op_sel_hi:[0,1]
	v_pk_mul_f32 v[112:113], v[112:113], v[192:193]
	v_pk_mul_f32 v[114:115], v[114:115], v[194:195]
	v_pk_mul_f32 v[116:117], v[116:117], v[196:197]
	v_pk_mul_f32 v[118:119], v[118:119], v[198:199]
	v_pk_mul_f32 v[120:121], v[120:121], v[200:201]
	v_pk_mul_f32 v[122:123], v[122:123], v[202:203]
	v_pk_mul_f32 v[124:125], v[124:125], v[204:205]
	v_pk_mul_f32 v[126:127], v[126:127], v[206:207]
	v_lshlrev_b32_e32 v64, 16, v80
	v_and_b32_e32 v65, 0xffff0000, v80
	v_lshlrev_b32_e32 v66, 16, v81
	v_and_b32_e32 v67, 0xffff0000, v81
	v_lshlrev_b32_e32 v68, 16, v82
	v_and_b32_e32 v69, 0xffff0000, v82
	v_lshlrev_b32_e32 v70, 16, v83
	v_and_b32_e32 v71, 0xffff0000, v83
	v_pk_fma_f32 v[112:113], v[90:91], v[64:65], v[112:113] op_sel_hi:[0,1,1]
	v_pk_fma_f32 v[114:115], v[90:91], v[66:67], v[114:115] op_sel_hi:[0,1,1]
	v_pk_fma_f32 v[116:117], v[90:91], v[68:69], v[116:117] op_sel_hi:[0,1,1]
	v_pk_fma_f32 v[118:119], v[90:91], v[70:71], v[118:119] op_sel_hi:[0,1,1]
	v_lshlrev_b32_e32 v64, 16, v84
	v_and_b32_e32 v65, 0xffff0000, v84
	v_lshlrev_b32_e32 v66, 16, v85
	v_and_b32_e32 v67, 0xffff0000, v85
	v_lshlrev_b32_e32 v68, 16, v86
	v_and_b32_e32 v69, 0xffff0000, v86
	v_lshlrev_b32_e32 v70, 16, v87
	v_and_b32_e32 v71, 0xffff0000, v87
	v_pk_fma_f32 v[120:121], v[90:91], v[64:65], v[120:121] op_sel_hi:[0,1,1]
	v_pk_fma_f32 v[122:123], v[90:91], v[66:67], v[122:123] op_sel_hi:[0,1,1]
	v_pk_fma_f32 v[124:125], v[90:91], v[68:69], v[124:125] op_sel_hi:[0,1,1]
	v_pk_fma_f32 v[126:127], v[90:91], v[70:71], v[126:127] op_sel_hi:[0,1,1]
	v_pk_mul_f32 v[134:135], v[112:113], v[112:113]
	v_pk_fma_f32 v[134:135], v[114:115], v[114:115], v[134:135]
	v_pk_fma_f32 v[134:135], v[116:117], v[116:117], v[134:135]
	v_pk_fma_f32 v[134:135], v[118:119], v[118:119], v[134:135]
	v_pk_fma_f32 v[134:135], v[120:121], v[120:121], v[134:135]
	v_pk_fma_f32 v[134:135], v[122:123], v[122:123], v[134:135]
	v_pk_fma_f32 v[134:135], v[124:125], v[124:125], v[134:135]
	v_pk_fma_f32 v[134:135], v[126:127], v[126:127], v[134:135]
	s_nop 0
	v_add_f32_e32 v134, v134, v135
	global_load_dword v88, v172, s[98:99]
	global_load_dwordx2 v[56:57], v170, s[98:99]
	global_load_dwordx2 v[58:59], v170, s[98:99] offset:512
	global_load_dwordx2 v[60:61], v170, s[98:99] offset:1024
	global_load_dwordx2 v[62:63], v170, s[98:99] offset:1536
	global_load_dwordx2 v[72:73], v171, s[98:99]
	global_load_dwordx2 v[74:75], v171, s[98:99] offset:512
	global_load_dwordx2 v[76:77], v171, s[98:99] offset:1024
	global_load_dwordx2 v[78:79], v171, s[98:99] offset:1536
	v_add_u32_e32 v170, 0x400000, v170
	v_add_u32_e32 v171, 0x400000, v171
	v_add_u32_e32 v172, 0x2000, v172
	global_load_dword v90, v172, s[98:99]
	global_load_dwordx2 v[64:65], v170, s[98:99]
	global_load_dwordx2 v[66:67], v170, s[98:99] offset:512
	global_load_dwordx2 v[68:69], v170, s[98:99] offset:1024
	global_load_dwordx2 v[70:71], v170, s[98:99] offset:1536
	global_load_dwordx2 v[80:81], v171, s[98:99]
	global_load_dwordx2 v[82:83], v171, s[98:99] offset:512
	global_load_dwordx2 v[84:85], v171, s[98:99] offset:1024
	global_load_dwordx2 v[86:87], v171, s[98:99] offset:1536
	v_add_u32_e32 v170, 0x400000, v170
	v_add_u32_e32 v171, 0x400000, v171
	v_add_u32_e32 v172, 0x2000, v172
	s_nop 1
	v_add_f32_dpp v132, v132, v132 quad_perm:[1,0,3,2] row_mask:0xf bank_mask:0xf
	v_add_f32_dpp v134, v134, v134 quad_perm:[1,0,3,2] row_mask:0xf bank_mask:0xf
	s_nop 0
	v_add_f32_dpp v132, v132, v132 quad_perm:[2,3,0,1] row_mask:0xf bank_mask:0xf
	v_add_f32_dpp v134, v134, v134 quad_perm:[2,3,0,1] row_mask:0xf bank_mask:0xf
	s_nop 0
	v_add_f32_dpp v132, v132, v132 row_half_mirror row_mask:0xf bank_mask:0xf
	v_add_f32_dpp v134, v134, v134 row_half_mirror row_mask:0xf bank_mask:0xf
	s_nop 0
	v_add_f32_dpp v132, v132, v132 row_mirror row_mask:0xf bank_mask:0xf
	v_add_f32_dpp v134, v134, v134 row_mirror row_mask:0xf bank_mask:0xf
	s_nop 0
	ds_bpermute_b32 v136, v187, v132
	ds_bpermute_b32 v137, v187, v134
	s_waitcnt lgkmcnt(0)
	v_add_f32_e32 v132, v132, v136
	v_add_f32_e32 v134, v134, v137
	ds_bpermute_b32 v136, v188, v132
	ds_bpermute_b32 v137, v188, v134
	s_waitcnt lgkmcnt(0)
; __device__ __forceinline__ void st4_bf16(bf16* p, v4f o) { v2u w; w.x = cvt_pk_nv(o.x, o.y); w.y = cvt_pk_nv(o.z, o.w); *(v2u*)p = w; }
; __device__ __forceinline__ float ssq4(v4f v) { return (v.x * v.x + v.y * v.y) + (v.z * v.z + v.w * v.w); }
; template <int R, bool BASE_F32, bool OUT_F32>
; __device__ __forceinline__ void rows_res(const Ctx& C, int m0, int stride, int mx, const float* gpost, float scale, int lane) {
;     ...
;     for (int r = 0; r < R; ++r) { float s = 0.f;
; #pragma unroll
;         for (int j = 0; j < 4; ++j) s += ssq4(d[r][j]);
;         r1[r] = s; }
; #pragma unroll
;     for (int r = 0; r < R; ++r) r1[r] = rsqrtf(wave_sum(r1[r]) * (1.f / DM) + EPS) * scale;
;     ...
;         for (int r = 0; r < R; ++r) { float s = 0.f;
; #pragma unroll
;             for (int j = 0; j < 4; ++j) s += ssq4(d[r][j]);
;             t[r] = s; }
; #pragma unroll
;         for (int r = 0; r < R; ++r) t[r] = wave_sum(t[r]) * (1.f / DM) + EPS;
; #pragma unroll
;         for (int r = 0; r < R; ++r) { const float rstd = rsqrtf(t[r]);
; #pragma unroll
;             for (int j = 0; j < 4; ++j) if (ok[r]) st4_bf16(XN + (size_t)mr[r] * DM + 4 * lane + 256 * j, d[r][j] * rstd);
;             if (lane == 0 && ok[r]) rs[mr[r]] = sqrtf(t[r]); }
	v_add_f32_e32 v132, v132, v136
	v_add_f32_e32 v134, v134, v137
	v_fmamk_f32 v164, v132, 0x3a800000, v138
	v_fmamk_f32 v167, v134, 0x3a800000, v138
	s_nop 0
	v_rsq_f32_e32 v132, v164
	v_rsq_f32_e32 v134, v167
	v_sqrt_f32_e32 v165, v164
	v_sqrt_f32_e32 v168, v167
	s_nop 1
	v_pk_mul_f32 v[140:141], v[96:97], v[132:133] op_sel_hi:[1,0]
	v_cvt_pk_bf16_f32 v148, v140, v141
	v_pk_mul_f32 v[142:143], v[98:99], v[132:133] op_sel_hi:[1,0]
	v_cvt_pk_bf16_f32 v149, v142, v143
	v_pk_mul_f32 v[144:145], v[100:101], v[132:133] op_sel_hi:[1,0]
	v_cvt_pk_bf16_f32 v150, v144, v145
	v_pk_mul_f32 v[146:147], v[102:103], v[132:133] op_sel_hi:[1,0]
	v_cvt_pk_bf16_f32 v151, v146, v147
	v_pk_mul_f32 v[140:141], v[104:105], v[132:133] op_sel_hi:[1,0]
	v_cvt_pk_bf16_f32 v152, v140, v141
	v_pk_mul_f32 v[142:143], v[106:107], v[132:133] op_sel_hi:[1,0]
	v_cvt_pk_bf16_f32 v153, v142, v143
	v_pk_mul_f32 v[144:145], v[108:109], v[132:133] op_sel_hi:[1,0]
	v_cvt_pk_bf16_f32 v154, v144, v145
	v_pk_mul_f32 v[146:147], v[110:111], v[132:133] op_sel_hi:[1,0]
	v_cvt_pk_bf16_f32 v155, v146, v147
	global_store_dwordx2 v173, v[148:149], s[98:99]
	global_store_dwordx2 v173, v[150:151], s[98:99] offset:512
	global_store_dwordx2 v173, v[152:153], s[98:99] offset:1024
	global_store_dwordx2 v173, v[154:155], s[98:99] offset:1536
	v_add_u32_e32 v173, 0x400000, v173
	v_pk_mul_f32 v[140:141], v[112:113], v[134:135] op_sel_hi:[1,0]
	v_cvt_pk_bf16_f32 v156, v140, v141
	v_pk_mul_f32 v[142:143], v[114:115], v[134:135] op_sel_hi:[1,0]
	v_cvt_pk_bf16_f32 v157, v142, v143
	v_pk_mul_f32 v[144:145], v[116:117], v[134:135] op_sel_hi:[1,0]
	v_cvt_pk_bf16_f32 v158, v144, v145
	v_pk_mul_f32 v[146:147], v[118:119], v[134:135] op_sel_hi:[1,0]
	v_cvt_pk_bf16_f32 v159, v146, v147
	v_pk_mul_f32 v[140:141], v[120:121], v[134:135] op_sel_hi:[1,0]
	v_cvt_pk_bf16_f32 v160, v140, v141
	v_pk_mul_f32 v[142:143], v[122:123], v[134:135] op_sel_hi:[1,0]
	v_cvt_pk_bf16_f32 v161, v142, v143
	v_pk_mul_f32 v[144:145], v[124:125], v[134:135] op_sel_hi:[1,0]
	v_cvt_pk_bf16_f32 v162, v144, v145
	v_pk_mul_f32 v[146:147], v[126:127], v[134:135] op_sel_hi:[1,0]
	v_cvt_pk_bf16_f32 v163, v146, v147
	global_store_dwordx2 v173, v[156:157], s[98:99]
	global_store_dwordx2 v173, v[158:159], s[98:99] offset:512
	global_store_dwordx2 v173, v[160:161], s[98:99] offset:1024
	global_store_dwordx2 v173, v[162:163], s[98:99] offset:1536
	v_add_u32_e32 v173, 0x400000, v173
	v_add_u32_e32 v166, -1, v165
	v_fma_f32 v140, -v166, v165, v164
	v_cmp_ge_f32_e32 vcc, 0, v140
	v_add_u32_e32 v141, 1, v165
	v_cndmask_b32_e32 v166, v165, v166, vcc
	v_fma_f32 v140, -v141, v165, v164
	v_cmp_lt_f32_e32 vcc, 0, v140
	s_nop 1
	v_cndmask_b32_e32 v165, v166, v141, vcc
	v_add_u32_e32 v169, -1, v168
	v_fma_f32 v142, -v169, v168, v167
	v_cmp_ge_f32_e32 vcc, 0, v142
	v_add_u32_e32 v143, 1, v168
	v_cndmask_b32_e32 v169, v168, v169, vcc
	v_fma_f32 v142, -v143, v168, v167
	v_cmp_lt_f32_e32 vcc, 0, v142
	s_nop 1
	v_cndmask_b32_e32 v168, v169, v143, vcc
	s_mov_b64 exec, 1
	global_store_dword v174, v165, s[98:99]
	v_add_u32_e32 v174, 0x2000, v174
	global_store_dword v174, v168, s[98:99]
	v_add_u32_e32 v174, 0x2000, v174
	s_mov_b64 exec, -1
	s_waitcnt vmcnt(51)
	v_lshlrev_b32_e32 v96, 16, v20
	v_and_b32_e32 v97, 0xffff0000, v20
	v_lshlrev_b32_e32 v98, 16, v21
	v_and_b32_e32 v99, 0xffff0000, v21
	v_lshlrev_b32_e32 v100, 16, v22
	v_and_b32_e32 v101, 0xffff0000, v22
	v_lshlrev_b32_e32 v102, 16, v23
	v_and_b32_e32 v103, 0xffff0000, v23
	v_lshlrev_b32_e32 v104, 16, v24
	v_and_b32_e32 v105, 0xffff0000, v24
	v_lshlrev_b32_e32 v106, 16, v25
	v_and_b32_e32 v107, 0xffff0000, v25
	v_lshlrev_b32_e32 v108, 16, v26
	v_and_b32_e32 v109, 0xffff0000, v26
	v_lshlrev_b32_e32 v110, 16, v27
	v_and_b32_e32 v111, 0xffff0000, v27
	v_pk_mul_f32 v[128:129], v[96:97], v[96:97]
	v_pk_fma_f32 v[128:129], v[98:99], v[98:99], v[128:129]
	v_pk_fma_f32 v[128:129], v[100:101], v[100:101], v[128:129]
	v_pk_fma_f32 v[128:129], v[102:103], v[102:103], v[128:129]
	v_pk_fma_f32 v[128:129], v[104:105], v[104:105], v[128:129]
	v_pk_fma_f32 v[128:129], v[106:107], v[106:107], v[128:129]
	v_pk_fma_f32 v[128:129], v[108:109], v[108:109], v[128:129]
	v_pk_fma_f32 v[128:129], v[110:111], v[110:111], v[128:129]
	s_nop 0
	v_add_f32_e32 v128, v128, v129
	s_waitcnt vmcnt(42)
	v_lshlrev_b32_e32 v112, 16, v28
	v_and_b32_e32 v113, 0xffff0000, v28
	v_lshlrev_b32_e32 v114, 16, v29
	v_and_b32_e32 v115, 0xffff0000, v29
	v_lshlrev_b32_e32 v116, 16, v30
	v_and_b32_e32 v117, 0xffff0000, v30
	v_lshlrev_b32_e32 v118, 16, v31
	v_and_b32_e32 v119, 0xffff0000, v31
	v_lshlrev_b32_e32 v120, 16, v32
	v_and_b32_e32 v121, 0xffff0000, v32
	v_lshlrev_b32_e32 v122, 16, v33
	v_and_b32_e32 v123, 0xffff0000, v33
	v_lshlrev_b32_e32 v124, 16, v34
	v_and_b32_e32 v125, 0xffff0000, v34
	v_lshlrev_b32_e32 v126, 16, v35
	v_and_b32_e32 v127, 0xffff0000, v35
	v_pk_mul_f32 v[130:131], v[112:113], v[112:113]
	v_pk_fma_f32 v[130:131], v[114:115], v[114:115], v[130:131]
	v_pk_fma_f32 v[130:131], v[116:117], v[116:117], v[130:131]
	v_pk_fma_f32 v[130:131], v[118:119], v[118:119], v[130:131]
	v_pk_fma_f32 v[130:131], v[120:121], v[120:121], v[130:131]
	v_pk_fma_f32 v[130:131], v[122:123], v[122:123], v[130:131]
	v_pk_fma_f32 v[130:131], v[124:125], v[124:125], v[130:131]
	v_pk_fma_f32 v[130:131], v[126:127], v[126:127], v[130:131]
	s_nop 0
	v_add_f32_e32 v130, v130, v131
	s_nop 1
	v_add_f32_dpp v128, v128, v128 quad_perm:[1,0,3,2] row_mask:0xf bank_mask:0xf
	v_add_f32_dpp v130, v130, v130 quad_perm:[1,0,3,2] row_mask:0xf bank_mask:0xf
	s_nop 0
	v_add_f32_dpp v128, v128, v128 quad_perm:[2,3,0,1] row_mask:0xf bank_mask:0xf
	v_add_f32_dpp v130, v130, v130 quad_perm:[2,3,0,1] row_mask:0xf bank_mask:0xf
	s_nop 0
	v_add_f32_dpp v128, v128, v128 row_half_mirror row_mask:0xf bank_mask:0xf
	v_add_f32_dpp v130, v130, v130 row_half_mirror row_mask:0xf bank_mask:0xf
	s_nop 0
	v_add_f32_dpp v128, v128, v128 row_mirror row_mask:0xf bank_mask:0xf
	v_add_f32_dpp v130, v130, v130 row_mirror row_mask:0xf bank_mask:0xf
	s_nop 0
	ds_bpermute_b32 v136, v187, v128
	ds_bpermute_b32 v137, v187, v130
	s_waitcnt lgkmcnt(0)
;     __device__ __forceinline__ float* out() const { return (float*)karg_in(33); }
; __device__ __forceinline__ float ssq4(v4f v) { return (v.x * v.x + v.y * v.y) + (v.z * v.z + v.w * v.w); }
; template <int R, bool BASE_F32, bool OUT_F32>
; __device__ __forceinline__ void rows_res(const Ctx& C, int m0, int stride, int mx, const float* gpost, float scale, int lane) {
;     ...
;     for (int r = 0; r < R; ++r) { float s = 0.f;
; #pragma unroll
;         for (int j = 0; j < 4; ++j) s += ssq4(d[r][j]);
;         r1[r] = s; }
; #pragma unroll
;     for (int r = 0; r < R; ++r) r1[r] = rsqrtf(wave_sum(r1[r]) * (1.f / DM) + EPS) * scale;
; #pragma unroll
;     for (int j = 0; j < 4; ++j) { const v4f gp = ld4_f32(gpost + 4 * lane + 256 * j);
; #pragma unroll
;         for (int r = 0; r < R; ++r) d[r][j] = b[r][j] + d[r][j] * r1[r] * gp; }
;     if (OUT_F32) { float* Y = C.out();
; #pragma unroll
;         for (int r = 0; r < R; ++r)
; #pragma unroll
;             for (int j = 0; j < 4; ++j) if (ok[r]) *(v4f*)(Y + (size_t)mr[r] * DM + 4 * lane + 256 * j) = d[r][j];
;     } else { float* rs = C.RS(); float t[R];
; #pragma unroll
;         for (int r = 0; r < R; ++r) { float s = 0.f;
; #pragma unroll
;             for (int j = 0; j < 4; ++j) s += ssq4(d[r][j]);
;             t[r] = s; }
; #pragma unroll
;         for (int r = 0; r < R; ++r) t[r] = wave_sum(t[r]) * (1.f / DM) + EPS;
	v_add_f32_e32 v128, v128, v136
	v_add_f32_e32 v130, v130, v137
	ds_bpermute_b32 v136, v188, v128
	ds_bpermute_b32 v137, v188, v130
	s_waitcnt lgkmcnt(0)
	v_add_f32_e32 v128, v128, v136
	v_add_f32_e32 v130, v130, v137
	v_fmamk_f32 v128, v128, 0x3a800000, v138
	v_fmamk_f32 v130, v130, 0x3a800000, v138
	s_nop 0
	v_rsq_f32_e32 v128, v128
	v_rsq_f32_e32 v130, v130
	s_nop 1
	s_waitcnt vmcnt(38)
	v_pk_mul_f32 v[96:97], v[128:129], v[96:97] op_sel_hi:[0,1]
	v_pk_mul_f32 v[98:99], v[128:129], v[98:99] op_sel_hi:[0,1]
	v_pk_mul_f32 v[100:101], v[128:129], v[100:101] op_sel_hi:[0,1]
	v_pk_mul_f32 v[102:103], v[128:129], v[102:103] op_sel_hi:[0,1]
	v_pk_mul_f32 v[104:105], v[128:129], v[104:105] op_sel_hi:[0,1]
	v_pk_mul_f32 v[106:107], v[128:129], v[106:107] op_sel_hi:[0,1]
	v_pk_mul_f32 v[108:109], v[128:129], v[108:109] op_sel_hi:[0,1]
	v_pk_mul_f32 v[110:111], v[128:129], v[110:111] op_sel_hi:[0,1]
	v_pk_mul_f32 v[96:97], v[96:97], v[192:193]
	v_pk_mul_f32 v[98:99], v[98:99], v[194:195]
	v_pk_mul_f32 v[100:101], v[100:101], v[196:197]
	v_pk_mul_f32 v[102:103], v[102:103], v[198:199]
	v_pk_mul_f32 v[104:105], v[104:105], v[200:201]
	v_pk_mul_f32 v[106:107], v[106:107], v[202:203]
	v_pk_mul_f32 v[108:109], v[108:109], v[204:205]
	v_pk_mul_f32 v[110:111], v[110:111], v[206:207]
	v_lshlrev_b32_e32 v20, 16, v36
	v_and_b32_e32 v21, 0xffff0000, v36
	v_lshlrev_b32_e32 v22, 16, v37
	v_and_b32_e32 v23, 0xffff0000, v37
	v_lshlrev_b32_e32 v24, 16, v38
	v_and_b32_e32 v25, 0xffff0000, v38
	v_lshlrev_b32_e32 v26, 16, v39
	v_and_b32_e32 v27, 0xffff0000, v39
	v_pk_fma_f32 v[96:97], v[52:53], v[20:21], v[96:97] op_sel_hi:[0,1,1]
	v_pk_fma_f32 v[98:99], v[52:53], v[22:23], v[98:99] op_sel_hi:[0,1,1]
	v_pk_fma_f32 v[100:101], v[52:53], v[24:25], v[100:101] op_sel_hi:[0,1,1]
	v_pk_fma_f32 v[102:103], v[52:53], v[26:27], v[102:103] op_sel_hi:[0,1,1]
	v_lshlrev_b32_e32 v20, 16, v40
	v_and_b32_e32 v21, 0xffff0000, v40
	v_lshlrev_b32_e32 v22, 16, v41
	v_and_b32_e32 v23, 0xffff0000, v41
	v_lshlrev_b32_e32 v24, 16, v42
	v_and_b32_e32 v25, 0xffff0000, v42
	v_lshlrev_b32_e32 v26, 16, v43
	v_and_b32_e32 v27, 0xffff0000, v43
	v_pk_fma_f32 v[104:105], v[52:53], v[20:21], v[104:105] op_sel_hi:[0,1,1]
	v_pk_fma_f32 v[106:107], v[52:53], v[22:23], v[106:107] op_sel_hi:[0,1,1]
	v_pk_fma_f32 v[108:109], v[52:53], v[24:25], v[108:109] op_sel_hi:[0,1,1]
	v_pk_fma_f32 v[110:111], v[52:53], v[26:27], v[110:111] op_sel_hi:[0,1,1]
	v_pk_mul_f32 v[132:133], v[96:97], v[96:97]
	v_pk_fma_f32 v[132:133], v[98:99], v[98:99], v[132:133]
	v_pk_fma_f32 v[132:133], v[100:101], v[100:101], v[132:133]
	v_pk_fma_f32 v[132:133], v[102:103], v[102:103], v[132:133]
	v_pk_fma_f32 v[132:133], v[104:105], v[104:105], v[132:133]
	v_pk_fma_f32 v[132:133], v[106:107], v[106:107], v[132:133]
	v_pk_fma_f32 v[132:133], v[108:109], v[108:109], v[132:133]
	v_pk_fma_f32 v[132:133], v[110:111], v[110:111], v[132:133]
	s_nop 0
	v_add_f32_e32 v132, v132, v133
	v_pk_mul_f32 v[112:113], v[130:131], v[112:113] op_sel_hi:[0,1]
	v_pk_mul_f32 v[114:115], v[130:131], v[114:115] op_sel_hi:[0,1]
	v_pk_mul_f32 v[116:117], v[130:131], v[116:117] op_sel_hi:[0,1]
	v_pk_mul_f32 v[118:119], v[130:131], v[118:119] op_sel_hi:[0,1]
	v_pk_mul_f32 v[120:121], v[130:131], v[120:121] op_sel_hi:[0,1]
	v_pk_mul_f32 v[122:123], v[130:131], v[122:123] op_sel_hi:[0,1]
	v_pk_mul_f32 v[124:125], v[130:131], v[124:125] op_sel_hi:[0,1]
	v_pk_mul_f32 v[126:127], v[130:131], v[126:127] op_sel_hi:[0,1]
	v_pk_mul_f32 v[112:113], v[112:113], v[192:193]
	v_pk_mul_f32 v[114:115], v[114:115], v[194:195]
	v_pk_mul_f32 v[116:117], v[116:117], v[196:197]
	v_pk_mul_f32 v[118:119], v[118:119], v[198:199]
	v_pk_mul_f32 v[120:121], v[120:121], v[200:201]
	v_pk_mul_f32 v[122:123], v[122:123], v[202:203]
	v_pk_mul_f32 v[124:125], v[124:125], v[204:205]
	v_pk_mul_f32 v[126:127], v[126:127], v[206:207]
	v_lshlrev_b32_e32 v28, 16, v44
	v_and_b32_e32 v29, 0xffff0000, v44
	v_lshlrev_b32_e32 v30, 16, v45
	v_and_b32_e32 v31, 0xffff0000, v45
	v_lshlrev_b32_e32 v32, 16, v46
	v_and_b32_e32 v33, 0xffff0000, v46
	v_lshlrev_b32_e32 v34, 16, v47
	v_and_b32_e32 v35, 0xffff0000, v47
	v_pk_fma_f32 v[112:113], v[54:55], v[28:29], v[112:113] op_sel_hi:[0,1,1]
	v_pk_fma_f32 v[114:115], v[54:55], v[30:31], v[114:115] op_sel_hi:[0,1,1]
	v_pk_fma_f32 v[116:117], v[54:55], v[32:33], v[116:117] op_sel_hi:[0,1,1]
	v_pk_fma_f32 v[118:119], v[54:55], v[34:35], v[118:119] op_sel_hi:[0,1,1]
	v_lshlrev_b32_e32 v28, 16, v48
	v_and_b32_e32 v29, 0xffff0000, v48
	v_lshlrev_b32_e32 v30, 16, v49
	v_and_b32_e32 v31, 0xffff0000, v49
	v_lshlrev_b32_e32 v32, 16, v50
	v_and_b32_e32 v33, 0xffff0000, v50
	v_lshlrev_b32_e32 v34, 16, v51
	v_and_b32_e32 v35, 0xffff0000, v51
	v_pk_fma_f32 v[120:121], v[54:55], v[28:29], v[120:121] op_sel_hi:[0,1,1]
	v_pk_fma_f32 v[122:123], v[54:55], v[30:31], v[122:123] op_sel_hi:[0,1,1]
	v_pk_fma_f32 v[124:125], v[54:55], v[32:33], v[124:125] op_sel_hi:[0,1,1]
	v_pk_fma_f32 v[126:127], v[54:55], v[34:35], v[126:127] op_sel_hi:[0,1,1]
	v_pk_mul_f32 v[134:135], v[112:113], v[112:113]
	v_pk_fma_f32 v[134:135], v[114:115], v[114:115], v[134:135]
	v_pk_fma_f32 v[134:135], v[116:117], v[116:117], v[134:135]
	v_pk_fma_f32 v[134:135], v[118:119], v[118:119], v[134:135]
	v_pk_fma_f32 v[134:135], v[120:121], v[120:121], v[134:135]
	v_pk_fma_f32 v[134:135], v[122:123], v[122:123], v[134:135]
	v_pk_fma_f32 v[134:135], v[124:125], v[124:125], v[134:135]
	v_pk_fma_f32 v[134:135], v[126:127], v[126:127], v[134:135]
	s_nop 0
	v_add_f32_e32 v134, v134, v135
	s_nop 1
	v_add_f32_dpp v132, v132, v132 quad_perm:[1,0,3,2] row_mask:0xf bank_mask:0xf
	v_add_f32_dpp v134, v134, v134 quad_perm:[1,0,3,2] row_mask:0xf bank_mask:0xf
	s_nop 0
	v_add_f32_dpp v132, v132, v132 quad_perm:[2,3,0,1] row_mask:0xf bank_mask:0xf
	v_add_f32_dpp v134, v134, v134 quad_perm:[2,3,0,1] row_mask:0xf bank_mask:0xf
	s_nop 0
	v_add_f32_dpp v132, v132, v132 row_half_mirror row_mask:0xf bank_mask:0xf
	v_add_f32_dpp v134, v134, v134 row_half_mirror row_mask:0xf bank_mask:0xf
	s_nop 0
	v_add_f32_dpp v132, v132, v132 row_mirror row_mask:0xf bank_mask:0xf
	v_add_f32_dpp v134, v134, v134 row_mirror row_mask:0xf bank_mask:0xf
	s_nop 0
	ds_bpermute_b32 v136, v187, v132
	ds_bpermute_b32 v137, v187, v134
	s_waitcnt lgkmcnt(0)
; __device__ __forceinline__ void st4_bf16(bf16* p, v4f o) { v2u w; w.x = cvt_pk_nv(o.x, o.y); w.y = cvt_pk_nv(o.z, o.w); *(v2u*)p = w; }
; __device__ __forceinline__ float ssq4(v4f v) { return (v.x * v.x + v.y * v.y) + (v.z * v.z + v.w * v.w); }
; template <int R, bool BASE_F32, bool OUT_F32>
; __device__ __forceinline__ void rows_res(const Ctx& C, int m0, int stride, int mx, const float* gpost, float scale, int lane) {
;     ...
;     for (int r = 0; r < R; ++r) { float s = 0.f;
; #pragma unroll
;         for (int j = 0; j < 4; ++j) s += ssq4(d[r][j]);
;         r1[r] = s; }
; #pragma unroll
;     for (int r = 0; r < R; ++r) r1[r] = rsqrtf(wave_sum(r1[r]) * (1.f / DM) + EPS) * scale;
;     ...
;         for (int r = 0; r < R; ++r) { float s = 0.f;
; #pragma unroll
;             for (int j = 0; j < 4; ++j) s += ssq4(d[r][j]);
;             t[r] = s; }
; #pragma unroll
;         for (int r = 0; r < R; ++r) t[r] = wave_sum(t[r]) * (1.f / DM) + EPS;
; #pragma unroll
;         for (int r = 0; r < R; ++r) { const float rstd = rsqrtf(t[r]);
; #pragma unroll
;             for (int j = 0; j < 4; ++j) if (ok[r]) st4_bf16(XN + (size_t)mr[r] * DM + 4 * lane + 256 * j, d[r][j] * rstd);
;             if (lane == 0 && ok[r]) rs[mr[r]] = sqrtf(t[r]); }
	v_add_f32_e32 v132, v132, v136
	v_add_f32_e32 v134, v134, v137
	ds_bpermute_b32 v136, v188, v132
	ds_bpermute_b32 v137, v188, v134
	s_waitcnt lgkmcnt(0)
	v_add_f32_e32 v132, v132, v136
	v_add_f32_e32 v134, v134, v137
	v_fmamk_f32 v164, v132, 0x3a800000, v138
	v_fmamk_f32 v167, v134, 0x3a800000, v138
	s_nop 0
	v_rsq_f32_e32 v132, v164
	v_rsq_f32_e32 v134, v167
	v_sqrt_f32_e32 v165, v164
	v_sqrt_f32_e32 v168, v167
	s_nop 1
	v_pk_mul_f32 v[140:141], v[96:97], v[132:133] op_sel_hi:[1,0]
	v_cvt_pk_bf16_f32 v148, v140, v141
	v_pk_mul_f32 v[142:143], v[98:99], v[132:133] op_sel_hi:[1,0]
	v_cvt_pk_bf16_f32 v149, v142, v143
	v_pk_mul_f32 v[144:145], v[100:101], v[132:133] op_sel_hi:[1,0]
	v_cvt_pk_bf16_f32 v150, v144, v145
	v_pk_mul_f32 v[146:147], v[102:103], v[132:133] op_sel_hi:[1,0]
	v_cvt_pk_bf16_f32 v151, v146, v147
	v_pk_mul_f32 v[140:141], v[104:105], v[132:133] op_sel_hi:[1,0]
	v_cvt_pk_bf16_f32 v152, v140, v141
	v_pk_mul_f32 v[142:143], v[106:107], v[132:133] op_sel_hi:[1,0]
	v_cvt_pk_bf16_f32 v153, v142, v143
	v_pk_mul_f32 v[144:145], v[108:109], v[132:133] op_sel_hi:[1,0]
	v_cvt_pk_bf16_f32 v154, v144, v145
	v_pk_mul_f32 v[146:147], v[110:111], v[132:133] op_sel_hi:[1,0]
	v_cvt_pk_bf16_f32 v155, v146, v147
	global_store_dwordx2 v173, v[148:149], s[98:99]
	global_store_dwordx2 v173, v[150:151], s[98:99] offset:512
	global_store_dwordx2 v173, v[152:153], s[98:99] offset:1024
	global_store_dwordx2 v173, v[154:155], s[98:99] offset:1536
	v_add_u32_e32 v173, 0x400000, v173
	v_pk_mul_f32 v[140:141], v[112:113], v[134:135] op_sel_hi:[1,0]
	v_cvt_pk_bf16_f32 v156, v140, v141
	v_pk_mul_f32 v[142:143], v[114:115], v[134:135] op_sel_hi:[1,0]
	v_cvt_pk_bf16_f32 v157, v142, v143
	v_pk_mul_f32 v[144:145], v[116:117], v[134:135] op_sel_hi:[1,0]
	v_cvt_pk_bf16_f32 v158, v144, v145
	v_pk_mul_f32 v[146:147], v[118:119], v[134:135] op_sel_hi:[1,0]
	v_cvt_pk_bf16_f32 v159, v146, v147
	v_pk_mul_f32 v[140:141], v[120:121], v[134:135] op_sel_hi:[1,0]
	v_cvt_pk_bf16_f32 v160, v140, v141
	v_pk_mul_f32 v[142:143], v[122:123], v[134:135] op_sel_hi:[1,0]
	v_cvt_pk_bf16_f32 v161, v142, v143
	v_pk_mul_f32 v[144:145], v[124:125], v[134:135] op_sel_hi:[1,0]
	v_cvt_pk_bf16_f32 v162, v144, v145
	v_pk_mul_f32 v[146:147], v[126:127], v[134:135] op_sel_hi:[1,0]
	v_cvt_pk_bf16_f32 v163, v146, v147
	global_store_dwordx2 v173, v[156:157], s[98:99]
	global_store_dwordx2 v173, v[158:159], s[98:99] offset:512
	global_store_dwordx2 v173, v[160:161], s[98:99] offset:1024
	global_store_dwordx2 v173, v[162:163], s[98:99] offset:1536
	v_add_u32_e32 v173, 0x400000, v173
	v_add_u32_e32 v166, -1, v165
	v_fma_f32 v140, -v166, v165, v164
	v_cmp_ge_f32_e32 vcc, 0, v140
	v_add_u32_e32 v141, 1, v165
	v_cndmask_b32_e32 v166, v165, v166, vcc
	v_fma_f32 v140, -v141, v165, v164
	v_cmp_lt_f32_e32 vcc, 0, v140
	s_nop 1
	v_cndmask_b32_e32 v165, v166, v141, vcc
	v_add_u32_e32 v169, -1, v168
	v_fma_f32 v142, -v169, v168, v167
	v_cmp_ge_f32_e32 vcc, 0, v142
	v_add_u32_e32 v143, 1, v168
	v_cndmask_b32_e32 v169, v168, v169, vcc
	v_fma_f32 v142, -v143, v168, v167
	v_cmp_lt_f32_e32 vcc, 0, v142
	s_nop 1
	v_cndmask_b32_e32 v168, v169, v143, vcc
	s_mov_b64 exec, 1
	global_store_dword v174, v165, s[98:99]
	v_add_u32_e32 v174, 0x2000, v174
	global_store_dword v174, v168, s[98:99]
	v_add_u32_e32 v174, 0x2000, v174
	s_mov_b64 exec, -1
	s_waitcnt vmcnt(33)
	v_lshlrev_b32_e32 v96, 16, v56
	v_and_b32_e32 v97, 0xffff0000, v56
	v_lshlrev_b32_e32 v98, 16, v57
	v_and_b32_e32 v99, 0xffff0000, v57
	v_lshlrev_b32_e32 v100, 16, v58
	v_and_b32_e32 v101, 0xffff0000, v58
	v_lshlrev_b32_e32 v102, 16, v59
	v_and_b32_e32 v103, 0xffff0000, v59
	v_lshlrev_b32_e32 v104, 16, v60
	v_and_b32_e32 v105, 0xffff0000, v60
	v_lshlrev_b32_e32 v106, 16, v61
	v_and_b32_e32 v107, 0xffff0000, v61
	v_lshlrev_b32_e32 v108, 16, v62
	v_and_b32_e32 v109, 0xffff0000, v62
	v_lshlrev_b32_e32 v110, 16, v63
	v_and_b32_e32 v111, 0xffff0000, v63
	v_pk_mul_f32 v[128:129], v[96:97], v[96:97]
	v_pk_fma_f32 v[128:129], v[98:99], v[98:99], v[128:129]
	v_pk_fma_f32 v[128:129], v[100:101], v[100:101], v[128:129]
	v_pk_fma_f32 v[128:129], v[102:103], v[102:103], v[128:129]
	v_pk_fma_f32 v[128:129], v[104:105], v[104:105], v[128:129]
	v_pk_fma_f32 v[128:129], v[106:107], v[106:107], v[128:129]
	v_pk_fma_f32 v[128:129], v[108:109], v[108:109], v[128:129]
	v_pk_fma_f32 v[128:129], v[110:111], v[110:111], v[128:129]
	s_nop 0
	v_add_f32_e32 v128, v128, v129
	s_waitcnt vmcnt(24)
	v_lshlrev_b32_e32 v112, 16, v64
	v_and_b32_e32 v113, 0xffff0000, v64
	v_lshlrev_b32_e32 v114, 16, v65
	v_and_b32_e32 v115, 0xffff0000, v65
	v_lshlrev_b32_e32 v116, 16, v66
	v_and_b32_e32 v117, 0xffff0000, v66
	v_lshlrev_b32_e32 v118, 16, v67
	v_and_b32_e32 v119, 0xffff0000, v67
	v_lshlrev_b32_e32 v120, 16, v68
	v_and_b32_e32 v121, 0xffff0000, v68
	v_lshlrev_b32_e32 v122, 16, v69
	v_and_b32_e32 v123, 0xffff0000, v69
	v_lshlrev_b32_e32 v124, 16, v70
	v_and_b32_e32 v125, 0xffff0000, v70
	v_lshlrev_b32_e32 v126, 16, v71
	v_and_b32_e32 v127, 0xffff0000, v71
	v_pk_mul_f32 v[130:131], v[112:113], v[112:113]
	v_pk_fma_f32 v[130:131], v[114:115], v[114:115], v[130:131]
	v_pk_fma_f32 v[130:131], v[116:117], v[116:117], v[130:131]
	v_pk_fma_f32 v[130:131], v[118:119], v[118:119], v[130:131]
	v_pk_fma_f32 v[130:131], v[120:121], v[120:121], v[130:131]
	v_pk_fma_f32 v[130:131], v[122:123], v[122:123], v[130:131]
	v_pk_fma_f32 v[130:131], v[124:125], v[124:125], v[130:131]
	v_pk_fma_f32 v[130:131], v[126:127], v[126:127], v[130:131]
	s_nop 0
	v_add_f32_e32 v130, v130, v131
	s_nop 1
	v_add_f32_dpp v128, v128, v128 quad_perm:[1,0,3,2] row_mask:0xf bank_mask:0xf
	v_add_f32_dpp v130, v130, v130 quad_perm:[1,0,3,2] row_mask:0xf bank_mask:0xf
	s_nop 0
	v_add_f32_dpp v128, v128, v128 quad_perm:[2,3,0,1] row_mask:0xf bank_mask:0xf
	v_add_f32_dpp v130, v130, v130 quad_perm:[2,3,0,1] row_mask:0xf bank_mask:0xf
	s_nop 0
	v_add_f32_dpp v128, v128, v128 row_half_mirror row_mask:0xf bank_mask:0xf
	v_add_f32_dpp v130, v130, v130 row_half_mirror row_mask:0xf bank_mask:0xf
	s_nop 0
	v_add_f32_dpp v128, v128, v128 row_mirror row_mask:0xf bank_mask:0xf
	v_add_f32_dpp v130, v130, v130 row_mirror row_mask:0xf bank_mask:0xf
	s_nop 0
	ds_bpermute_b32 v136, v187, v128
	ds_bpermute_b32 v137, v187, v130
	s_waitcnt lgkmcnt(0)
;     __device__ __forceinline__ float* out() const { return (float*)karg_in(33); }
; __device__ __forceinline__ float ssq4(v4f v) { return (v.x * v.x + v.y * v.y) + (v.z * v.z + v.w * v.w); }
; template <int R, bool BASE_F32, bool OUT_F32>
; __device__ __forceinline__ void rows_res(const Ctx& C, int m0, int stride, int mx, const float* gpost, float scale, int lane) {
;     ...
;     for (int r = 0; r < R; ++r) r1[r] = rsqrtf(wave_sum(r1[r]) * (1.f / DM) + EPS) * scale;
; #pragma unroll
;     for (int j = 0; j < 4; ++j) { const v4f gp = ld4_f32(gpost + 4 * lane + 256 * j);
; #pragma unroll
;         for (int r = 0; r < R; ++r) d[r][j] = b[r][j] + d[r][j] * r1[r] * gp; }
;     if (OUT_F32) { float* Y = C.out();
; #pragma unroll
;         for (int r = 0; r < R; ++r)
; #pragma unroll
;             for (int j = 0; j < 4; ++j) if (ok[r]) *(v4f*)(Y + (size_t)mr[r] * DM + 4 * lane + 256 * j) = d[r][j];
;     } else { float* rs = C.RS(); float t[R];
; #pragma unroll
;         for (int r = 0; r < R; ++r) { float s = 0.f;
; #pragma unroll
;             for (int j = 0; j < 4; ++j) s += ssq4(d[r][j]);
;             t[r] = s; }
; #pragma unroll
;         for (int r = 0; r < R; ++r) t[r] = wave_sum(t[r]) * (1.f / DM) + EPS;
	v_add_f32_e32 v128, v128, v136
	v_add_f32_e32 v130, v130, v137
	ds_bpermute_b32 v136, v188, v128
	ds_bpermute_b32 v137, v188, v130
	s_waitcnt lgkmcnt(0)
	v_add_f32_e32 v128, v128, v136
	v_add_f32_e32 v130, v130, v137
	v_fmamk_f32 v128, v128, 0x3a800000, v138
	v_fmamk_f32 v130, v130, 0x3a800000, v138
	s_nop 0
	v_rsq_f32_e32 v128, v128
	v_rsq_f32_e32 v130, v130
	s_nop 1
	s_waitcnt vmcnt(20)
	v_pk_mul_f32 v[96:97], v[128:129], v[96:97] op_sel_hi:[0,1]
	v_pk_mul_f32 v[98:99], v[128:129], v[98:99] op_sel_hi:[0,1]
	v_pk_mul_f32 v[100:101], v[128:129], v[100:101] op_sel_hi:[0,1]
	v_pk_mul_f32 v[102:103], v[128:129], v[102:103] op_sel_hi:[0,1]
	v_pk_mul_f32 v[104:105], v[128:129], v[104:105] op_sel_hi:[0,1]
	v_pk_mul_f32 v[106:107], v[128:129], v[106:107] op_sel_hi:[0,1]
	v_pk_mul_f32 v[108:109], v[128:129], v[108:109] op_sel_hi:[0,1]
	v_pk_mul_f32 v[110:111], v[128:129], v[110:111] op_sel_hi:[0,1]
	v_pk_mul_f32 v[96:97], v[96:97], v[192:193]
	v_pk_mul_f32 v[98:99], v[98:99], v[194:195]
	v_pk_mul_f32 v[100:101], v[100:101], v[196:197]
	v_pk_mul_f32 v[102:103], v[102:103], v[198:199]
	v_pk_mul_f32 v[104:105], v[104:105], v[200:201]
	v_pk_mul_f32 v[106:107], v[106:107], v[202:203]
	v_pk_mul_f32 v[108:109], v[108:109], v[204:205]
	v_pk_mul_f32 v[110:111], v[110:111], v[206:207]
	v_lshlrev_b32_e32 v56, 16, v72
	v_and_b32_e32 v57, 0xffff0000, v72
	v_lshlrev_b32_e32 v58, 16, v73
	v_and_b32_e32 v59, 0xffff0000, v73
	v_lshlrev_b32_e32 v60, 16, v74
	v_and_b32_e32 v61, 0xffff0000, v74
	v_lshlrev_b32_e32 v62, 16, v75
	v_and_b32_e32 v63, 0xffff0000, v75
	v_pk_fma_f32 v[96:97], v[88:89], v[56:57], v[96:97] op_sel_hi:[0,1,1]
	v_pk_fma_f32 v[98:99], v[88:89], v[58:59], v[98:99] op_sel_hi:[0,1,1]
	v_pk_fma_f32 v[100:101], v[88:89], v[60:61], v[100:101] op_sel_hi:[0,1,1]
	v_pk_fma_f32 v[102:103], v[88:89], v[62:63], v[102:103] op_sel_hi:[0,1,1]
	v_lshlrev_b32_e32 v56, 16, v76
	v_and_b32_e32 v57, 0xffff0000, v76
	v_lshlrev_b32_e32 v58, 16, v77
	v_and_b32_e32 v59, 0xffff0000, v77
	v_lshlrev_b32_e32 v60, 16, v78
	v_and_b32_e32 v61, 0xffff0000, v78
	v_lshlrev_b32_e32 v62, 16, v79
	v_and_b32_e32 v63, 0xffff0000, v79
	v_pk_fma_f32 v[104:105], v[88:89], v[56:57], v[104:105] op_sel_hi:[0,1,1]
	v_pk_fma_f32 v[106:107], v[88:89], v[58:59], v[106:107] op_sel_hi:[0,1,1]
	v_pk_fma_f32 v[108:109], v[88:89], v[60:61], v[108:109] op_sel_hi:[0,1,1]
	v_pk_fma_f32 v[110:111], v[88:89], v[62:63], v[110:111] op_sel_hi:[0,1,1]
	v_pk_mul_f32 v[132:133], v[96:97], v[96:97]
	v_pk_fma_f32 v[132:133], v[98:99], v[98:99], v[132:133]
	v_pk_fma_f32 v[132:133], v[100:101], v[100:101], v[132:133]
	v_pk_fma_f32 v[132:133], v[102:103], v[102:103], v[132:133]
	v_pk_fma_f32 v[132:133], v[104:105], v[104:105], v[132:133]
	v_pk_fma_f32 v[132:133], v[106:107], v[106:107], v[132:133]
	v_pk_fma_f32 v[132:133], v[108:109], v[108:109], v[132:133]
	v_pk_fma_f32 v[132:133], v[110:111], v[110:111], v[132:133]
	s_nop 0
	v_add_f32_e32 v132, v132, v133
	v_pk_mul_f32 v[112:113], v[130:131], v[112:113] op_sel_hi:[0,1]
	v_pk_mul_f32 v[114:115], v[130:131], v[114:115] op_sel_hi:[0,1]
	v_pk_mul_f32 v[116:117], v[130:131], v[116:117] op_sel_hi:[0,1]
	v_pk_mul_f32 v[118:119], v[130:131], v[118:119] op_sel_hi:[0,1]
	v_pk_mul_f32 v[120:121], v[130:131], v[120:121] op_sel_hi:[0,1]
	v_pk_mul_f32 v[122:123], v[130:131], v[122:123] op_sel_hi:[0,1]
	v_pk_mul_f32 v[124:125], v[130:131], v[124:125] op_sel_hi:[0,1]
	v_pk_mul_f32 v[126:127], v[130:131], v[126:127] op_sel_hi:[0,1]
	v_pk_mul_f32 v[112:113], v[112:113], v[192:193]
	v_pk_mul_f32 v[114:115], v[114:115], v[194:195]
	v_pk_mul_f32 v[116:117], v[116:117], v[196:197]
	v_pk_mul_f32 v[118:119], v[118:119], v[198:199]
	v_pk_mul_f32 v[120:121], v[120:121], v[200:201]
	v_pk_mul_f32 v[122:123], v[122:123], v[202:203]
	v_pk_mul_f32 v[124:125], v[124:125], v[204:205]
	v_pk_mul_f32 v[126:127], v[126:127], v[206:207]
	v_lshlrev_b32_e32 v64, 16, v80
	v_and_b32_e32 v65, 0xffff0000, v80
	v_lshlrev_b32_e32 v66, 16, v81
	v_and_b32_e32 v67, 0xffff0000, v81
	v_lshlrev_b32_e32 v68, 16, v82
	v_and_b32_e32 v69, 0xffff0000, v82
	v_lshlrev_b32_e32 v70, 16, v83
	v_and_b32_e32 v71, 0xffff0000, v83
	v_pk_fma_f32 v[112:113], v[90:91], v[64:65], v[112:113] op_sel_hi:[0,1,1]
	v_pk_fma_f32 v[114:115], v[90:91], v[66:67], v[114:115] op_sel_hi:[0,1,1]
	v_pk_fma_f32 v[116:117], v[90:91], v[68:69], v[116:117] op_sel_hi:[0,1,1]
	v_pk_fma_f32 v[118:119], v[90:91], v[70:71], v[118:119] op_sel_hi:[0,1,1]
	v_lshlrev_b32_e32 v64, 16, v84
	v_and_b32_e32 v65, 0xffff0000, v84
	v_lshlrev_b32_e32 v66, 16, v85
	v_and_b32_e32 v67, 0xffff0000, v85
	v_lshlrev_b32_e32 v68, 16, v86
	v_and_b32_e32 v69, 0xffff0000, v86
	v_lshlrev_b32_e32 v70, 16, v87
	v_and_b32_e32 v71, 0xffff0000, v87
	v_pk_fma_f32 v[120:121], v[90:91], v[64:65], v[120:121] op_sel_hi:[0,1,1]
	v_pk_fma_f32 v[122:123], v[90:91], v[66:67], v[122:123] op_sel_hi:[0,1,1]
	v_pk_fma_f32 v[124:125], v[90:91], v[68:69], v[124:125] op_sel_hi:[0,1,1]
	v_pk_fma_f32 v[126:127], v[90:91], v[70:71], v[126:127] op_sel_hi:[0,1,1]
	v_pk_mul_f32 v[134:135], v[112:113], v[112:113]
	v_pk_fma_f32 v[134:135], v[114:115], v[114:115], v[134:135]
	v_pk_fma_f32 v[134:135], v[116:117], v[116:117], v[134:135]
	v_pk_fma_f32 v[134:135], v[118:119], v[118:119], v[134:135]
	v_pk_fma_f32 v[134:135], v[120:121], v[120:121], v[134:135]
	v_pk_fma_f32 v[134:135], v[122:123], v[122:123], v[134:135]
	v_pk_fma_f32 v[134:135], v[124:125], v[124:125], v[134:135]
	v_pk_fma_f32 v[134:135], v[126:127], v[126:127], v[134:135]
	s_nop 0
	v_add_f32_e32 v134, v134, v135
	s_nop 1
	v_add_f32_dpp v132, v132, v132 quad_perm:[1,0,3,2] row_mask:0xf bank_mask:0xf
	v_add_f32_dpp v134, v134, v134 quad_perm:[1,0,3,2] row_mask:0xf bank_mask:0xf
	s_nop 0
	v_add_f32_dpp v132, v132, v132 quad_perm:[2,3,0,1] row_mask:0xf bank_mask:0xf
	v_add_f32_dpp v134, v134, v134 quad_perm:[2,3,0,1] row_mask:0xf bank_mask:0xf
	s_nop 0
	v_add_f32_dpp v132, v132, v132 row_half_mirror row_mask:0xf bank_mask:0xf
	v_add_f32_dpp v134, v134, v134 row_half_mirror row_mask:0xf bank_mask:0xf
	s_nop 0
	v_add_f32_dpp v132, v132, v132 row_mirror row_mask:0xf bank_mask:0xf
	v_add_f32_dpp v134, v134, v134 row_mirror row_mask:0xf bank_mask:0xf
	s_nop 0
	ds_bpermute_b32 v136, v187, v132
	ds_bpermute_b32 v137, v187, v134
	s_waitcnt lgkmcnt(0)
; __device__ __forceinline__ void st4_bf16(bf16* p, v4f o) { v2u w; w.x = cvt_pk_nv(o.x, o.y); w.y = cvt_pk_nv(o.z, o.w); *(v2u*)p = w; }
; template <int R, bool BASE_F32, bool OUT_F32>
; __device__ __forceinline__ void rows_res(const Ctx& C, int m0, int stride, int mx, const float* gpost, float scale, int lane) {
;     ...
;         for (int r = 0; r < R; ++r) t[r] = wave_sum(t[r]) * (1.f / DM) + EPS;
; #pragma unroll
;         for (int r = 0; r < R; ++r) { const float rstd = rsqrtf(t[r]);
; #pragma unroll
;             for (int j = 0; j < 4; ++j) if (ok[r]) st4_bf16(XN + (size_t)mr[r] * DM + 4 * lane + 256 * j, d[r][j] * rstd);
;             if (lane == 0 && ok[r]) rs[mr[r]] = sqrtf(t[r]); }
	v_add_f32_e32 v132, v132, v136
	v_add_f32_e32 v134, v134, v137
	ds_bpermute_b32 v136, v188, v132
	ds_bpermute_b32 v137, v188, v134
	s_waitcnt lgkmcnt(0)
	v_add_f32_e32 v132, v132, v136
	v_add_f32_e32 v134, v134, v137
	v_fmamk_f32 v164, v132, 0x3a800000, v138
	v_fmamk_f32 v167, v134, 0x3a800000, v138
	s_nop 0
	v_rsq_f32_e32 v132, v164
	v_rsq_f32_e32 v134, v167
	v_sqrt_f32_e32 v165, v164
	v_sqrt_f32_e32 v168, v167
	s_nop 1
	v_pk_mul_f32 v[140:141], v[96:97], v[132:133] op_sel_hi:[1,0]
	v_cvt_pk_bf16_f32 v148, v140, v141
	v_pk_mul_f32 v[142:143], v[98:99], v[132:133] op_sel_hi:[1,0]
	v_cvt_pk_bf16_f32 v149, v142, v143
	v_pk_mul_f32 v[144:145], v[100:101], v[132:133] op_sel_hi:[1,0]
	v_cvt_pk_bf16_f32 v150, v144, v145
	v_pk_mul_f32 v[146:147], v[102:103], v[132:133] op_sel_hi:[1,0]
	v_cvt_pk_bf16_f32 v151, v146, v147
	v_pk_mul_f32 v[140:141], v[104:105], v[132:133] op_sel_hi:[1,0]
	v_cvt_pk_bf16_f32 v152, v140, v141
	v_pk_mul_f32 v[142:143], v[106:107], v[132:133] op_sel_hi:[1,0]
	v_cvt_pk_bf16_f32 v153, v142, v143
	v_pk_mul_f32 v[144:145], v[108:109], v[132:133] op_sel_hi:[1,0]
	v_cvt_pk_bf16_f32 v154, v144, v145
	v_pk_mul_f32 v[146:147], v[110:111], v[132:133] op_sel_hi:[1,0]
	v_cvt_pk_bf16_f32 v155, v146, v147
	global_store_dwordx2 v173, v[148:149], s[98:99]
	global_store_dwordx2 v173, v[150:151], s[98:99] offset:512
	global_store_dwordx2 v173, v[152:153], s[98:99] offset:1024
	global_store_dwordx2 v173, v[154:155], s[98:99] offset:1536
	v_add_u32_e32 v173, 0x400000, v173
	v_pk_mul_f32 v[140:141], v[112:113], v[134:135] op_sel_hi:[1,0]
	v_cvt_pk_bf16_f32 v156, v140, v141
	v_pk_mul_f32 v[142:143], v[114:115], v[134:135] op_sel_hi:[1,0]
	v_cvt_pk_bf16_f32 v157, v142, v143
	v_pk_mul_f32 v[144:145], v[116:117], v[134:135] op_sel_hi:[1,0]
	v_cvt_pk_bf16_f32 v158, v144, v145
	v_pk_mul_f32 v[146:147], v[118:119], v[134:135] op_sel_hi:[1,0]
	v_cvt_pk_bf16_f32 v159, v146, v147
	v_pk_mul_f32 v[140:141], v[120:121], v[134:135] op_sel_hi:[1,0]
	v_cvt_pk_bf16_f32 v160, v140, v141
	v_pk_mul_f32 v[142:143], v[122:123], v[134:135] op_sel_hi:[1,0]
	v_cvt_pk_bf16_f32 v161, v142, v143
	v_pk_mul_f32 v[144:145], v[124:125], v[134:135] op_sel_hi:[1,0]
	v_cvt_pk_bf16_f32 v162, v144, v145
	v_pk_mul_f32 v[146:147], v[126:127], v[134:135] op_sel_hi:[1,0]
	v_cvt_pk_bf16_f32 v163, v146, v147
	global_store_dwordx2 v173, v[156:157], s[98:99]
	global_store_dwordx2 v173, v[158:159], s[98:99] offset:512
	global_store_dwordx2 v173, v[160:161], s[98:99] offset:1024
	global_store_dwordx2 v173, v[162:163], s[98:99] offset:1536
	v_add_u32_e32 v173, 0x400000, v173
	v_add_u32_e32 v166, -1, v165
	v_fma_f32 v140, -v166, v165, v164
	v_cmp_ge_f32_e32 vcc, 0, v140
	v_add_u32_e32 v141, 1, v165
	v_cndmask_b32_e32 v166, v165, v166, vcc
	v_fma_f32 v140, -v141, v165, v164
	v_cmp_lt_f32_e32 vcc, 0, v140
	s_nop 1
	v_cndmask_b32_e32 v165, v166, v141, vcc
	v_add_u32_e32 v169, -1, v168
	v_fma_f32 v142, -v169, v168, v167
	v_cmp_ge_f32_e32 vcc, 0, v142
	v_add_u32_e32 v143, 1, v168
	v_cndmask_b32_e32 v169, v168, v169, vcc
	v_fma_f32 v142, -v143, v168, v167
	v_cmp_lt_f32_e32 vcc, 0, v142
	s_nop 1
	v_cndmask_b32_e32 v168, v169, v143, vcc
	s_mov_b64 exec, 1
	global_store_dword v174, v165, s[98:99]
	v_add_u32_e32 v174, 0x2000, v174
	global_store_dword v174, v168, s[98:99]
	v_add_u32_e32 v174, 0x2000, v174
	s_mov_b64 exec, -1
	s_branch .LBB0_1013
	v_mov_b32_e32 v3, v1
	s_mov_b32 s0, 0x358637bd
	s_waitcnt lgkmcnt(0)
	v_lshl_add_u64 v[4:5], s[16:17], 0, v[2:3]
	s_mov_b64 s[18:19], 0x7100000
	s_mov_b64 s[20:21], 0x3000000
	v_mov_b32_e32 v3, 0x2a80000
	s_mov_b32 s22, 0x3a800000
	v_mov_b64_e32 v[6:7], s[0:1]
	s_mov_b32 s42, 0x800000
	v_mov_b32_e32 v41, 0x358637bd
	s_mov_b32 s43, 0xf800000
	v_mov_b32_e32 v148, 0x260
	s_mov_b32 s24, s23
	v_readlane_b32 s56, v232, 5
	s_branch .LBB0_997
